# back-edge rotation (7.11) on the 9 GEMM K-loops: loop-back barrier becomes the loop head, counter/exit test/back edge run before it, exit path gets its own barrier
# baseline (speedup 1.0000x reference)
.LBB0_181:
	s_ashr_i32 s13, s12, 31
	s_lshl_b64 s[14:15], s[12:13], 21
	v_readlane_b32 s30, v253, 6
	v_readlane_b32 s31, v253, 7
	s_add_u32 s14, s30, s14
	s_addc_u32 s15, s31, s15
	s_and_b64 s[30:31], s[0:1], exec
	s_cselect_b32 s13, s15, s73
	s_cselect_b32 s37, s14, s72
	s_ashr_i32 s11, s10, 31
	s_lshl_b64 s[30:31], s[10:11], 21
	s_add_u32 s34, s16, s30
	s_addc_u32 s35, s17, s31
	s_and_b64 s[30:31], s[0:1], exec
	s_cselect_b32 s11, s35, s75
	s_cselect_b32 s38, s34, s74
	s_add_u32 s72, s72, 0x100080
	s_addc_u32 s73, s73, 0
	s_add_u32 s39, s74, 0x100
	v_mov_b32_e32 v0, 0
	s_addc_u32 s40, s75, 0
	s_mov_b32 s41, -2
	v_mov_b32_e32 v1, v0
	v_mov_b32_e32 v2, v0
	v_mov_b32_e32 v3, v0
	v_mov_b32_e32 v4, v0
	v_mov_b32_e32 v5, v0
	v_mov_b32_e32 v6, v0
	v_mov_b32_e32 v7, v0
	v_mov_b32_e32 v16, v0
	v_mov_b32_e32 v17, v0
	v_mov_b32_e32 v18, v0
	v_mov_b32_e32 v19, v0
	v_mov_b32_e32 v20, v0
	v_mov_b32_e32 v21, v0
	v_mov_b32_e32 v22, v0
	v_mov_b32_e32 v23, v0
	v_mov_b32_e32 v32, v0
	v_mov_b32_e32 v33, v0
	v_mov_b32_e32 v34, v0
	v_mov_b32_e32 v35, v0
	v_mov_b32_e32 v36, v0
	v_mov_b32_e32 v37, v0
	v_mov_b32_e32 v38, v0
	v_mov_b32_e32 v39, v0
	v_mov_b32_e32 v48, v0
	v_mov_b32_e32 v49, v0
	v_mov_b32_e32 v50, v0
	v_mov_b32_e32 v51, v0
	v_mov_b32_e32 v52, v0
	v_mov_b32_e32 v53, v0
	v_mov_b32_e32 v54, v0
	v_mov_b32_e32 v55, v0
	v_mov_b32_e32 v8, v0
	v_mov_b32_e32 v9, v0
	v_mov_b32_e32 v10, v0
	v_mov_b32_e32 v11, v0
	v_mov_b32_e32 v12, v0
	v_mov_b32_e32 v13, v0
	v_mov_b32_e32 v14, v0
	v_mov_b32_e32 v15, v0
	v_mov_b32_e32 v24, v0
	v_mov_b32_e32 v25, v0
	v_mov_b32_e32 v26, v0
	v_mov_b32_e32 v27, v0
	v_mov_b32_e32 v28, v0
	v_mov_b32_e32 v29, v0
	v_mov_b32_e32 v30, v0
	v_mov_b32_e32 v31, v0
	v_mov_b32_e32 v40, v0
	v_mov_b32_e32 v41, v0
	v_mov_b32_e32 v42, v0
	v_mov_b32_e32 v43, v0
	v_mov_b32_e32 v44, v0
	v_mov_b32_e32 v45, v0
	v_mov_b32_e32 v46, v0
	v_mov_b32_e32 v47, v0
	v_mov_b32_e32 v56, v0
	v_mov_b32_e32 v57, v0
	v_mov_b32_e32 v58, v0
	v_mov_b32_e32 v59, v0
	v_mov_b32_e32 v60, v0
	v_mov_b32_e32 v61, v0
	v_mov_b32_e32 v62, v0
	v_mov_b32_e32 v63, v0
	v_mov_b32_e32 v64, v0
	v_mov_b32_e32 v65, v0
	v_mov_b32_e32 v66, v0
	v_mov_b32_e32 v67, v0
	v_mov_b32_e32 v68, v0
	v_mov_b32_e32 v69, v0
	v_mov_b32_e32 v70, v0
	v_mov_b32_e32 v71, v0
	v_mov_b32_e32 v80, v0
	v_mov_b32_e32 v81, v0
	v_mov_b32_e32 v82, v0
	v_mov_b32_e32 v83, v0
	v_mov_b32_e32 v84, v0
	v_mov_b32_e32 v85, v0
	v_mov_b32_e32 v86, v0
	v_mov_b32_e32 v87, v0
	v_mov_b32_e32 v96, v0
	v_mov_b32_e32 v97, v0
	v_mov_b32_e32 v98, v0
	v_mov_b32_e32 v99, v0
	v_mov_b32_e32 v100, v0
	v_mov_b32_e32 v101, v0
	v_mov_b32_e32 v102, v0
	v_mov_b32_e32 v103, v0
	v_mov_b32_e32 v112, v0
	v_mov_b32_e32 v113, v0
	v_mov_b32_e32 v114, v0
	v_mov_b32_e32 v115, v0
	v_mov_b32_e32 v116, v0
	v_mov_b32_e32 v117, v0
	v_mov_b32_e32 v118, v0
	v_mov_b32_e32 v119, v0
	v_mov_b32_e32 v72, v0
	v_mov_b32_e32 v73, v0
	v_mov_b32_e32 v74, v0
	v_mov_b32_e32 v75, v0
	v_mov_b32_e32 v76, v0
	v_mov_b32_e32 v77, v0
	v_mov_b32_e32 v78, v0
	v_mov_b32_e32 v79, v0
	v_mov_b32_e32 v88, v0
	v_mov_b32_e32 v89, v0
	v_mov_b32_e32 v90, v0
	v_mov_b32_e32 v91, v0
	v_mov_b32_e32 v92, v0
	v_mov_b32_e32 v93, v0
	v_mov_b32_e32 v94, v0
	v_mov_b32_e32 v95, v0
	v_mov_b32_e32 v104, v0
	v_mov_b32_e32 v105, v0
	v_mov_b32_e32 v106, v0
	v_mov_b32_e32 v107, v0
	v_mov_b32_e32 v108, v0
	v_mov_b32_e32 v109, v0
	v_mov_b32_e32 v110, v0
	v_mov_b32_e32 v111, v0
	v_mov_b32_e32 v120, v0
	v_mov_b32_e32 v121, v0
	v_mov_b32_e32 v122, v0
	v_mov_b32_e32 v123, v0
	v_mov_b32_e32 v124, v0
	v_mov_b32_e32 v125, v0
	v_mov_b32_e32 v126, v0
	v_mov_b32_e32 v127, v0
	s_branch .LBB0_182

.LBB0_182:
	ds_read_b128 v[144:147], v153 offset:0
	ds_read_b128 v[156:159], v153 offset:1024
	ds_read_b128 v[160:163], v153 offset:2048
	ds_read_b128 v[164:167], v153 offset:3072
	ds_read_b128 v[168:171], v154 offset:0
	ds_read_b128 v[172:175], v154 offset:1024
	ds_read_b128 v[176:179], v154 offset:2048
	ds_read_b128 v[180:183], v154 offset:3072
	s_add_u32 s30, s72, 0xfff00080
	s_addc_u32 s31, s73, -1
	s_cmp_eq_u32 s41, 60
	s_cselect_b32 s31, s13, s31
	s_cselect_b32 s30, s37, s30
	s_cselect_b32 s75, s11, s40
	s_cselect_b32 s74, s38, s39
	ds_read_b128 v[184:187], v155 offset:0
	ds_read_b128 v[188:191], v155 offset:1024
	ds_read_b128 v[192:195], v155 offset:2048
	ds_read_b128 v[196:199], v155 offset:3072
	ds_read_b128 v[200:203], v155 offset:4096
	ds_read_b128 v[204:207], v155 offset:5120
	ds_read_b128 v[208:211], v155 offset:6144
	ds_read_b128 v[212:215], v155 offset:7168
	s_add_i32 m0, s29, 0xc000
	s_nop 0
	global_load_lds_dwordx4 v136, s[72:73]
	s_add_i32 m0, s29, 0xe000
	s_nop 0
	global_load_lds_dwordx4 v138, s[72:73]
	s_waitcnt vmcnt(8)
	s_waitcnt lgkmcnt(0)
	s_barrier
	v_mfma_f32_16x16x32_bf16 v[124:127], v[144:147], v[184:187], v[124:127]
	v_mfma_f32_16x16x32_bf16 v[120:123], v[160:163], v[184:187], v[120:123]
	v_mfma_f32_16x16x32_bf16 v[108:111], v[144:147], v[192:195], v[108:111]
	v_mfma_f32_16x16x32_bf16 v[104:107], v[160:163], v[192:195], v[104:107]
	v_mfma_f32_16x16x32_bf16 v[92:95], v[144:147], v[200:203], v[92:95]
	v_mfma_f32_16x16x32_bf16 v[88:91], v[160:163], v[200:203], v[88:91]
	v_mfma_f32_16x16x32_bf16 v[76:79], v[144:147], v[208:211], v[76:79]
	v_mfma_f32_16x16x32_bf16 v[72:75], v[160:163], v[208:211], v[72:75]
	v_mfma_f32_16x16x32_bf16 v[124:127], v[156:159], v[188:191], v[124:127]
	v_mfma_f32_16x16x32_bf16 v[120:123], v[164:167], v[188:191], v[120:123]
	v_mfma_f32_16x16x32_bf16 v[108:111], v[156:159], v[196:199], v[108:111]
	v_mfma_f32_16x16x32_bf16 v[104:107], v[164:167], v[196:199], v[104:107]
	v_mfma_f32_16x16x32_bf16 v[92:95], v[156:159], v[204:207], v[92:95]
	v_mfma_f32_16x16x32_bf16 v[88:91], v[164:167], v[204:207], v[88:91]
	v_mfma_f32_16x16x32_bf16 v[76:79], v[156:159], v[212:215], v[76:79]
	v_mfma_f32_16x16x32_bf16 v[72:75], v[164:167], v[212:215], v[72:75]
	v_mfma_f32_16x16x32_bf16 v[116:119], v[168:171], v[184:187], v[116:119]
	v_mfma_f32_16x16x32_bf16 v[112:115], v[176:179], v[184:187], v[112:115]
	v_mfma_f32_16x16x32_bf16 v[100:103], v[168:171], v[192:195], v[100:103]
	v_mfma_f32_16x16x32_bf16 v[96:99], v[176:179], v[192:195], v[96:99]
	v_mfma_f32_16x16x32_bf16 v[84:87], v[168:171], v[200:203], v[84:87]
	v_mfma_f32_16x16x32_bf16 v[80:83], v[176:179], v[200:203], v[80:83]
	v_mfma_f32_16x16x32_bf16 v[68:71], v[168:171], v[208:211], v[68:71]
	v_mfma_f32_16x16x32_bf16 v[64:67], v[176:179], v[208:211], v[64:67]
	v_mfma_f32_16x16x32_bf16 v[116:119], v[172:175], v[188:191], v[116:119]
	v_mfma_f32_16x16x32_bf16 v[112:115], v[180:183], v[188:191], v[112:115]
	v_mfma_f32_16x16x32_bf16 v[100:103], v[172:175], v[196:199], v[100:103]
	v_mfma_f32_16x16x32_bf16 v[96:99], v[180:183], v[196:199], v[96:99]
	v_mfma_f32_16x16x32_bf16 v[84:87], v[172:175], v[204:207], v[84:87]
	v_mfma_f32_16x16x32_bf16 v[80:83], v[180:183], v[204:207], v[80:83]
	v_mfma_f32_16x16x32_bf16 v[68:71], v[172:175], v[212:215], v[68:71]
	v_mfma_f32_16x16x32_bf16 v[64:67], v[180:183], v[212:215], v[64:67]
	s_barrier
	s_add_u32 s42, s74, 0x100000
	s_addc_u32 s43, s75, 0
	ds_read_b128 v[184:187], v155 offset:16384
	ds_read_b128 v[188:191], v155 offset:17408
	ds_read_b128 v[192:195], v155 offset:18432
	ds_read_b128 v[196:199], v155 offset:19456
	ds_read_b128 v[200:203], v155 offset:20480
	ds_read_b128 v[204:207], v155 offset:21504
	ds_read_b128 v[208:211], v155 offset:22528
	ds_read_b128 v[212:215], v155 offset:23552
	s_add_i32 m0, s29, 0x10000
	s_nop 0
	global_load_lds_dwordx4 v130, s[74:75]
	s_add_i32 m0, s29, 0x12000
	s_nop 0
	global_load_lds_dwordx4 v134, s[74:75]
	s_add_i32 m0, s29, 0x14000
	s_nop 0
	global_load_lds_dwordx4 v130, s[42:43]
	s_add_i32 m0, s29, 0x16000
	s_nop 0
	global_load_lds_dwordx4 v134, s[42:43]
	s_add_i32 m0, s29, 0x0
	s_nop 0
	global_load_lds_dwordx4 v128, s[30:31]
	s_add_i32 m0, s29, 0x2000
	s_nop 0
	global_load_lds_dwordx4 v132, s[30:31]
	s_waitcnt vmcnt(8)
	s_waitcnt lgkmcnt(0)
	s_barrier
	v_mfma_f32_16x16x32_bf16 v[60:63], v[144:147], v[184:187], v[60:63]
	v_mfma_f32_16x16x32_bf16 v[56:59], v[160:163], v[184:187], v[56:59]
	v_mfma_f32_16x16x32_bf16 v[44:47], v[144:147], v[192:195], v[44:47]
	v_mfma_f32_16x16x32_bf16 v[40:43], v[160:163], v[192:195], v[40:43]
	v_mfma_f32_16x16x32_bf16 v[28:31], v[144:147], v[200:203], v[28:31]
	v_mfma_f32_16x16x32_bf16 v[24:27], v[160:163], v[200:203], v[24:27]
	v_mfma_f32_16x16x32_bf16 v[12:15], v[144:147], v[208:211], v[12:15]
	v_mfma_f32_16x16x32_bf16 v[8:11], v[160:163], v[208:211], v[8:11]
	v_mfma_f32_16x16x32_bf16 v[60:63], v[156:159], v[188:191], v[60:63]
	v_mfma_f32_16x16x32_bf16 v[56:59], v[164:167], v[188:191], v[56:59]
	v_mfma_f32_16x16x32_bf16 v[44:47], v[156:159], v[196:199], v[44:47]
	v_mfma_f32_16x16x32_bf16 v[40:43], v[164:167], v[196:199], v[40:43]
	v_mfma_f32_16x16x32_bf16 v[28:31], v[156:159], v[204:207], v[28:31]
	v_mfma_f32_16x16x32_bf16 v[24:27], v[164:167], v[204:207], v[24:27]
	v_mfma_f32_16x16x32_bf16 v[12:15], v[156:159], v[212:215], v[12:15]
	v_mfma_f32_16x16x32_bf16 v[8:11], v[164:167], v[212:215], v[8:11]
	v_mfma_f32_16x16x32_bf16 v[52:55], v[168:171], v[184:187], v[52:55]
	v_mfma_f32_16x16x32_bf16 v[48:51], v[176:179], v[184:187], v[48:51]
	v_mfma_f32_16x16x32_bf16 v[36:39], v[168:171], v[192:195], v[36:39]
	v_mfma_f32_16x16x32_bf16 v[32:35], v[176:179], v[192:195], v[32:35]
	v_mfma_f32_16x16x32_bf16 v[20:23], v[168:171], v[200:203], v[20:23]
	v_mfma_f32_16x16x32_bf16 v[16:19], v[176:179], v[200:203], v[16:19]
	v_mfma_f32_16x16x32_bf16 v[4:7], v[168:171], v[208:211], v[4:7]
	v_mfma_f32_16x16x32_bf16 v[0:3], v[176:179], v[208:211], v[0:3]
	v_mfma_f32_16x16x32_bf16 v[52:55], v[172:175], v[188:191], v[52:55]
	v_mfma_f32_16x16x32_bf16 v[48:51], v[180:183], v[188:191], v[48:51]
	v_mfma_f32_16x16x32_bf16 v[36:39], v[172:175], v[196:199], v[36:39]
	v_mfma_f32_16x16x32_bf16 v[32:35], v[180:183], v[196:199], v[32:35]
	v_mfma_f32_16x16x32_bf16 v[20:23], v[172:175], v[204:207], v[20:23]
	v_mfma_f32_16x16x32_bf16 v[16:19], v[180:183], v[204:207], v[16:19]
	v_mfma_f32_16x16x32_bf16 v[4:7], v[172:175], v[212:215], v[4:7]
	v_mfma_f32_16x16x32_bf16 v[0:3], v[180:183], v[212:215], v[0:3]
	s_barrier
	s_add_u32 s98, s30, 0x100000
	s_addc_u32 s99, s31, 0
	ds_read_b128 v[144:147], v153 offset:32768
	ds_read_b128 v[156:159], v153 offset:33792
	ds_read_b128 v[160:163], v153 offset:34816
	ds_read_b128 v[164:167], v153 offset:35840
	ds_read_b128 v[168:171], v154 offset:32768
	ds_read_b128 v[172:175], v154 offset:33792
	ds_read_b128 v[176:179], v154 offset:34816
	ds_read_b128 v[180:183], v154 offset:35840
	ds_read_b128 v[184:187], v155 offset:32768
	ds_read_b128 v[188:191], v155 offset:33792
	ds_read_b128 v[192:195], v155 offset:34816
	ds_read_b128 v[196:199], v155 offset:35840
	ds_read_b128 v[200:203], v155 offset:36864
	ds_read_b128 v[204:207], v155 offset:37888
	ds_read_b128 v[208:211], v155 offset:38912
	ds_read_b128 v[212:215], v155 offset:39936
	s_add_i32 m0, s29, 0x4000
	s_nop 0
	global_load_lds_dwordx4 v128, s[98:99]
	s_add_i32 m0, s29, 0x6000
	s_nop 0
	global_load_lds_dwordx4 v132, s[98:99]
	s_waitcnt vmcnt(8)
	s_waitcnt lgkmcnt(0)
	s_barrier
	v_mfma_f32_16x16x32_bf16 v[124:127], v[144:147], v[184:187], v[124:127]
	v_mfma_f32_16x16x32_bf16 v[120:123], v[160:163], v[184:187], v[120:123]
	v_mfma_f32_16x16x32_bf16 v[108:111], v[144:147], v[192:195], v[108:111]
	v_mfma_f32_16x16x32_bf16 v[104:107], v[160:163], v[192:195], v[104:107]
	v_mfma_f32_16x16x32_bf16 v[92:95], v[144:147], v[200:203], v[92:95]
	v_mfma_f32_16x16x32_bf16 v[88:91], v[160:163], v[200:203], v[88:91]
	v_mfma_f32_16x16x32_bf16 v[76:79], v[144:147], v[208:211], v[76:79]
	v_mfma_f32_16x16x32_bf16 v[72:75], v[160:163], v[208:211], v[72:75]
	v_mfma_f32_16x16x32_bf16 v[124:127], v[156:159], v[188:191], v[124:127]
	v_mfma_f32_16x16x32_bf16 v[120:123], v[164:167], v[188:191], v[120:123]
	v_mfma_f32_16x16x32_bf16 v[108:111], v[156:159], v[196:199], v[108:111]
	v_mfma_f32_16x16x32_bf16 v[104:107], v[164:167], v[196:199], v[104:107]
	v_mfma_f32_16x16x32_bf16 v[92:95], v[156:159], v[204:207], v[92:95]
	v_mfma_f32_16x16x32_bf16 v[88:91], v[164:167], v[204:207], v[88:91]
	v_mfma_f32_16x16x32_bf16 v[76:79], v[156:159], v[212:215], v[76:79]
	v_mfma_f32_16x16x32_bf16 v[72:75], v[164:167], v[212:215], v[72:75]
	v_mfma_f32_16x16x32_bf16 v[116:119], v[168:171], v[184:187], v[116:119]
	v_mfma_f32_16x16x32_bf16 v[112:115], v[176:179], v[184:187], v[112:115]
	v_mfma_f32_16x16x32_bf16 v[100:103], v[168:171], v[192:195], v[100:103]
	v_mfma_f32_16x16x32_bf16 v[96:99], v[176:179], v[192:195], v[96:99]
	v_mfma_f32_16x16x32_bf16 v[84:87], v[168:171], v[200:203], v[84:87]
	v_mfma_f32_16x16x32_bf16 v[80:83], v[176:179], v[200:203], v[80:83]
	v_mfma_f32_16x16x32_bf16 v[68:71], v[168:171], v[208:211], v[68:71]
	v_mfma_f32_16x16x32_bf16 v[64:67], v[176:179], v[208:211], v[64:67]
	v_mfma_f32_16x16x32_bf16 v[116:119], v[172:175], v[188:191], v[116:119]
	v_mfma_f32_16x16x32_bf16 v[112:115], v[180:183], v[188:191], v[112:115]
	v_mfma_f32_16x16x32_bf16 v[100:103], v[172:175], v[196:199], v[100:103]
	v_mfma_f32_16x16x32_bf16 v[96:99], v[180:183], v[196:199], v[96:99]
	v_mfma_f32_16x16x32_bf16 v[84:87], v[172:175], v[204:207], v[84:87]
	v_mfma_f32_16x16x32_bf16 v[80:83], v[180:183], v[204:207], v[80:83]
	v_mfma_f32_16x16x32_bf16 v[68:71], v[172:175], v[212:215], v[68:71]
	v_mfma_f32_16x16x32_bf16 v[64:67], v[180:183], v[212:215], v[64:67]
	s_barrier
	s_add_u32 s100, s74, 0x80
	s_addc_u32 s101, s75, 0
	s_add_u32 s42, s74, 0x100080
	s_addc_u32 s43, s75, 0
	s_add_u32 s98, s30, 0x80
	s_addc_u32 s99, s31, 0
	ds_read_b128 v[184:187], v155 offset:49152
	ds_read_b128 v[188:191], v155 offset:50176
	ds_read_b128 v[192:195], v155 offset:51200
	ds_read_b128 v[196:199], v155 offset:52224
	ds_read_b128 v[200:203], v155 offset:53248
	ds_read_b128 v[204:207], v155 offset:54272
	ds_read_b128 v[208:211], v155 offset:55296
	ds_read_b128 v[212:215], v155 offset:56320
	s_add_i32 m0, s29, 0x18000
	s_nop 0
	global_load_lds_dwordx4 v130, s[100:101]
	s_add_i32 m0, s29, 0x1a000
	s_nop 0
	global_load_lds_dwordx4 v134, s[100:101]
	s_add_i32 m0, s29, 0x1c000
	s_nop 0
	global_load_lds_dwordx4 v130, s[42:43]
	s_add_i32 m0, s29, 0x1e000
	s_nop 0
	global_load_lds_dwordx4 v134, s[42:43]
	s_add_i32 m0, s29, 0x8000
	s_nop 0
	global_load_lds_dwordx4 v128, s[98:99]
	s_add_i32 m0, s29, 0xa000
	s_nop 0
	global_load_lds_dwordx4 v132, s[98:99]
	s_waitcnt vmcnt(8)
	s_waitcnt lgkmcnt(0)
	s_barrier
	v_mfma_f32_16x16x32_bf16 v[60:63], v[144:147], v[184:187], v[60:63]
	v_mfma_f32_16x16x32_bf16 v[56:59], v[160:163], v[184:187], v[56:59]
	v_mfma_f32_16x16x32_bf16 v[44:47], v[144:147], v[192:195], v[44:47]
	v_mfma_f32_16x16x32_bf16 v[40:43], v[160:163], v[192:195], v[40:43]
	v_mfma_f32_16x16x32_bf16 v[28:31], v[144:147], v[200:203], v[28:31]
	v_mfma_f32_16x16x32_bf16 v[24:27], v[160:163], v[200:203], v[24:27]
	v_mfma_f32_16x16x32_bf16 v[12:15], v[144:147], v[208:211], v[12:15]
	v_mfma_f32_16x16x32_bf16 v[8:11], v[160:163], v[208:211], v[8:11]
	v_mfma_f32_16x16x32_bf16 v[60:63], v[156:159], v[188:191], v[60:63]
	v_mfma_f32_16x16x32_bf16 v[56:59], v[164:167], v[188:191], v[56:59]
	v_mfma_f32_16x16x32_bf16 v[44:47], v[156:159], v[196:199], v[44:47]
	v_mfma_f32_16x16x32_bf16 v[40:43], v[164:167], v[196:199], v[40:43]
	v_mfma_f32_16x16x32_bf16 v[28:31], v[156:159], v[204:207], v[28:31]
	v_mfma_f32_16x16x32_bf16 v[24:27], v[164:167], v[204:207], v[24:27]
	v_mfma_f32_16x16x32_bf16 v[12:15], v[156:159], v[212:215], v[12:15]
	v_mfma_f32_16x16x32_bf16 v[8:11], v[164:167], v[212:215], v[8:11]
	v_mfma_f32_16x16x32_bf16 v[52:55], v[168:171], v[184:187], v[52:55]
	v_mfma_f32_16x16x32_bf16 v[48:51], v[176:179], v[184:187], v[48:51]
	v_mfma_f32_16x16x32_bf16 v[36:39], v[168:171], v[192:195], v[36:39]
	v_mfma_f32_16x16x32_bf16 v[32:35], v[176:179], v[192:195], v[32:35]
	v_mfma_f32_16x16x32_bf16 v[20:23], v[168:171], v[200:203], v[20:23]
	v_mfma_f32_16x16x32_bf16 v[16:19], v[176:179], v[200:203], v[16:19]
	v_mfma_f32_16x16x32_bf16 v[4:7], v[168:171], v[208:211], v[4:7]
	v_mfma_f32_16x16x32_bf16 v[0:3], v[176:179], v[208:211], v[0:3]
	v_mfma_f32_16x16x32_bf16 v[52:55], v[172:175], v[188:191], v[52:55]
	v_mfma_f32_16x16x32_bf16 v[48:51], v[180:183], v[188:191], v[48:51]
	v_mfma_f32_16x16x32_bf16 v[36:39], v[172:175], v[196:199], v[36:39]
	v_mfma_f32_16x16x32_bf16 v[32:35], v[180:183], v[196:199], v[32:35]
	v_mfma_f32_16x16x32_bf16 v[20:23], v[172:175], v[204:207], v[20:23]
	v_mfma_f32_16x16x32_bf16 v[16:19], v[180:183], v[204:207], v[16:19]
	v_mfma_f32_16x16x32_bf16 v[4:7], v[172:175], v[212:215], v[4:7]
	v_mfma_f32_16x16x32_bf16 v[0:3], v[180:183], v[212:215], v[0:3]
	s_add_i32 s41, s41, 2
	s_add_u32 s72, s72, 0x100
	s_addc_u32 s73, s73, 0
	s_add_u32 s39, s39, 0x100
	s_addc_u32 s40, s40, 0
	s_cmp_gt_u32 s41, 61
	s_cbranch_scc0 .Lrot_182
	s_barrier
	s_and_b64 vcc, exec, s[6:7]
	s_cbranch_vccz .LBB0_185
	s_barrier

.LBB0_400:
	s_add_i32 s17, s87, -2
	s_add_u32 s36, s46, 0x100
	v_mov_b32_e32 v0, 0
	s_addc_u32 s37, s47, 0
	s_mov_b32 s30, 0
	v_mov_b32_e32 v1, v0
	v_mov_b32_e32 v2, v0
	v_mov_b32_e32 v3, v0
	v_mov_b32_e32 v4, v0
	v_mov_b32_e32 v5, v0
	v_mov_b32_e32 v6, v0
	v_mov_b32_e32 v7, v0
	v_mov_b32_e32 v16, v0
	v_mov_b32_e32 v17, v0
	v_mov_b32_e32 v18, v0
	v_mov_b32_e32 v19, v0
	v_mov_b32_e32 v20, v0
	v_mov_b32_e32 v21, v0
	v_mov_b32_e32 v22, v0
	v_mov_b32_e32 v23, v0
	v_mov_b32_e32 v32, v0
	v_mov_b32_e32 v33, v0
	v_mov_b32_e32 v34, v0
	v_mov_b32_e32 v35, v0
	v_mov_b32_e32 v36, v0
	v_mov_b32_e32 v37, v0
	v_mov_b32_e32 v38, v0
	v_mov_b32_e32 v39, v0
	v_mov_b32_e32 v48, v0
	v_mov_b32_e32 v49, v0
	v_mov_b32_e32 v50, v0
	v_mov_b32_e32 v51, v0
	v_mov_b32_e32 v52, v0
	v_mov_b32_e32 v53, v0
	v_mov_b32_e32 v54, v0
	v_mov_b32_e32 v55, v0
	v_mov_b32_e32 v8, v0
	v_mov_b32_e32 v9, v0
	v_mov_b32_e32 v10, v0
	v_mov_b32_e32 v11, v0
	v_mov_b32_e32 v12, v0
	v_mov_b32_e32 v13, v0
	v_mov_b32_e32 v14, v0
	v_mov_b32_e32 v15, v0
	v_mov_b32_e32 v24, v0
	v_mov_b32_e32 v25, v0
	v_mov_b32_e32 v26, v0
	v_mov_b32_e32 v27, v0
	v_mov_b32_e32 v28, v0
	v_mov_b32_e32 v29, v0
	v_mov_b32_e32 v30, v0
	v_mov_b32_e32 v31, v0
	v_mov_b32_e32 v40, v0
	v_mov_b32_e32 v41, v0
	v_mov_b32_e32 v42, v0
	v_mov_b32_e32 v43, v0
	v_mov_b32_e32 v44, v0
	v_mov_b32_e32 v45, v0
	v_mov_b32_e32 v46, v0
	v_mov_b32_e32 v47, v0
	v_mov_b32_e32 v56, v0
	v_mov_b32_e32 v57, v0
	v_mov_b32_e32 v58, v0
	v_mov_b32_e32 v59, v0
	v_mov_b32_e32 v60, v0
	v_mov_b32_e32 v61, v0
	v_mov_b32_e32 v62, v0
	v_mov_b32_e32 v63, v0
	v_mov_b32_e32 v64, v0
	v_mov_b32_e32 v65, v0
	v_mov_b32_e32 v66, v0
	v_mov_b32_e32 v67, v0
	v_mov_b32_e32 v68, v0
	v_mov_b32_e32 v69, v0
	v_mov_b32_e32 v70, v0
	v_mov_b32_e32 v71, v0
	v_mov_b32_e32 v80, v0
	v_mov_b32_e32 v81, v0
	v_mov_b32_e32 v82, v0
	v_mov_b32_e32 v83, v0
	v_mov_b32_e32 v84, v0
	v_mov_b32_e32 v85, v0
	v_mov_b32_e32 v86, v0
	v_mov_b32_e32 v87, v0
	v_mov_b32_e32 v96, v0
	v_mov_b32_e32 v97, v0
	v_mov_b32_e32 v98, v0
	v_mov_b32_e32 v99, v0
	v_mov_b32_e32 v100, v0
	v_mov_b32_e32 v101, v0
	v_mov_b32_e32 v102, v0
	v_mov_b32_e32 v103, v0
	v_mov_b32_e32 v112, v0
	v_mov_b32_e32 v113, v0
	v_mov_b32_e32 v114, v0
	v_mov_b32_e32 v115, v0
	v_mov_b32_e32 v116, v0
	v_mov_b32_e32 v117, v0
	v_mov_b32_e32 v118, v0
	v_mov_b32_e32 v119, v0
	v_mov_b32_e32 v72, v0
	v_mov_b32_e32 v73, v0
	v_mov_b32_e32 v74, v0
	v_mov_b32_e32 v75, v0
	v_mov_b32_e32 v76, v0
	v_mov_b32_e32 v77, v0
	v_mov_b32_e32 v78, v0
	v_mov_b32_e32 v79, v0
	v_mov_b32_e32 v88, v0
	v_mov_b32_e32 v89, v0
	v_mov_b32_e32 v90, v0
	v_mov_b32_e32 v91, v0
	v_mov_b32_e32 v92, v0
	v_mov_b32_e32 v93, v0
	v_mov_b32_e32 v94, v0
	v_mov_b32_e32 v95, v0
	v_mov_b32_e32 v104, v0
	v_mov_b32_e32 v105, v0
	v_mov_b32_e32 v106, v0
	v_mov_b32_e32 v107, v0
	v_mov_b32_e32 v108, v0
	v_mov_b32_e32 v109, v0
	v_mov_b32_e32 v110, v0
	v_mov_b32_e32 v111, v0
	v_mov_b32_e32 v120, v0
	v_mov_b32_e32 v121, v0
	v_mov_b32_e32 v122, v0
	v_mov_b32_e32 v123, v0
	v_mov_b32_e32 v124, v0
	v_mov_b32_e32 v125, v0
	v_mov_b32_e32 v126, v0
	v_mov_b32_e32 v127, v0
	s_branch .LBB0_401

.LBB0_401:
	ds_read_b128 v[142:145], v169 offset:0
	ds_read_b128 v[146:149], v169 offset:1024
	ds_read_b128 v[150:153], v169 offset:2048
	ds_read_b128 v[154:157], v169 offset:3072
	ds_read_b128 v[158:161], v170 offset:0
	ds_read_b128 v[162:165], v170 offset:1024
	ds_read_b128 v[172:175], v170 offset:2048
	ds_read_b128 v[176:179], v170 offset:3072
	s_add_i32 s38, s30, 2
	s_add_u32 s46, s44, 0x100
	s_addc_u32 s47, s45, 0
	s_cmp_eq_u32 s17, s30
	s_cselect_b32 s30, s34, s46
	s_cselect_b32 s31, s35, s47
	s_cselect_b32 s53, s41, s37
	s_cselect_b32 s52, s40, s36
	ds_read_b128 v[180:183], v171 offset:0
	ds_read_b128 v[184:187], v171 offset:1024
	ds_read_b128 v[188:191], v171 offset:2048
	ds_read_b128 v[192:195], v171 offset:3072
	ds_read_b128 v[196:199], v171 offset:4096
	ds_read_b128 v[200:203], v171 offset:5120
	ds_read_b128 v[204:207], v171 offset:6144
	ds_read_b128 v[208:211], v171 offset:7168
	s_add_i32 m0, s60, 0xc000
	s_nop 0
	global_load_lds_dwordx4 v136, s[44:45]
	s_add_i32 m0, s60, 0xe000
	s_nop 0
	global_load_lds_dwordx4 v138, s[44:45]
	s_waitcnt vmcnt(8)
	s_waitcnt lgkmcnt(0)
	s_barrier
	v_mfma_f32_16x16x32_bf16 v[124:127], v[142:145], v[180:183], v[124:127]
	v_mfma_f32_16x16x32_bf16 v[120:123], v[150:153], v[180:183], v[120:123]
	v_mfma_f32_16x16x32_bf16 v[108:111], v[142:145], v[188:191], v[108:111]
	v_mfma_f32_16x16x32_bf16 v[104:107], v[150:153], v[188:191], v[104:107]
	v_mfma_f32_16x16x32_bf16 v[92:95], v[142:145], v[196:199], v[92:95]
	v_mfma_f32_16x16x32_bf16 v[88:91], v[150:153], v[196:199], v[88:91]
	v_mfma_f32_16x16x32_bf16 v[76:79], v[142:145], v[204:207], v[76:79]
	v_mfma_f32_16x16x32_bf16 v[72:75], v[150:153], v[204:207], v[72:75]
	v_mfma_f32_16x16x32_bf16 v[124:127], v[146:149], v[184:187], v[124:127]
	v_mfma_f32_16x16x32_bf16 v[120:123], v[154:157], v[184:187], v[120:123]
	v_mfma_f32_16x16x32_bf16 v[108:111], v[146:149], v[192:195], v[108:111]
	v_mfma_f32_16x16x32_bf16 v[104:107], v[154:157], v[192:195], v[104:107]
	v_mfma_f32_16x16x32_bf16 v[92:95], v[146:149], v[200:203], v[92:95]
	v_mfma_f32_16x16x32_bf16 v[88:91], v[154:157], v[200:203], v[88:91]
	v_mfma_f32_16x16x32_bf16 v[76:79], v[146:149], v[208:211], v[76:79]
	v_mfma_f32_16x16x32_bf16 v[72:75], v[154:157], v[208:211], v[72:75]
	v_mfma_f32_16x16x32_bf16 v[116:119], v[158:161], v[180:183], v[116:119]
	v_mfma_f32_16x16x32_bf16 v[112:115], v[172:175], v[180:183], v[112:115]
	v_mfma_f32_16x16x32_bf16 v[100:103], v[158:161], v[188:191], v[100:103]
	v_mfma_f32_16x16x32_bf16 v[96:99], v[172:175], v[188:191], v[96:99]
	v_mfma_f32_16x16x32_bf16 v[84:87], v[158:161], v[196:199], v[84:87]
	v_mfma_f32_16x16x32_bf16 v[80:83], v[172:175], v[196:199], v[80:83]
	v_mfma_f32_16x16x32_bf16 v[68:71], v[158:161], v[204:207], v[68:71]
	v_mfma_f32_16x16x32_bf16 v[64:67], v[172:175], v[204:207], v[64:67]
	v_mfma_f32_16x16x32_bf16 v[116:119], v[162:165], v[184:187], v[116:119]
	v_mfma_f32_16x16x32_bf16 v[112:115], v[176:179], v[184:187], v[112:115]
	v_mfma_f32_16x16x32_bf16 v[100:103], v[162:165], v[192:195], v[100:103]
	v_mfma_f32_16x16x32_bf16 v[96:99], v[176:179], v[192:195], v[96:99]
	v_mfma_f32_16x16x32_bf16 v[84:87], v[162:165], v[200:203], v[84:87]
	v_mfma_f32_16x16x32_bf16 v[80:83], v[176:179], v[200:203], v[80:83]
	v_mfma_f32_16x16x32_bf16 v[68:71], v[162:165], v[208:211], v[68:71]
	v_mfma_f32_16x16x32_bf16 v[64:67], v[176:179], v[208:211], v[64:67]
	s_barrier
	s_add_u32 s42, s52, 0x2b0000
	s_addc_u32 s43, s53, 0
	ds_read_b128 v[180:183], v171 offset:16384
	ds_read_b128 v[184:187], v171 offset:17408
	ds_read_b128 v[188:191], v171 offset:18432
	ds_read_b128 v[192:195], v171 offset:19456
	ds_read_b128 v[196:199], v171 offset:20480
	ds_read_b128 v[200:203], v171 offset:21504
	ds_read_b128 v[204:207], v171 offset:22528
	ds_read_b128 v[208:211], v171 offset:23552
	s_add_i32 m0, s60, 0x10000
	s_nop 0
	global_load_lds_dwordx4 v130, s[52:53]
	s_add_i32 m0, s60, 0x12000
	s_nop 0
	global_load_lds_dwordx4 v134, s[52:53]
	s_add_i32 m0, s60, 0x14000
	s_nop 0
	global_load_lds_dwordx4 v130, s[42:43]
	s_add_i32 m0, s60, 0x16000
	s_nop 0
	global_load_lds_dwordx4 v134, s[42:43]
	s_add_i32 m0, s60, 0x0
	s_nop 0
	global_load_lds_dwordx4 v128, s[30:31]
	s_add_i32 m0, s60, 0x2000
	s_nop 0
	global_load_lds_dwordx4 v132, s[30:31]
	s_waitcnt vmcnt(8)
	s_waitcnt lgkmcnt(0)
	s_barrier
	v_mfma_f32_16x16x32_bf16 v[60:63], v[142:145], v[180:183], v[60:63]
	v_mfma_f32_16x16x32_bf16 v[56:59], v[150:153], v[180:183], v[56:59]
	v_mfma_f32_16x16x32_bf16 v[44:47], v[142:145], v[188:191], v[44:47]
	v_mfma_f32_16x16x32_bf16 v[40:43], v[150:153], v[188:191], v[40:43]
	v_mfma_f32_16x16x32_bf16 v[28:31], v[142:145], v[196:199], v[28:31]
	v_mfma_f32_16x16x32_bf16 v[24:27], v[150:153], v[196:199], v[24:27]
	v_mfma_f32_16x16x32_bf16 v[12:15], v[142:145], v[204:207], v[12:15]
	v_mfma_f32_16x16x32_bf16 v[8:11], v[150:153], v[204:207], v[8:11]
	v_mfma_f32_16x16x32_bf16 v[60:63], v[146:149], v[184:187], v[60:63]
	v_mfma_f32_16x16x32_bf16 v[56:59], v[154:157], v[184:187], v[56:59]
	v_mfma_f32_16x16x32_bf16 v[44:47], v[146:149], v[192:195], v[44:47]
	v_mfma_f32_16x16x32_bf16 v[40:43], v[154:157], v[192:195], v[40:43]
	v_mfma_f32_16x16x32_bf16 v[28:31], v[146:149], v[200:203], v[28:31]
	v_mfma_f32_16x16x32_bf16 v[24:27], v[154:157], v[200:203], v[24:27]
	v_mfma_f32_16x16x32_bf16 v[12:15], v[146:149], v[208:211], v[12:15]
	v_mfma_f32_16x16x32_bf16 v[8:11], v[154:157], v[208:211], v[8:11]
	v_mfma_f32_16x16x32_bf16 v[52:55], v[158:161], v[180:183], v[52:55]
	v_mfma_f32_16x16x32_bf16 v[48:51], v[172:175], v[180:183], v[48:51]
	v_mfma_f32_16x16x32_bf16 v[36:39], v[158:161], v[188:191], v[36:39]
	v_mfma_f32_16x16x32_bf16 v[32:35], v[172:175], v[188:191], v[32:35]
	v_mfma_f32_16x16x32_bf16 v[20:23], v[158:161], v[196:199], v[20:23]
	v_mfma_f32_16x16x32_bf16 v[16:19], v[172:175], v[196:199], v[16:19]
	v_mfma_f32_16x16x32_bf16 v[4:7], v[158:161], v[204:207], v[4:7]
	v_mfma_f32_16x16x32_bf16 v[0:3], v[172:175], v[204:207], v[0:3]
	v_mfma_f32_16x16x32_bf16 v[52:55], v[162:165], v[184:187], v[52:55]
	v_mfma_f32_16x16x32_bf16 v[48:51], v[176:179], v[184:187], v[48:51]
	v_mfma_f32_16x16x32_bf16 v[36:39], v[162:165], v[192:195], v[36:39]
	v_mfma_f32_16x16x32_bf16 v[32:35], v[176:179], v[192:195], v[32:35]
	v_mfma_f32_16x16x32_bf16 v[20:23], v[162:165], v[200:203], v[20:23]
	v_mfma_f32_16x16x32_bf16 v[16:19], v[176:179], v[200:203], v[16:19]
	v_mfma_f32_16x16x32_bf16 v[4:7], v[162:165], v[208:211], v[4:7]
	v_mfma_f32_16x16x32_bf16 v[0:3], v[176:179], v[208:211], v[0:3]
	s_barrier
	s_add_u32 s98, s30, 0x2b0000
	s_addc_u32 s99, s31, 0
	ds_read_b128 v[142:145], v169 offset:32768
	ds_read_b128 v[146:149], v169 offset:33792
	ds_read_b128 v[150:153], v169 offset:34816
	ds_read_b128 v[154:157], v169 offset:35840
	ds_read_b128 v[158:161], v170 offset:32768
	ds_read_b128 v[162:165], v170 offset:33792
	ds_read_b128 v[172:175], v170 offset:34816
	ds_read_b128 v[176:179], v170 offset:35840
	ds_read_b128 v[180:183], v171 offset:32768
	ds_read_b128 v[184:187], v171 offset:33792
	ds_read_b128 v[188:191], v171 offset:34816
	ds_read_b128 v[192:195], v171 offset:35840
	ds_read_b128 v[196:199], v171 offset:36864
	ds_read_b128 v[200:203], v171 offset:37888
	ds_read_b128 v[204:207], v171 offset:38912
	ds_read_b128 v[208:211], v171 offset:39936
	s_add_i32 m0, s60, 0x4000
	s_nop 0
	global_load_lds_dwordx4 v128, s[98:99]
	s_add_i32 m0, s60, 0x6000
	s_nop 0
	global_load_lds_dwordx4 v132, s[98:99]
	s_waitcnt vmcnt(8)
	s_waitcnt lgkmcnt(0)
	s_barrier
	v_mfma_f32_16x16x32_bf16 v[124:127], v[142:145], v[180:183], v[124:127]
	v_mfma_f32_16x16x32_bf16 v[120:123], v[150:153], v[180:183], v[120:123]
	v_mfma_f32_16x16x32_bf16 v[108:111], v[142:145], v[188:191], v[108:111]
	v_mfma_f32_16x16x32_bf16 v[104:107], v[150:153], v[188:191], v[104:107]
	v_mfma_f32_16x16x32_bf16 v[92:95], v[142:145], v[196:199], v[92:95]
	v_mfma_f32_16x16x32_bf16 v[88:91], v[150:153], v[196:199], v[88:91]
	v_mfma_f32_16x16x32_bf16 v[76:79], v[142:145], v[204:207], v[76:79]
	v_mfma_f32_16x16x32_bf16 v[72:75], v[150:153], v[204:207], v[72:75]
	v_mfma_f32_16x16x32_bf16 v[124:127], v[146:149], v[184:187], v[124:127]
	v_mfma_f32_16x16x32_bf16 v[120:123], v[154:157], v[184:187], v[120:123]
	v_mfma_f32_16x16x32_bf16 v[108:111], v[146:149], v[192:195], v[108:111]
	v_mfma_f32_16x16x32_bf16 v[104:107], v[154:157], v[192:195], v[104:107]
	v_mfma_f32_16x16x32_bf16 v[92:95], v[146:149], v[200:203], v[92:95]
	v_mfma_f32_16x16x32_bf16 v[88:91], v[154:157], v[200:203], v[88:91]
	v_mfma_f32_16x16x32_bf16 v[76:79], v[146:149], v[208:211], v[76:79]
	v_mfma_f32_16x16x32_bf16 v[72:75], v[154:157], v[208:211], v[72:75]
	v_mfma_f32_16x16x32_bf16 v[116:119], v[158:161], v[180:183], v[116:119]
	v_mfma_f32_16x16x32_bf16 v[112:115], v[172:175], v[180:183], v[112:115]
	v_mfma_f32_16x16x32_bf16 v[100:103], v[158:161], v[188:191], v[100:103]
	v_mfma_f32_16x16x32_bf16 v[96:99], v[172:175], v[188:191], v[96:99]
	v_mfma_f32_16x16x32_bf16 v[84:87], v[158:161], v[196:199], v[84:87]
	v_mfma_f32_16x16x32_bf16 v[80:83], v[172:175], v[196:199], v[80:83]
	v_mfma_f32_16x16x32_bf16 v[68:71], v[158:161], v[204:207], v[68:71]
	v_mfma_f32_16x16x32_bf16 v[64:67], v[172:175], v[204:207], v[64:67]
	v_mfma_f32_16x16x32_bf16 v[116:119], v[162:165], v[184:187], v[116:119]
	v_mfma_f32_16x16x32_bf16 v[112:115], v[176:179], v[184:187], v[112:115]
	v_mfma_f32_16x16x32_bf16 v[100:103], v[162:165], v[192:195], v[100:103]
	v_mfma_f32_16x16x32_bf16 v[96:99], v[176:179], v[192:195], v[96:99]
	v_mfma_f32_16x16x32_bf16 v[84:87], v[162:165], v[200:203], v[84:87]
	v_mfma_f32_16x16x32_bf16 v[80:83], v[176:179], v[200:203], v[80:83]
	v_mfma_f32_16x16x32_bf16 v[68:71], v[162:165], v[208:211], v[68:71]
	v_mfma_f32_16x16x32_bf16 v[64:67], v[176:179], v[208:211], v[64:67]
	s_barrier
	s_add_u32 s100, s52, 0x80
	s_addc_u32 s101, s53, 0
	s_add_u32 s42, s52, 0x2b0080
	s_addc_u32 s43, s53, 0
	s_add_u32 s98, s30, 0x80
	s_addc_u32 s99, s31, 0
	ds_read_b128 v[180:183], v171 offset:49152
	ds_read_b128 v[184:187], v171 offset:50176
	ds_read_b128 v[188:191], v171 offset:51200
	ds_read_b128 v[192:195], v171 offset:52224
	ds_read_b128 v[196:199], v171 offset:53248
	ds_read_b128 v[200:203], v171 offset:54272
	ds_read_b128 v[204:207], v171 offset:55296
	ds_read_b128 v[208:211], v171 offset:56320
	s_add_i32 m0, s60, 0x18000
	s_nop 0
	global_load_lds_dwordx4 v130, s[100:101]
	s_add_i32 m0, s60, 0x1a000
	s_nop 0
	global_load_lds_dwordx4 v134, s[100:101]
	s_add_i32 m0, s60, 0x1c000
	s_nop 0
	global_load_lds_dwordx4 v130, s[42:43]
	s_add_i32 m0, s60, 0x1e000
	s_nop 0
	global_load_lds_dwordx4 v134, s[42:43]
	s_add_i32 m0, s60, 0x8000
	s_nop 0
	global_load_lds_dwordx4 v128, s[98:99]
	s_add_i32 m0, s60, 0xa000
	s_nop 0
	global_load_lds_dwordx4 v132, s[98:99]
	s_waitcnt vmcnt(8)
	s_waitcnt lgkmcnt(0)
	s_barrier
	v_mfma_f32_16x16x32_bf16 v[60:63], v[142:145], v[180:183], v[60:63]
	v_mfma_f32_16x16x32_bf16 v[56:59], v[150:153], v[180:183], v[56:59]
	v_mfma_f32_16x16x32_bf16 v[44:47], v[142:145], v[188:191], v[44:47]
	v_mfma_f32_16x16x32_bf16 v[40:43], v[150:153], v[188:191], v[40:43]
	v_mfma_f32_16x16x32_bf16 v[28:31], v[142:145], v[196:199], v[28:31]
	v_mfma_f32_16x16x32_bf16 v[24:27], v[150:153], v[196:199], v[24:27]
	v_mfma_f32_16x16x32_bf16 v[12:15], v[142:145], v[204:207], v[12:15]
	v_mfma_f32_16x16x32_bf16 v[8:11], v[150:153], v[204:207], v[8:11]
	v_mfma_f32_16x16x32_bf16 v[60:63], v[146:149], v[184:187], v[60:63]
	v_mfma_f32_16x16x32_bf16 v[56:59], v[154:157], v[184:187], v[56:59]
	v_mfma_f32_16x16x32_bf16 v[44:47], v[146:149], v[192:195], v[44:47]
	v_mfma_f32_16x16x32_bf16 v[40:43], v[154:157], v[192:195], v[40:43]
	v_mfma_f32_16x16x32_bf16 v[28:31], v[146:149], v[200:203], v[28:31]
	v_mfma_f32_16x16x32_bf16 v[24:27], v[154:157], v[200:203], v[24:27]
	v_mfma_f32_16x16x32_bf16 v[12:15], v[146:149], v[208:211], v[12:15]
	v_mfma_f32_16x16x32_bf16 v[8:11], v[154:157], v[208:211], v[8:11]
	v_mfma_f32_16x16x32_bf16 v[52:55], v[158:161], v[180:183], v[52:55]
	v_mfma_f32_16x16x32_bf16 v[48:51], v[172:175], v[180:183], v[48:51]
	v_mfma_f32_16x16x32_bf16 v[36:39], v[158:161], v[188:191], v[36:39]
	v_mfma_f32_16x16x32_bf16 v[32:35], v[172:175], v[188:191], v[32:35]
	v_mfma_f32_16x16x32_bf16 v[20:23], v[158:161], v[196:199], v[20:23]
	v_mfma_f32_16x16x32_bf16 v[16:19], v[172:175], v[196:199], v[16:19]
	v_mfma_f32_16x16x32_bf16 v[4:7], v[158:161], v[204:207], v[4:7]
	v_mfma_f32_16x16x32_bf16 v[0:3], v[172:175], v[204:207], v[0:3]
	v_mfma_f32_16x16x32_bf16 v[52:55], v[162:165], v[184:187], v[52:55]
	v_mfma_f32_16x16x32_bf16 v[48:51], v[176:179], v[184:187], v[48:51]
	v_mfma_f32_16x16x32_bf16 v[36:39], v[162:165], v[192:195], v[36:39]
	v_mfma_f32_16x16x32_bf16 v[32:35], v[176:179], v[192:195], v[32:35]
	v_mfma_f32_16x16x32_bf16 v[20:23], v[162:165], v[200:203], v[20:23]
	v_mfma_f32_16x16x32_bf16 v[16:19], v[176:179], v[200:203], v[16:19]
	v_mfma_f32_16x16x32_bf16 v[4:7], v[162:165], v[208:211], v[4:7]
	v_mfma_f32_16x16x32_bf16 v[0:3], v[176:179], v[208:211], v[0:3]
	s_add_u32 s36, s36, 0x100
	s_addc_u32 s37, s37, 0
	s_cmp_ge_i32 s38, s87
	s_mov_b64 s[44:45], s[46:47]
	s_mov_b32 s30, s38
	s_cbranch_scc0 .Lrot_401
	s_barrier
	s_and_b64 vcc, exec, s[12:13]
	s_cbranch_vccz .LBB0_404

.LBB0_574:
	s_ashr_i32 s17, s16, 31
	s_lshl_b64 s[30:31], s[16:17], 21
	v_readlane_b32 s38, v253, 6
	v_readlane_b32 s39, v253, 7
	s_add_u32 s7, s38, s30
	s_addc_u32 s17, s39, s31
	s_ashr_i32 s15, s14, 31
	s_lshl_b64 s[30:31], s[14:15], 7
	s_add_u32 s44, s7, s30
	s_addc_u32 s45, s17, s31
	s_ashr_i32 s35, s34, 31
	s_lshl_b64 s[38:39], s[34:35], 21
	s_add_u32 s7, s56, s38
	s_addc_u32 s15, s57, s39
	s_add_u32 s46, s7, s30
	s_addc_u32 s47, s15, s31
	s_cmp_lt_i32 s36, 1
	s_cbranch_scc1 .LBB0_580
	s_and_b64 s[30:31], s[40:41], exec
	s_cselect_b32 s7, s45, s53
	s_cselect_b32 s15, s44, s52
	s_cselect_b32 s17, s47, s55
	s_cselect_b32 s35, s46, s54
	s_add_i32 s37, s36, -2
	s_add_u32 s52, s52, 0x100080
	s_addc_u32 s53, s53, 0
	s_add_u32 s38, s54, 0x100
	v_mov_b32_e32 v64, 0
	s_addc_u32 s39, s55, 0
	s_mov_b32 s30, 0
	v_mov_b32_e32 v65, v64
	v_mov_b32_e32 v66, v64
	v_mov_b32_e32 v67, v64
	v_mov_b32_e32 v68, v64
	v_mov_b32_e32 v69, v64
	v_mov_b32_e32 v70, v64
	v_mov_b32_e32 v71, v64
	v_mov_b32_e32 v72, v64
	v_mov_b32_e32 v73, v64
	v_mov_b32_e32 v74, v64
	v_mov_b32_e32 v75, v64
	v_mov_b32_e32 v76, v64
	v_mov_b32_e32 v77, v64
	v_mov_b32_e32 v78, v64
	v_mov_b32_e32 v79, v64
	v_mov_b32_e32 v80, v64
	v_mov_b32_e32 v81, v64
	v_mov_b32_e32 v82, v64
	v_mov_b32_e32 v83, v64
	v_mov_b32_e32 v84, v64
	v_mov_b32_e32 v85, v64
	v_mov_b32_e32 v86, v64
	v_mov_b32_e32 v87, v64
	v_mov_b32_e32 v88, v64
	v_mov_b32_e32 v89, v64
	v_mov_b32_e32 v90, v64
	v_mov_b32_e32 v91, v64
	v_mov_b32_e32 v92, v64
	v_mov_b32_e32 v93, v64
	v_mov_b32_e32 v94, v64
	v_mov_b32_e32 v95, v64
	v_mov_b32_e32 v0, v64
	v_mov_b32_e32 v1, v64
	v_mov_b32_e32 v2, v64
	v_mov_b32_e32 v3, v64
	v_mov_b32_e32 v4, v64
	v_mov_b32_e32 v5, v64
	v_mov_b32_e32 v6, v64
	v_mov_b32_e32 v7, v64
	v_mov_b32_e32 v8, v64
	v_mov_b32_e32 v9, v64
	v_mov_b32_e32 v10, v64
	v_mov_b32_e32 v11, v64
	v_mov_b32_e32 v12, v64
	v_mov_b32_e32 v13, v64
	v_mov_b32_e32 v14, v64
	v_mov_b32_e32 v15, v64
	v_mov_b32_e32 v16, v64
	v_mov_b32_e32 v17, v64
	v_mov_b32_e32 v18, v64
	v_mov_b32_e32 v19, v64
	v_mov_b32_e32 v20, v64
	v_mov_b32_e32 v21, v64
	v_mov_b32_e32 v22, v64
	v_mov_b32_e32 v23, v64
	v_mov_b32_e32 v24, v64
	v_mov_b32_e32 v25, v64
	v_mov_b32_e32 v26, v64
	v_mov_b32_e32 v27, v64
	v_mov_b32_e32 v28, v64
	v_mov_b32_e32 v29, v64
	v_mov_b32_e32 v30, v64
	v_mov_b32_e32 v31, v64
	v_mov_b32_e32 v96, v64
	v_mov_b32_e32 v97, v64
	v_mov_b32_e32 v98, v64
	v_mov_b32_e32 v99, v64
	v_mov_b32_e32 v100, v64
	v_mov_b32_e32 v101, v64
	v_mov_b32_e32 v102, v64
	v_mov_b32_e32 v103, v64
	v_mov_b32_e32 v104, v64
	v_mov_b32_e32 v105, v64
	v_mov_b32_e32 v106, v64
	v_mov_b32_e32 v107, v64
	v_mov_b32_e32 v108, v64
	v_mov_b32_e32 v109, v64
	v_mov_b32_e32 v110, v64
	v_mov_b32_e32 v111, v64
	v_mov_b32_e32 v112, v64
	v_mov_b32_e32 v113, v64
	v_mov_b32_e32 v114, v64
	v_mov_b32_e32 v115, v64
	v_mov_b32_e32 v116, v64
	v_mov_b32_e32 v117, v64
	v_mov_b32_e32 v118, v64
	v_mov_b32_e32 v119, v64
	v_mov_b32_e32 v120, v64
	v_mov_b32_e32 v121, v64
	v_mov_b32_e32 v122, v64
	v_mov_b32_e32 v123, v64
	v_mov_b32_e32 v124, v64
	v_mov_b32_e32 v125, v64
	v_mov_b32_e32 v126, v64
	v_mov_b32_e32 v127, v64
	v_mov_b32_e32 v32, v64
	v_mov_b32_e32 v33, v64
	v_mov_b32_e32 v34, v64
	v_mov_b32_e32 v35, v64
	v_mov_b32_e32 v36, v64
	v_mov_b32_e32 v37, v64
	v_mov_b32_e32 v38, v64
	v_mov_b32_e32 v39, v64
	v_mov_b32_e32 v40, v64
	v_mov_b32_e32 v41, v64
	v_mov_b32_e32 v42, v64
	v_mov_b32_e32 v43, v64
	v_mov_b32_e32 v44, v64
	v_mov_b32_e32 v45, v64
	v_mov_b32_e32 v46, v64
	v_mov_b32_e32 v47, v64
	v_mov_b32_e32 v48, v64
	v_mov_b32_e32 v49, v64
	v_mov_b32_e32 v50, v64
	v_mov_b32_e32 v51, v64
	v_mov_b32_e32 v52, v64
	v_mov_b32_e32 v53, v64
	v_mov_b32_e32 v54, v64
	v_mov_b32_e32 v55, v64
	v_mov_b32_e32 v56, v64
	v_mov_b32_e32 v57, v64
	v_mov_b32_e32 v58, v64
	v_mov_b32_e32 v59, v64
	v_mov_b32_e32 v60, v64
	v_mov_b32_e32 v61, v64
	v_mov_b32_e32 v62, v64
	v_mov_b32_e32 v63, v64
	s_branch .LBB0_576

.LBB0_576:
	ds_read_b128 v[154:157], v149
	ds_read_b128 v[158:161], v149 offset:1024
	ds_read_b128 v[162:165], v149 offset:2048
	ds_read_b128 v[166:169], v149 offset:3072
	ds_read_b128 v[170:173], v150
	ds_read_b128 v[174:177], v150 offset:1024
	ds_read_b128 v[178:181], v150 offset:2048
	ds_read_b128 v[182:185], v150 offset:3072
	s_add_i32 s42, s30, 2
	s_add_u32 s43, s52, 0xfff00080
	s_addc_u32 s31, s53, -1
	s_cmp_eq_u32 s37, s30
	s_cselect_b32 s30, s15, s43
	s_cselect_b32 s31, s7, s31
	s_cselect_b32 s55, s17, s39
	s_cselect_b32 s54, s35, s38
	v_lshl_add_u64 v[144:145], s[52:53], 0, v[138:139]
	s_add_i32 m0, s9, 0xc000
	ds_read_b128 v[186:189], v151
	ds_read_b128 v[190:193], v151 offset:1024
	ds_read_b128 v[194:197], v151 offset:2048
	ds_read_b128 v[198:201], v151 offset:3072
	ds_read_b128 v[202:205], v151 offset:4096
	ds_read_b128 v[206:209], v151 offset:5120
	ds_read_b128 v[210:213], v151 offset:6144
	ds_read_b128 v[214:217], v151 offset:7168
	global_load_lds_dwordx4 v[144:145], off
	v_lshl_add_u64 v[144:145], s[52:53], 0, v[140:141]
	s_add_i32 m0, s9, 0xe000
	s_nop 0
	global_load_lds_dwordx4 v[144:145], off
	s_waitcnt vmcnt(8)
	s_waitcnt lgkmcnt(0)
	s_barrier
	v_mfma_f32_16x16x32_bf16 v[60:63], v[154:157], v[186:189], v[60:63]
	v_mfma_f32_16x16x32_bf16 v[56:59], v[162:165], v[186:189], v[56:59]
	v_mfma_f32_16x16x32_bf16 v[52:55], v[154:157], v[194:197], v[52:55]
	v_mfma_f32_16x16x32_bf16 v[48:51], v[162:165], v[194:197], v[48:51]
	v_mfma_f32_16x16x32_bf16 v[44:47], v[154:157], v[202:205], v[44:47]
	v_mfma_f32_16x16x32_bf16 v[40:43], v[162:165], v[202:205], v[40:43]
	v_mfma_f32_16x16x32_bf16 v[36:39], v[154:157], v[210:213], v[36:39]
	v_mfma_f32_16x16x32_bf16 v[32:35], v[162:165], v[210:213], v[32:35]
	v_mfma_f32_16x16x32_bf16 v[60:63], v[158:161], v[190:193], v[60:63]
	v_mfma_f32_16x16x32_bf16 v[56:59], v[166:169], v[190:193], v[56:59]
	v_mfma_f32_16x16x32_bf16 v[52:55], v[158:161], v[198:201], v[52:55]
	v_mfma_f32_16x16x32_bf16 v[48:51], v[166:169], v[198:201], v[48:51]
	v_mfma_f32_16x16x32_bf16 v[44:47], v[158:161], v[206:209], v[44:47]
	v_mfma_f32_16x16x32_bf16 v[40:43], v[166:169], v[206:209], v[40:43]
	v_mfma_f32_16x16x32_bf16 v[36:39], v[158:161], v[214:217], v[36:39]
	v_mfma_f32_16x16x32_bf16 v[32:35], v[166:169], v[214:217], v[32:35]
	v_mfma_f32_16x16x32_bf16 v[124:127], v[170:173], v[186:189], v[124:127]
	v_mfma_f32_16x16x32_bf16 v[120:123], v[178:181], v[186:189], v[120:123]
	v_mfma_f32_16x16x32_bf16 v[116:119], v[170:173], v[194:197], v[116:119]
	v_mfma_f32_16x16x32_bf16 v[112:115], v[178:181], v[194:197], v[112:115]
	v_mfma_f32_16x16x32_bf16 v[108:111], v[170:173], v[202:205], v[108:111]
	v_mfma_f32_16x16x32_bf16 v[104:107], v[178:181], v[202:205], v[104:107]
	v_mfma_f32_16x16x32_bf16 v[100:103], v[170:173], v[210:213], v[100:103]
	v_mfma_f32_16x16x32_bf16 v[96:99], v[178:181], v[210:213], v[96:99]
	v_mfma_f32_16x16x32_bf16 v[124:127], v[174:177], v[190:193], v[124:127]
	v_mfma_f32_16x16x32_bf16 v[120:123], v[182:185], v[190:193], v[120:123]
	v_mfma_f32_16x16x32_bf16 v[116:119], v[174:177], v[198:201], v[116:119]
	v_mfma_f32_16x16x32_bf16 v[112:115], v[182:185], v[198:201], v[112:115]
	v_mfma_f32_16x16x32_bf16 v[108:111], v[174:177], v[206:209], v[108:111]
	v_mfma_f32_16x16x32_bf16 v[104:107], v[182:185], v[206:209], v[104:107]
	v_mfma_f32_16x16x32_bf16 v[100:103], v[174:177], v[214:217], v[100:103]
	v_mfma_f32_16x16x32_bf16 v[96:99], v[182:185], v[214:217], v[96:99]
	s_barrier
	s_add_i32 s43, s74, s33
	v_lshl_add_u64 v[144:145], s[54:55], 0, v[130:131]
	s_mov_b32 m0, s43
	ds_read_b128 v[186:189], v151 offset:16384
	ds_read_b128 v[190:193], v151 offset:17408
	ds_read_b128 v[194:197], v151 offset:18432
	ds_read_b128 v[198:201], v151 offset:19456
	ds_read_b128 v[202:205], v151 offset:20480
	ds_read_b128 v[206:209], v151 offset:21504
	ds_read_b128 v[210:213], v151 offset:22528
	ds_read_b128 v[214:217], v151 offset:23552
	global_load_lds_dwordx4 v[144:145], off
	s_add_i32 m0, s43, 0x2000
	s_add_u32 s48, s54, 0x100000
	v_lshl_add_u64 v[218:219], s[54:55], 0, v[134:135]
	s_addc_u32 s49, s55, 0
	s_add_i32 s43, s75, s33
	global_load_lds_dwordx4 v[218:219], off
	v_lshl_add_u64 v[220:221], s[48:49], 0, v[130:131]
	s_mov_b32 m0, s43
	v_lshl_add_u64 v[222:223], s[30:31], 0, v[132:133]
	global_load_lds_dwordx4 v[220:221], off
	v_lshl_add_u64 v[220:221], s[48:49], 0, v[134:135]
	s_add_i32 m0, s43, 0x2000
	s_nop 0
	global_load_lds_dwordx4 v[220:221], off
	v_lshl_add_u64 v[220:221], s[30:31], 0, v[128:129]
	s_mov_b32 m0, s9
	s_nop 0
	global_load_lds_dwordx4 v[220:221], off
	s_mov_b32 m0, s58
	s_nop 0
	global_load_lds_dwordx4 v[222:223], off
	s_waitcnt vmcnt(8)
	s_waitcnt lgkmcnt(0)
	s_barrier
	v_mfma_f32_16x16x32_bf16 v[28:31], v[154:157], v[186:189], v[28:31]
	v_mfma_f32_16x16x32_bf16 v[24:27], v[162:165], v[186:189], v[24:27]
	v_mfma_f32_16x16x32_bf16 v[20:23], v[154:157], v[194:197], v[20:23]
	v_mfma_f32_16x16x32_bf16 v[16:19], v[162:165], v[194:197], v[16:19]
	v_mfma_f32_16x16x32_bf16 v[12:15], v[154:157], v[202:205], v[12:15]
	v_mfma_f32_16x16x32_bf16 v[8:11], v[162:165], v[202:205], v[8:11]
	v_mfma_f32_16x16x32_bf16 v[4:7], v[154:157], v[210:213], v[4:7]
	v_mfma_f32_16x16x32_bf16 v[0:3], v[162:165], v[210:213], v[0:3]
	v_mfma_f32_16x16x32_bf16 v[28:31], v[158:161], v[190:193], v[28:31]
	v_mfma_f32_16x16x32_bf16 v[24:27], v[166:169], v[190:193], v[24:27]
	v_mfma_f32_16x16x32_bf16 v[20:23], v[158:161], v[198:201], v[20:23]
	v_mfma_f32_16x16x32_bf16 v[16:19], v[166:169], v[198:201], v[16:19]
	v_mfma_f32_16x16x32_bf16 v[12:15], v[158:161], v[206:209], v[12:15]
	v_mfma_f32_16x16x32_bf16 v[8:11], v[166:169], v[206:209], v[8:11]
	v_mfma_f32_16x16x32_bf16 v[4:7], v[158:161], v[214:217], v[4:7]
	v_mfma_f32_16x16x32_bf16 v[0:3], v[166:169], v[214:217], v[0:3]
	v_mfma_f32_16x16x32_bf16 v[92:95], v[170:173], v[186:189], v[92:95]
	v_mfma_f32_16x16x32_bf16 v[88:91], v[178:181], v[186:189], v[88:91]
	v_mfma_f32_16x16x32_bf16 v[84:87], v[170:173], v[194:197], v[84:87]
	v_mfma_f32_16x16x32_bf16 v[80:83], v[178:181], v[194:197], v[80:83]
	v_mfma_f32_16x16x32_bf16 v[76:79], v[170:173], v[202:205], v[76:79]
	v_mfma_f32_16x16x32_bf16 v[72:75], v[178:181], v[202:205], v[72:75]
	v_mfma_f32_16x16x32_bf16 v[68:71], v[170:173], v[210:213], v[68:71]
	v_mfma_f32_16x16x32_bf16 v[64:67], v[178:181], v[210:213], v[64:67]
	v_mfma_f32_16x16x32_bf16 v[92:95], v[174:177], v[190:193], v[92:95]
	v_mfma_f32_16x16x32_bf16 v[88:91], v[182:185], v[190:193], v[88:91]
	v_mfma_f32_16x16x32_bf16 v[84:87], v[174:177], v[198:201], v[84:87]
	v_mfma_f32_16x16x32_bf16 v[80:83], v[182:185], v[198:201], v[80:83]
	v_mfma_f32_16x16x32_bf16 v[76:79], v[174:177], v[206:209], v[76:79]
	v_mfma_f32_16x16x32_bf16 v[72:75], v[182:185], v[206:209], v[72:75]
	v_mfma_f32_16x16x32_bf16 v[68:71], v[174:177], v[214:217], v[68:71]
	v_mfma_f32_16x16x32_bf16 v[64:67], v[182:185], v[214:217], v[64:67]
	s_barrier
	s_add_i32 s43, 0, 0x18000
	v_add_u32_e32 v153, s43, v147
	s_add_i32 s48, 0, 0x1c000
	ds_read_b128 v[154:157], v153
	ds_read_b128 v[158:161], v153 offset:1024
	ds_read_b128 v[162:165], v153 offset:2048
	ds_read_b128 v[166:169], v153 offset:3072
	v_add_u32_e32 v153, s48, v147
	ds_read_b128 v[170:173], v153
	ds_read_b128 v[174:177], v153 offset:1024
	ds_read_b128 v[178:181], v153 offset:2048
	ds_read_b128 v[182:185], v153 offset:3072
	s_add_u32 s30, s30, 0x100000
	s_addc_u32 s31, s31, 0
	s_mov_b32 m0, s59
	v_lshl_add_u64 v[224:225], s[30:31], 0, v[128:129]
	ds_read_b128 v[186:189], v151 offset:32768
	ds_read_b128 v[190:193], v151 offset:33792
	ds_read_b128 v[194:197], v151 offset:34816
	ds_read_b128 v[198:201], v151 offset:35840
	ds_read_b128 v[202:205], v151 offset:36864
	ds_read_b128 v[206:209], v151 offset:37888
	ds_read_b128 v[210:213], v151 offset:38912
	ds_read_b128 v[214:217], v151 offset:39936
	global_load_lds_dwordx4 v[224:225], off
	v_lshl_add_u64 v[224:225], s[30:31], 0, v[132:133]
	s_mov_b32 m0, s60
	s_nop 0
	global_load_lds_dwordx4 v[224:225], off
	s_waitcnt vmcnt(8)
	s_waitcnt lgkmcnt(0)
	s_barrier
	v_mfma_f32_16x16x32_bf16 v[60:63], v[154:157], v[186:189], v[60:63]
	v_mfma_f32_16x16x32_bf16 v[56:59], v[162:165], v[186:189], v[56:59]
	v_mfma_f32_16x16x32_bf16 v[52:55], v[154:157], v[194:197], v[52:55]
	v_mfma_f32_16x16x32_bf16 v[48:51], v[162:165], v[194:197], v[48:51]
	v_mfma_f32_16x16x32_bf16 v[44:47], v[154:157], v[202:205], v[44:47]
	v_mfma_f32_16x16x32_bf16 v[40:43], v[162:165], v[202:205], v[40:43]
	v_mfma_f32_16x16x32_bf16 v[36:39], v[154:157], v[210:213], v[36:39]
	v_mfma_f32_16x16x32_bf16 v[32:35], v[162:165], v[210:213], v[32:35]
	v_mfma_f32_16x16x32_bf16 v[60:63], v[158:161], v[190:193], v[60:63]
	v_mfma_f32_16x16x32_bf16 v[56:59], v[166:169], v[190:193], v[56:59]
	v_mfma_f32_16x16x32_bf16 v[52:55], v[158:161], v[198:201], v[52:55]
	v_mfma_f32_16x16x32_bf16 v[48:51], v[166:169], v[198:201], v[48:51]
	v_mfma_f32_16x16x32_bf16 v[44:47], v[158:161], v[206:209], v[44:47]
	v_mfma_f32_16x16x32_bf16 v[40:43], v[166:169], v[206:209], v[40:43]
	v_mfma_f32_16x16x32_bf16 v[36:39], v[158:161], v[214:217], v[36:39]
	v_mfma_f32_16x16x32_bf16 v[32:35], v[166:169], v[214:217], v[32:35]
	v_mfma_f32_16x16x32_bf16 v[124:127], v[170:173], v[186:189], v[124:127]
	v_mfma_f32_16x16x32_bf16 v[120:123], v[178:181], v[186:189], v[120:123]
	v_mfma_f32_16x16x32_bf16 v[116:119], v[170:173], v[194:197], v[116:119]
	v_mfma_f32_16x16x32_bf16 v[112:115], v[178:181], v[194:197], v[112:115]
	v_mfma_f32_16x16x32_bf16 v[108:111], v[170:173], v[202:205], v[108:111]
	v_mfma_f32_16x16x32_bf16 v[104:107], v[178:181], v[202:205], v[104:107]
	v_mfma_f32_16x16x32_bf16 v[100:103], v[170:173], v[210:213], v[100:103]
	v_mfma_f32_16x16x32_bf16 v[96:99], v[178:181], v[210:213], v[96:99]
	v_mfma_f32_16x16x32_bf16 v[124:127], v[174:177], v[190:193], v[124:127]
	v_mfma_f32_16x16x32_bf16 v[120:123], v[182:185], v[190:193], v[120:123]
	v_mfma_f32_16x16x32_bf16 v[116:119], v[174:177], v[198:201], v[116:119]
	v_mfma_f32_16x16x32_bf16 v[112:115], v[182:185], v[198:201], v[112:115]
	v_mfma_f32_16x16x32_bf16 v[108:111], v[174:177], v[206:209], v[108:111]
	v_mfma_f32_16x16x32_bf16 v[104:107], v[182:185], v[206:209], v[104:107]
	v_mfma_f32_16x16x32_bf16 v[100:103], v[174:177], v[214:217], v[100:103]
	v_mfma_f32_16x16x32_bf16 v[96:99], v[182:185], v[214:217], v[96:99]
	s_barrier
	s_add_i32 s30, s43, s33
	v_lshl_add_u64 v[144:145], v[144:145], 0, s[4:5]
	s_mov_b32 m0, s30
	ds_read_b128 v[186:189], v151 offset:49152
	ds_read_b128 v[190:193], v151 offset:50176
	ds_read_b128 v[194:197], v151 offset:51200
	ds_read_b128 v[198:201], v151 offset:52224
	ds_read_b128 v[202:205], v151 offset:53248
	ds_read_b128 v[206:209], v151 offset:54272
	ds_read_b128 v[210:213], v151 offset:55296
	ds_read_b128 v[214:217], v151 offset:56320
	global_load_lds_dwordx4 v[144:145], off
	s_add_i32 m0, s30, 0x2000
	s_add_u32 s30, s54, 0x100080
	v_lshl_add_u64 v[144:145], v[218:219], 0, s[4:5]
	s_addc_u32 s31, s55, 0
	s_add_i32 s43, s48, s33
	global_load_lds_dwordx4 v[144:145], off
	v_lshl_add_u64 v[144:145], s[30:31], 0, v[130:131]
	s_mov_b32 m0, s43
	s_nop 0
	global_load_lds_dwordx4 v[144:145], off
	v_lshl_add_u64 v[144:145], s[30:31], 0, v[134:135]
	s_add_i32 m0, s43, 0x2000
	s_nop 0
	global_load_lds_dwordx4 v[144:145], off
	v_lshl_add_u64 v[144:145], v[220:221], 0, s[4:5]
	s_mov_b32 m0, s70
	s_nop 0
	global_load_lds_dwordx4 v[144:145], off
	v_lshl_add_u64 v[144:145], v[222:223], 0, s[4:5]
	s_mov_b32 m0, s71
	s_nop 0
	global_load_lds_dwordx4 v[144:145], off
	s_waitcnt vmcnt(8)
	s_waitcnt lgkmcnt(0)
	s_barrier
	v_mfma_f32_16x16x32_bf16 v[28:31], v[154:157], v[186:189], v[28:31]
	v_mfma_f32_16x16x32_bf16 v[24:27], v[162:165], v[186:189], v[24:27]
	v_mfma_f32_16x16x32_bf16 v[20:23], v[154:157], v[194:197], v[20:23]
	v_mfma_f32_16x16x32_bf16 v[16:19], v[162:165], v[194:197], v[16:19]
	v_mfma_f32_16x16x32_bf16 v[12:15], v[154:157], v[202:205], v[12:15]
	v_mfma_f32_16x16x32_bf16 v[8:11], v[162:165], v[202:205], v[8:11]
	v_mfma_f32_16x16x32_bf16 v[4:7], v[154:157], v[210:213], v[4:7]
	v_mfma_f32_16x16x32_bf16 v[0:3], v[162:165], v[210:213], v[0:3]
	v_mfma_f32_16x16x32_bf16 v[28:31], v[158:161], v[190:193], v[28:31]
	v_mfma_f32_16x16x32_bf16 v[24:27], v[166:169], v[190:193], v[24:27]
	v_mfma_f32_16x16x32_bf16 v[20:23], v[158:161], v[198:201], v[20:23]
	v_mfma_f32_16x16x32_bf16 v[16:19], v[166:169], v[198:201], v[16:19]
	v_mfma_f32_16x16x32_bf16 v[12:15], v[158:161], v[206:209], v[12:15]
	v_mfma_f32_16x16x32_bf16 v[8:11], v[166:169], v[206:209], v[8:11]
	v_mfma_f32_16x16x32_bf16 v[4:7], v[158:161], v[214:217], v[4:7]
	v_mfma_f32_16x16x32_bf16 v[0:3], v[166:169], v[214:217], v[0:3]
	v_mfma_f32_16x16x32_bf16 v[92:95], v[170:173], v[186:189], v[92:95]
	v_mfma_f32_16x16x32_bf16 v[88:91], v[178:181], v[186:189], v[88:91]
	v_mfma_f32_16x16x32_bf16 v[84:87], v[170:173], v[194:197], v[84:87]
	v_mfma_f32_16x16x32_bf16 v[80:83], v[178:181], v[194:197], v[80:83]
	v_mfma_f32_16x16x32_bf16 v[76:79], v[170:173], v[202:205], v[76:79]
	v_mfma_f32_16x16x32_bf16 v[72:75], v[178:181], v[202:205], v[72:75]
	v_mfma_f32_16x16x32_bf16 v[68:71], v[170:173], v[210:213], v[68:71]
	v_mfma_f32_16x16x32_bf16 v[64:67], v[178:181], v[210:213], v[64:67]
	v_mfma_f32_16x16x32_bf16 v[92:95], v[174:177], v[190:193], v[92:95]
	v_mfma_f32_16x16x32_bf16 v[88:91], v[182:185], v[190:193], v[88:91]
	v_mfma_f32_16x16x32_bf16 v[84:87], v[174:177], v[198:201], v[84:87]
	v_mfma_f32_16x16x32_bf16 v[80:83], v[182:185], v[198:201], v[80:83]
	v_mfma_f32_16x16x32_bf16 v[76:79], v[174:177], v[206:209], v[76:79]
	v_mfma_f32_16x16x32_bf16 v[72:75], v[182:185], v[206:209], v[72:75]
	v_mfma_f32_16x16x32_bf16 v[68:71], v[174:177], v[214:217], v[68:71]
	v_mfma_f32_16x16x32_bf16 v[64:67], v[182:185], v[214:217], v[64:67]
	s_add_u32 s52, s52, 0x100
	s_addc_u32 s53, s53, 0
	s_add_u32 s38, s38, 0x100
	s_addc_u32 s39, s39, 0
	s_cmp_ge_i32 s42, s36
	s_mov_b32 s30, s42
	s_cbranch_scc0 .Lrot_576
	s_barrier
	s_and_b64 vcc, exec, s[10:11]
	s_cbranch_vccz .LBB0_581

.LBB0_737:
	s_ashr_i32 s39, s38, 31
	s_lshl_b64 s[30:31], s[38:39], 19
	s_add_u32 s40, s33, s30
	s_addc_u32 s41, s52, s31
	s_and_b64 s[30:31], s[0:1], exec
	s_cselect_b32 s36, s41, s45
	s_cselect_b32 s37, s40, s44
	s_ashr_i32 s35, s34, 31
	s_lshl_b64 s[30:31], s[34:35], 19
	s_add_u32 s42, s28, s30
	s_addc_u32 s43, s29, s31
	s_and_b64 s[30:31], s[0:1], exec
	s_cselect_b32 s35, s43, s47
	s_cselect_b32 s39, s42, s46
	s_add_u32 s44, s44, 0x40080
	s_addc_u32 s45, s45, 0
	s_add_u32 s48, s46, 0x100
	v_mov_b32_e32 v0, 0
	s_addc_u32 s49, s47, 0
	s_mov_b32 s50, -2
	v_mov_b32_e32 v1, v0
	v_mov_b32_e32 v2, v0
	v_mov_b32_e32 v3, v0
	v_mov_b32_e32 v4, v0
	v_mov_b32_e32 v5, v0
	v_mov_b32_e32 v6, v0
	v_mov_b32_e32 v7, v0
	v_mov_b32_e32 v8, v0
	v_mov_b32_e32 v9, v0
	v_mov_b32_e32 v10, v0
	v_mov_b32_e32 v11, v0
	v_mov_b32_e32 v16, v0
	v_mov_b32_e32 v17, v0
	v_mov_b32_e32 v18, v0
	v_mov_b32_e32 v19, v0
	v_mov_b32_e32 v24, v0
	v_mov_b32_e32 v25, v0
	v_mov_b32_e32 v26, v0
	v_mov_b32_e32 v27, v0
	v_mov_b32_e32 v32, v0
	v_mov_b32_e32 v33, v0
	v_mov_b32_e32 v34, v0
	v_mov_b32_e32 v35, v0
	v_mov_b32_e32 v40, v0
	v_mov_b32_e32 v41, v0
	v_mov_b32_e32 v42, v0
	v_mov_b32_e32 v43, v0
	v_mov_b32_e32 v48, v0
	v_mov_b32_e32 v49, v0
	v_mov_b32_e32 v50, v0
	v_mov_b32_e32 v51, v0
	v_mov_b32_e32 v12, v0
	v_mov_b32_e32 v13, v0
	v_mov_b32_e32 v14, v0
	v_mov_b32_e32 v15, v0
	v_mov_b32_e32 v20, v0
	v_mov_b32_e32 v21, v0
	v_mov_b32_e32 v22, v0
	v_mov_b32_e32 v23, v0
	v_mov_b32_e32 v28, v0
	v_mov_b32_e32 v29, v0
	v_mov_b32_e32 v30, v0
	v_mov_b32_e32 v31, v0
	v_mov_b32_e32 v36, v0
	v_mov_b32_e32 v37, v0
	v_mov_b32_e32 v38, v0
	v_mov_b32_e32 v39, v0
	v_mov_b32_e32 v44, v0
	v_mov_b32_e32 v45, v0
	v_mov_b32_e32 v46, v0
	v_mov_b32_e32 v47, v0
	v_mov_b32_e32 v52, v0
	v_mov_b32_e32 v53, v0
	v_mov_b32_e32 v54, v0
	v_mov_b32_e32 v55, v0
	v_mov_b32_e32 v56, v0
	v_mov_b32_e32 v57, v0
	v_mov_b32_e32 v58, v0
	v_mov_b32_e32 v59, v0
	v_mov_b32_e32 v60, v0
	v_mov_b32_e32 v61, v0
	v_mov_b32_e32 v62, v0
	v_mov_b32_e32 v63, v0
	v_mov_b32_e32 v64, v0
	v_mov_b32_e32 v65, v0
	v_mov_b32_e32 v66, v0
	v_mov_b32_e32 v67, v0
	v_mov_b32_e32 v68, v0
	v_mov_b32_e32 v69, v0
	v_mov_b32_e32 v70, v0
	v_mov_b32_e32 v71, v0
	v_mov_b32_e32 v72, v0
	v_mov_b32_e32 v73, v0
	v_mov_b32_e32 v74, v0
	v_mov_b32_e32 v75, v0
	v_mov_b32_e32 v80, v0
	v_mov_b32_e32 v81, v0
	v_mov_b32_e32 v82, v0
	v_mov_b32_e32 v83, v0
	v_mov_b32_e32 v88, v0
	v_mov_b32_e32 v89, v0
	v_mov_b32_e32 v90, v0
	v_mov_b32_e32 v91, v0
	v_mov_b32_e32 v96, v0
	v_mov_b32_e32 v97, v0
	v_mov_b32_e32 v98, v0
	v_mov_b32_e32 v99, v0
	v_mov_b32_e32 v104, v0
	v_mov_b32_e32 v105, v0
	v_mov_b32_e32 v106, v0
	v_mov_b32_e32 v107, v0
	v_mov_b32_e32 v112, v0
	v_mov_b32_e32 v113, v0
	v_mov_b32_e32 v114, v0
	v_mov_b32_e32 v115, v0
	v_mov_b32_e32 v76, v0
	v_mov_b32_e32 v77, v0
	v_mov_b32_e32 v78, v0
	v_mov_b32_e32 v79, v0
	v_mov_b32_e32 v84, v0
	v_mov_b32_e32 v85, v0
	v_mov_b32_e32 v86, v0
	v_mov_b32_e32 v87, v0
	v_mov_b32_e32 v92, v0
	v_mov_b32_e32 v93, v0
	v_mov_b32_e32 v94, v0
	v_mov_b32_e32 v95, v0
	v_mov_b32_e32 v100, v0
	v_mov_b32_e32 v101, v0
	v_mov_b32_e32 v102, v0
	v_mov_b32_e32 v103, v0
	v_mov_b32_e32 v108, v0
	v_mov_b32_e32 v109, v0
	v_mov_b32_e32 v110, v0
	v_mov_b32_e32 v111, v0
	v_mov_b32_e32 v116, v0
	v_mov_b32_e32 v117, v0
	v_mov_b32_e32 v118, v0
	v_mov_b32_e32 v119, v0
	v_mov_b32_e32 v120, v0
	v_mov_b32_e32 v121, v0
	v_mov_b32_e32 v122, v0
	v_mov_b32_e32 v123, v0
	v_mov_b32_e32 v124, v0
	v_mov_b32_e32 v125, v0
	v_mov_b32_e32 v126, v0
	v_mov_b32_e32 v127, v0
	s_branch .LBB0_738

.LBB0_738:
	ds_read_b128 v[182:185], v129
	ds_read_b128 v[186:189], v129 offset:1024
	ds_read_b128 v[190:193], v129 offset:2048
	ds_read_b128 v[194:197], v129 offset:3072
	ds_read_b128 v[198:201], v178
	ds_read_b128 v[202:205], v178 offset:1024
	ds_read_b128 v[206:209], v178 offset:2048
	ds_read_b128 v[210:213], v178 offset:3072
	s_add_u32 s30, s44, 0xfffc0080
	s_addc_u32 s31, s45, -1
	s_cmp_eq_u32 s50, 12
	s_cselect_b32 s31, s36, s31
	s_cselect_b32 s30, s37, s30
	s_cselect_b32 s47, s35, s49
	s_cselect_b32 s46, s39, s48
	v_lshl_add_u64 v[154:155], s[44:45], 0, v[146:147]
	s_add_i32 m0, s54, 0xc000
	ds_read_b128 v[214:217], v179
	ds_read_b128 v[218:221], v179 offset:1024
	ds_read_b128 v[222:225], v179 offset:2048
	ds_read_b128 v[226:229], v179 offset:3072
	ds_read_b128 v[230:233], v179 offset:4096
	ds_read_b128 v[234:237], v179 offset:5120
	ds_read_b128 v[238:241], v179 offset:6144
	ds_read_b128 v[242:245], v179 offset:7168
	global_load_lds_dwordx4 v[154:155], off
	v_lshl_add_u64 v[154:155], s[44:45], 0, v[148:149]
	s_add_i32 m0, s54, 0xe000
	s_nop 0
	global_load_lds_dwordx4 v[154:155], off
	s_waitcnt vmcnt(8)
	s_waitcnt lgkmcnt(0)
	s_barrier
	v_mfma_f32_16x16x32_bf16 v[124:127], v[182:185], v[214:217], v[124:127]
	v_mfma_f32_16x16x32_bf16 v[120:123], v[190:193], v[214:217], v[120:123]
	v_mfma_f32_16x16x32_bf16 v[116:119], v[182:185], v[222:225], v[116:119]
	v_mfma_f32_16x16x32_bf16 v[108:111], v[190:193], v[222:225], v[108:111]
	v_mfma_f32_16x16x32_bf16 v[100:103], v[182:185], v[230:233], v[100:103]
	v_mfma_f32_16x16x32_bf16 v[92:95], v[190:193], v[230:233], v[92:95]
	v_mfma_f32_16x16x32_bf16 v[84:87], v[182:185], v[238:241], v[84:87]
	v_mfma_f32_16x16x32_bf16 v[76:79], v[190:193], v[238:241], v[76:79]
	v_mfma_f32_16x16x32_bf16 v[124:127], v[186:189], v[218:221], v[124:127]
	v_mfma_f32_16x16x32_bf16 v[120:123], v[194:197], v[218:221], v[120:123]
	v_mfma_f32_16x16x32_bf16 v[116:119], v[186:189], v[226:229], v[116:119]
	v_mfma_f32_16x16x32_bf16 v[108:111], v[194:197], v[226:229], v[108:111]
	v_mfma_f32_16x16x32_bf16 v[100:103], v[186:189], v[234:237], v[100:103]
	v_mfma_f32_16x16x32_bf16 v[92:95], v[194:197], v[234:237], v[92:95]
	v_mfma_f32_16x16x32_bf16 v[84:87], v[186:189], v[242:245], v[84:87]
	v_mfma_f32_16x16x32_bf16 v[76:79], v[194:197], v[242:245], v[76:79]
	v_mfma_f32_16x16x32_bf16 v[112:115], v[198:201], v[214:217], v[112:115]
	v_mfma_f32_16x16x32_bf16 v[104:107], v[206:209], v[214:217], v[104:107]
	v_mfma_f32_16x16x32_bf16 v[96:99], v[198:201], v[222:225], v[96:99]
	v_mfma_f32_16x16x32_bf16 v[88:91], v[206:209], v[222:225], v[88:91]
	v_mfma_f32_16x16x32_bf16 v[80:83], v[198:201], v[230:233], v[80:83]
	v_mfma_f32_16x16x32_bf16 v[72:75], v[206:209], v[230:233], v[72:75]
	v_mfma_f32_16x16x32_bf16 v[68:71], v[198:201], v[238:241], v[68:71]
	v_mfma_f32_16x16x32_bf16 v[64:67], v[206:209], v[238:241], v[64:67]
	v_mfma_f32_16x16x32_bf16 v[112:115], v[202:205], v[218:221], v[112:115]
	v_mfma_f32_16x16x32_bf16 v[104:107], v[210:213], v[218:221], v[104:107]
	v_mfma_f32_16x16x32_bf16 v[96:99], v[202:205], v[226:229], v[96:99]
	v_mfma_f32_16x16x32_bf16 v[88:91], v[210:213], v[226:229], v[88:91]
	v_mfma_f32_16x16x32_bf16 v[80:83], v[202:205], v[234:237], v[80:83]
	v_mfma_f32_16x16x32_bf16 v[72:75], v[210:213], v[234:237], v[72:75]
	v_mfma_f32_16x16x32_bf16 v[68:71], v[202:205], v[242:245], v[68:71]
	v_mfma_f32_16x16x32_bf16 v[64:67], v[210:213], v[242:245], v[64:67]
	s_barrier
	s_add_i32 s51, s62, s15
	v_lshl_add_u64 v[154:155], s[46:47], 0, v[136:137]
	s_mov_b32 m0, s51
	ds_read_b128 v[214:217], v179 offset:16384
	ds_read_b128 v[218:221], v179 offset:17408
	ds_read_b128 v[222:225], v179 offset:18432
	ds_read_b128 v[226:229], v179 offset:19456
	ds_read_b128 v[230:233], v179 offset:20480
	ds_read_b128 v[234:237], v179 offset:21504
	ds_read_b128 v[238:241], v179 offset:22528
	ds_read_b128 v[242:245], v179 offset:23552
	global_load_lds_dwordx4 v[154:155], off
	s_add_i32 m0, s51, 0x2000
	s_add_u32 s70, s46, 0x40000
	v_lshl_add_u64 v[246:247], s[46:47], 0, v[132:133]
	s_addc_u32 s71, s47, 0
	s_add_i32 s51, s63, s15
	global_load_lds_dwordx4 v[246:247], off
	v_lshl_add_u64 v[248:249], s[70:71], 0, v[136:137]
	s_mov_b32 m0, s51
	v_lshl_add_u64 v[250:251], s[30:31], 0, v[134:135]
	global_load_lds_dwordx4 v[248:249], off
	v_lshl_add_u64 v[248:249], s[70:71], 0, v[132:133]
	s_add_i32 m0, s51, 0x2000
	s_nop 0
	global_load_lds_dwordx4 v[248:249], off
	v_lshl_add_u64 v[248:249], s[30:31], 0, v[138:139]
	s_mov_b32 m0, s54
	s_nop 0
	global_load_lds_dwordx4 v[248:249], off
	s_mov_b32 m0, s55
	s_nop 0
	global_load_lds_dwordx4 v[250:251], off
	s_waitcnt vmcnt(8)
	s_waitcnt lgkmcnt(0)
	s_barrier
	v_mfma_f32_16x16x32_bf16 v[60:63], v[182:185], v[214:217], v[60:63]
	v_mfma_f32_16x16x32_bf16 v[56:59], v[190:193], v[214:217], v[56:59]
	v_mfma_f32_16x16x32_bf16 v[52:55], v[182:185], v[222:225], v[52:55]
	v_mfma_f32_16x16x32_bf16 v[44:47], v[190:193], v[222:225], v[44:47]
	v_mfma_f32_16x16x32_bf16 v[36:39], v[182:185], v[230:233], v[36:39]
	v_mfma_f32_16x16x32_bf16 v[28:31], v[190:193], v[230:233], v[28:31]
	v_mfma_f32_16x16x32_bf16 v[20:23], v[182:185], v[238:241], v[20:23]
	v_mfma_f32_16x16x32_bf16 v[12:15], v[190:193], v[238:241], v[12:15]
	v_mfma_f32_16x16x32_bf16 v[60:63], v[186:189], v[218:221], v[60:63]
	v_mfma_f32_16x16x32_bf16 v[56:59], v[194:197], v[218:221], v[56:59]
	v_mfma_f32_16x16x32_bf16 v[52:55], v[186:189], v[226:229], v[52:55]
	v_mfma_f32_16x16x32_bf16 v[44:47], v[194:197], v[226:229], v[44:47]
	v_mfma_f32_16x16x32_bf16 v[36:39], v[186:189], v[234:237], v[36:39]
	v_mfma_f32_16x16x32_bf16 v[28:31], v[194:197], v[234:237], v[28:31]
	v_mfma_f32_16x16x32_bf16 v[20:23], v[186:189], v[242:245], v[20:23]
	v_mfma_f32_16x16x32_bf16 v[12:15], v[194:197], v[242:245], v[12:15]
	v_mfma_f32_16x16x32_bf16 v[48:51], v[198:201], v[214:217], v[48:51]
	v_mfma_f32_16x16x32_bf16 v[40:43], v[206:209], v[214:217], v[40:43]
	v_mfma_f32_16x16x32_bf16 v[32:35], v[198:201], v[222:225], v[32:35]
	v_mfma_f32_16x16x32_bf16 v[24:27], v[206:209], v[222:225], v[24:27]
	v_mfma_f32_16x16x32_bf16 v[16:19], v[198:201], v[230:233], v[16:19]
	v_mfma_f32_16x16x32_bf16 v[8:11], v[206:209], v[230:233], v[8:11]
	v_mfma_f32_16x16x32_bf16 v[4:7], v[198:201], v[238:241], v[4:7]
	v_mfma_f32_16x16x32_bf16 v[0:3], v[206:209], v[238:241], v[0:3]
	v_mfma_f32_16x16x32_bf16 v[48:51], v[202:205], v[218:221], v[48:51]
	v_mfma_f32_16x16x32_bf16 v[40:43], v[210:213], v[218:221], v[40:43]
	v_mfma_f32_16x16x32_bf16 v[32:35], v[202:205], v[226:229], v[32:35]
	v_mfma_f32_16x16x32_bf16 v[24:27], v[210:213], v[226:229], v[24:27]
	v_mfma_f32_16x16x32_bf16 v[16:19], v[202:205], v[234:237], v[16:19]
	v_mfma_f32_16x16x32_bf16 v[8:11], v[210:213], v[234:237], v[8:11]
	v_mfma_f32_16x16x32_bf16 v[4:7], v[202:205], v[242:245], v[4:7]
	v_mfma_f32_16x16x32_bf16 v[0:3], v[210:213], v[242:245], v[0:3]
	s_barrier
	s_add_i32 s51, 0, 0x18000
	v_add_u32_e32 v166, s51, v176
	s_add_i32 s70, 0, 0x1c000
	ds_read_b128 v[182:185], v166
	ds_read_b128 v[186:189], v166 offset:1024
	ds_read_b128 v[190:193], v166 offset:2048
	ds_read_b128 v[194:197], v166 offset:3072
	v_add_u32_e32 v166, s70, v176
	ds_read_b128 v[198:201], v166
	ds_read_b128 v[202:205], v166 offset:1024
	ds_read_b128 v[206:209], v166 offset:2048
	ds_read_b128 v[210:213], v166 offset:3072
	s_add_u32 s30, s30, 0x40000
	s_addc_u32 s31, s31, 0
	s_mov_b32 m0, s56
	v_lshl_add_u64 v[166:167], s[30:31], 0, v[138:139]
	ds_read_b128 v[214:217], v179 offset:32768
	ds_read_b128 v[218:221], v179 offset:33792
	ds_read_b128 v[222:225], v179 offset:34816
	ds_read_b128 v[226:229], v179 offset:35840
	ds_read_b128 v[230:233], v179 offset:36864
	ds_read_b128 v[234:237], v179 offset:37888
	ds_read_b128 v[238:241], v179 offset:38912
	ds_read_b128 v[242:245], v179 offset:39936
	global_load_lds_dwordx4 v[166:167], off
	v_lshl_add_u64 v[166:167], s[30:31], 0, v[134:135]
	s_mov_b32 m0, s57
	s_nop 0
	global_load_lds_dwordx4 v[166:167], off
	s_waitcnt vmcnt(8)
	s_waitcnt lgkmcnt(0)
	s_barrier
	v_mfma_f32_16x16x32_bf16 v[124:127], v[182:185], v[214:217], v[124:127]
	v_mfma_f32_16x16x32_bf16 v[120:123], v[190:193], v[214:217], v[120:123]
	v_mfma_f32_16x16x32_bf16 v[116:119], v[182:185], v[222:225], v[116:119]
	v_mfma_f32_16x16x32_bf16 v[108:111], v[190:193], v[222:225], v[108:111]
	v_mfma_f32_16x16x32_bf16 v[100:103], v[182:185], v[230:233], v[100:103]
	v_mfma_f32_16x16x32_bf16 v[92:95], v[190:193], v[230:233], v[92:95]
	v_mfma_f32_16x16x32_bf16 v[84:87], v[182:185], v[238:241], v[84:87]
	v_mfma_f32_16x16x32_bf16 v[76:79], v[190:193], v[238:241], v[76:79]
	v_mfma_f32_16x16x32_bf16 v[124:127], v[186:189], v[218:221], v[124:127]
	v_mfma_f32_16x16x32_bf16 v[120:123], v[194:197], v[218:221], v[120:123]
	v_mfma_f32_16x16x32_bf16 v[116:119], v[186:189], v[226:229], v[116:119]
	v_mfma_f32_16x16x32_bf16 v[108:111], v[194:197], v[226:229], v[108:111]
	v_mfma_f32_16x16x32_bf16 v[100:103], v[186:189], v[234:237], v[100:103]
	v_mfma_f32_16x16x32_bf16 v[92:95], v[194:197], v[234:237], v[92:95]
	v_mfma_f32_16x16x32_bf16 v[84:87], v[186:189], v[242:245], v[84:87]
	v_mfma_f32_16x16x32_bf16 v[76:79], v[194:197], v[242:245], v[76:79]
	v_mfma_f32_16x16x32_bf16 v[112:115], v[198:201], v[214:217], v[112:115]
	v_mfma_f32_16x16x32_bf16 v[104:107], v[206:209], v[214:217], v[104:107]
	v_mfma_f32_16x16x32_bf16 v[96:99], v[198:201], v[222:225], v[96:99]
	v_mfma_f32_16x16x32_bf16 v[88:91], v[206:209], v[222:225], v[88:91]
	v_mfma_f32_16x16x32_bf16 v[80:83], v[198:201], v[230:233], v[80:83]
	v_mfma_f32_16x16x32_bf16 v[72:75], v[206:209], v[230:233], v[72:75]
	v_mfma_f32_16x16x32_bf16 v[68:71], v[198:201], v[238:241], v[68:71]
	v_mfma_f32_16x16x32_bf16 v[64:67], v[206:209], v[238:241], v[64:67]
	v_mfma_f32_16x16x32_bf16 v[112:115], v[202:205], v[218:221], v[112:115]
	v_mfma_f32_16x16x32_bf16 v[104:107], v[210:213], v[218:221], v[104:107]
	v_mfma_f32_16x16x32_bf16 v[96:99], v[202:205], v[226:229], v[96:99]
	v_mfma_f32_16x16x32_bf16 v[88:91], v[210:213], v[226:229], v[88:91]
	v_mfma_f32_16x16x32_bf16 v[80:83], v[202:205], v[234:237], v[80:83]
	v_mfma_f32_16x16x32_bf16 v[72:75], v[210:213], v[234:237], v[72:75]
	v_mfma_f32_16x16x32_bf16 v[68:71], v[202:205], v[242:245], v[68:71]
	v_mfma_f32_16x16x32_bf16 v[64:67], v[210:213], v[242:245], v[64:67]
	s_barrier
	s_add_i32 s30, s51, s15
	v_lshl_add_u64 v[154:155], v[154:155], 0, s[6:7]
	s_mov_b32 m0, s30
	ds_read_b128 v[214:217], v179 offset:49152
	ds_read_b128 v[218:221], v179 offset:50176
	ds_read_b128 v[222:225], v179 offset:51200
	ds_read_b128 v[226:229], v179 offset:52224
	ds_read_b128 v[230:233], v179 offset:53248
	ds_read_b128 v[234:237], v179 offset:54272
	ds_read_b128 v[238:241], v179 offset:55296
	ds_read_b128 v[242:245], v179 offset:56320
	global_load_lds_dwordx4 v[154:155], off
	s_add_i32 m0, s30, 0x2000
	s_add_u32 s30, s46, 0x40080
	v_lshl_add_u64 v[154:155], v[246:247], 0, s[6:7]
	s_addc_u32 s31, s47, 0
	s_add_i32 s46, s70, s15
	global_load_lds_dwordx4 v[154:155], off
	v_lshl_add_u64 v[154:155], s[30:31], 0, v[136:137]
	s_mov_b32 m0, s46
	s_nop 0
	global_load_lds_dwordx4 v[154:155], off
	v_lshl_add_u64 v[154:155], s[30:31], 0, v[132:133]
	s_add_i32 m0, s46, 0x2000
	s_nop 0
	global_load_lds_dwordx4 v[154:155], off
	v_lshl_add_u64 v[154:155], v[248:249], 0, s[6:7]
	s_mov_b32 m0, s59
	s_nop 0
	global_load_lds_dwordx4 v[154:155], off
	v_lshl_add_u64 v[154:155], v[250:251], 0, s[6:7]
	s_mov_b32 m0, s60
	s_nop 0
	global_load_lds_dwordx4 v[154:155], off
	s_waitcnt vmcnt(8)
	s_waitcnt lgkmcnt(0)
	s_barrier
	v_mfma_f32_16x16x32_bf16 v[60:63], v[182:185], v[214:217], v[60:63]
	v_mfma_f32_16x16x32_bf16 v[56:59], v[190:193], v[214:217], v[56:59]
	v_mfma_f32_16x16x32_bf16 v[52:55], v[182:185], v[222:225], v[52:55]
	v_mfma_f32_16x16x32_bf16 v[44:47], v[190:193], v[222:225], v[44:47]
	v_mfma_f32_16x16x32_bf16 v[36:39], v[182:185], v[230:233], v[36:39]
	v_mfma_f32_16x16x32_bf16 v[28:31], v[190:193], v[230:233], v[28:31]
	v_mfma_f32_16x16x32_bf16 v[20:23], v[182:185], v[238:241], v[20:23]
	v_mfma_f32_16x16x32_bf16 v[12:15], v[190:193], v[238:241], v[12:15]
	v_mfma_f32_16x16x32_bf16 v[60:63], v[186:189], v[218:221], v[60:63]
	v_mfma_f32_16x16x32_bf16 v[56:59], v[194:197], v[218:221], v[56:59]
	v_mfma_f32_16x16x32_bf16 v[52:55], v[186:189], v[226:229], v[52:55]
	v_mfma_f32_16x16x32_bf16 v[44:47], v[194:197], v[226:229], v[44:47]
	v_mfma_f32_16x16x32_bf16 v[36:39], v[186:189], v[234:237], v[36:39]
	v_mfma_f32_16x16x32_bf16 v[28:31], v[194:197], v[234:237], v[28:31]
	v_mfma_f32_16x16x32_bf16 v[20:23], v[186:189], v[242:245], v[20:23]
	v_mfma_f32_16x16x32_bf16 v[12:15], v[194:197], v[242:245], v[12:15]
	v_mfma_f32_16x16x32_bf16 v[48:51], v[198:201], v[214:217], v[48:51]
	v_mfma_f32_16x16x32_bf16 v[40:43], v[206:209], v[214:217], v[40:43]
	v_mfma_f32_16x16x32_bf16 v[32:35], v[198:201], v[222:225], v[32:35]
	v_mfma_f32_16x16x32_bf16 v[24:27], v[206:209], v[222:225], v[24:27]
	v_mfma_f32_16x16x32_bf16 v[16:19], v[198:201], v[230:233], v[16:19]
	v_mfma_f32_16x16x32_bf16 v[8:11], v[206:209], v[230:233], v[8:11]
	v_mfma_f32_16x16x32_bf16 v[4:7], v[198:201], v[238:241], v[4:7]
	v_mfma_f32_16x16x32_bf16 v[0:3], v[206:209], v[238:241], v[0:3]
	v_mfma_f32_16x16x32_bf16 v[48:51], v[202:205], v[218:221], v[48:51]
	v_mfma_f32_16x16x32_bf16 v[40:43], v[210:213], v[218:221], v[40:43]
	v_mfma_f32_16x16x32_bf16 v[32:35], v[202:205], v[226:229], v[32:35]
	v_mfma_f32_16x16x32_bf16 v[24:27], v[210:213], v[226:229], v[24:27]
	v_mfma_f32_16x16x32_bf16 v[16:19], v[202:205], v[234:237], v[16:19]
	v_mfma_f32_16x16x32_bf16 v[8:11], v[210:213], v[234:237], v[8:11]
	v_mfma_f32_16x16x32_bf16 v[4:7], v[202:205], v[242:245], v[4:7]
	v_mfma_f32_16x16x32_bf16 v[0:3], v[210:213], v[242:245], v[0:3]
	s_add_i32 s50, s50, 2
	s_add_u32 s44, s44, 0x100
	s_addc_u32 s45, s45, 0
	s_add_u32 s48, s48, 0x100
	s_addc_u32 s49, s49, 0
	s_cmp_gt_u32 s50, 13
	s_cbranch_scc0 .Lrot_738
	s_barrier
	s_and_b64 vcc, exec, s[8:9]
	s_cbranch_vccz .LBB0_741
	s_barrier

.LBB0_757:
	s_ashr_i32 s35, s34, 31
	s_lshl_b64 s[36:37], s[34:35], 18
	v_readlane_b32 s38, v252, 20
	v_readlane_b32 s39, v252, 21
	s_add_u32 s38, s38, s36
	s_addc_u32 s39, s39, s37
	s_and_b64 s[36:37], s[0:1], exec
	s_cselect_b32 s35, s39, s43
	s_cselect_b32 s36, s38, s42
	s_ashr_i32 s31, s30, 31
	s_lshl_b64 s[40:41], s[30:31], 18
	s_add_u32 s40, s29, s40
	s_addc_u32 s41, s33, s41
	s_and_b64 s[46:47], s[0:1], exec
	s_cselect_b32 s31, s41, s45
	s_cselect_b32 s37, s40, s44
	s_add_u32 s42, s42, 0x20080
	s_addc_u32 s43, s43, 0
	s_add_u32 s48, s44, 0x100
	v_mov_b32_e32 v0, 0
	s_addc_u32 s49, s45, 0
	s_mov_b32 s50, -2
	v_mov_b32_e32 v1, v0
	v_mov_b32_e32 v2, v0
	v_mov_b32_e32 v3, v0
	v_mov_b32_e32 v4, v0
	v_mov_b32_e32 v5, v0
	v_mov_b32_e32 v6, v0
	v_mov_b32_e32 v7, v0
	v_mov_b32_e32 v8, v0
	v_mov_b32_e32 v9, v0
	v_mov_b32_e32 v10, v0
	v_mov_b32_e32 v11, v0
	v_mov_b32_e32 v12, v0
	v_mov_b32_e32 v13, v0
	v_mov_b32_e32 v14, v0
	v_mov_b32_e32 v15, v0
	v_mov_b32_e32 v24, v0
	v_mov_b32_e32 v25, v0
	v_mov_b32_e32 v26, v0
	v_mov_b32_e32 v27, v0
	v_mov_b32_e32 v28, v0
	v_mov_b32_e32 v29, v0
	v_mov_b32_e32 v30, v0
	v_mov_b32_e32 v31, v0
	v_mov_b32_e32 v40, v0
	v_mov_b32_e32 v41, v0
	v_mov_b32_e32 v42, v0
	v_mov_b32_e32 v43, v0
	v_mov_b32_e32 v44, v0
	v_mov_b32_e32 v45, v0
	v_mov_b32_e32 v46, v0
	v_mov_b32_e32 v47, v0
	v_mov_b32_e32 v16, v0
	v_mov_b32_e32 v17, v0
	v_mov_b32_e32 v18, v0
	v_mov_b32_e32 v19, v0
	v_mov_b32_e32 v20, v0
	v_mov_b32_e32 v21, v0
	v_mov_b32_e32 v22, v0
	v_mov_b32_e32 v23, v0
	v_mov_b32_e32 v32, v0
	v_mov_b32_e32 v33, v0
	v_mov_b32_e32 v34, v0
	v_mov_b32_e32 v35, v0
	v_mov_b32_e32 v36, v0
	v_mov_b32_e32 v37, v0
	v_mov_b32_e32 v38, v0
	v_mov_b32_e32 v39, v0
	v_mov_b32_e32 v48, v0
	v_mov_b32_e32 v49, v0
	v_mov_b32_e32 v50, v0
	v_mov_b32_e32 v51, v0
	v_mov_b32_e32 v52, v0
	v_mov_b32_e32 v53, v0
	v_mov_b32_e32 v54, v0
	v_mov_b32_e32 v55, v0
	v_mov_b32_e32 v56, v0
	v_mov_b32_e32 v57, v0
	v_mov_b32_e32 v58, v0
	v_mov_b32_e32 v59, v0
	v_mov_b32_e32 v60, v0
	v_mov_b32_e32 v61, v0
	v_mov_b32_e32 v62, v0
	v_mov_b32_e32 v63, v0
	v_mov_b32_e32 v64, v0
	v_mov_b32_e32 v65, v0
	v_mov_b32_e32 v66, v0
	v_mov_b32_e32 v67, v0
	v_mov_b32_e32 v68, v0
	v_mov_b32_e32 v69, v0
	v_mov_b32_e32 v70, v0
	v_mov_b32_e32 v71, v0
	v_mov_b32_e32 v72, v0
	v_mov_b32_e32 v73, v0
	v_mov_b32_e32 v74, v0
	v_mov_b32_e32 v75, v0
	v_mov_b32_e32 v76, v0
	v_mov_b32_e32 v77, v0
	v_mov_b32_e32 v78, v0
	v_mov_b32_e32 v79, v0
	v_mov_b32_e32 v88, v0
	v_mov_b32_e32 v89, v0
	v_mov_b32_e32 v90, v0
	v_mov_b32_e32 v91, v0
	v_mov_b32_e32 v92, v0
	v_mov_b32_e32 v93, v0
	v_mov_b32_e32 v94, v0
	v_mov_b32_e32 v95, v0
	v_mov_b32_e32 v104, v0
	v_mov_b32_e32 v105, v0
	v_mov_b32_e32 v106, v0
	v_mov_b32_e32 v107, v0
	v_mov_b32_e32 v108, v0
	v_mov_b32_e32 v109, v0
	v_mov_b32_e32 v110, v0
	v_mov_b32_e32 v111, v0
	v_mov_b32_e32 v80, v0
	v_mov_b32_e32 v81, v0
	v_mov_b32_e32 v82, v0
	v_mov_b32_e32 v83, v0
	v_mov_b32_e32 v84, v0
	v_mov_b32_e32 v85, v0
	v_mov_b32_e32 v86, v0
	v_mov_b32_e32 v87, v0
	v_mov_b32_e32 v96, v0
	v_mov_b32_e32 v97, v0
	v_mov_b32_e32 v98, v0
	v_mov_b32_e32 v99, v0
	v_mov_b32_e32 v100, v0
	v_mov_b32_e32 v101, v0
	v_mov_b32_e32 v102, v0
	v_mov_b32_e32 v103, v0
	v_mov_b32_e32 v112, v0
	v_mov_b32_e32 v113, v0
	v_mov_b32_e32 v114, v0
	v_mov_b32_e32 v115, v0
	v_mov_b32_e32 v116, v0
	v_mov_b32_e32 v117, v0
	v_mov_b32_e32 v118, v0
	v_mov_b32_e32 v119, v0
	v_mov_b32_e32 v120, v0
	v_mov_b32_e32 v121, v0
	v_mov_b32_e32 v122, v0
	v_mov_b32_e32 v123, v0
	v_mov_b32_e32 v124, v0
	v_mov_b32_e32 v125, v0
	v_mov_b32_e32 v126, v0
	v_mov_b32_e32 v127, v0
	s_branch .LBB0_758

.LBB0_758:
	ds_read_b128 v[174:177], v155
	ds_read_b128 v[178:181], v155 offset:1024
	ds_read_b128 v[182:185], v155 offset:2048
	ds_read_b128 v[186:189], v155 offset:3072
	ds_read_b128 v[190:193], v171
	ds_read_b128 v[194:197], v171 offset:1024
	ds_read_b128 v[198:201], v171 offset:2048
	ds_read_b128 v[202:205], v171 offset:3072
	s_add_u32 s44, s42, 0xfffe0080
	s_addc_u32 s45, s43, -1
	s_cmp_eq_u32 s50, 4
	s_cselect_b32 s47, s35, s45
	s_cselect_b32 s46, s36, s44
	s_cselect_b32 s45, s31, s49
	s_cselect_b32 s44, s37, s48
	v_lshl_add_u64 v[130:131], s[42:43], 0, v[144:145]
	s_add_i32 m0, s54, 0xc000
	ds_read_b128 v[206:209], v172
	ds_read_b128 v[210:213], v172 offset:1024
	ds_read_b128 v[214:217], v172 offset:2048
	ds_read_b128 v[218:221], v172 offset:3072
	ds_read_b128 v[222:225], v172 offset:4096
	ds_read_b128 v[226:229], v172 offset:5120
	ds_read_b128 v[230:233], v172 offset:6144
	ds_read_b128 v[234:237], v172 offset:7168
	global_load_lds_dwordx4 v[130:131], off
	v_lshl_add_u64 v[130:131], s[42:43], 0, v[146:147]
	s_add_i32 m0, s54, 0xe000
	s_nop 0
	global_load_lds_dwordx4 v[130:131], off
	s_waitcnt vmcnt(8)
	s_waitcnt lgkmcnt(0)
	s_barrier
	v_mfma_f32_16x16x32_bf16 v[124:127], v[174:177], v[206:209], v[124:127]
	v_mfma_f32_16x16x32_bf16 v[120:123], v[182:185], v[206:209], v[120:123]
	v_mfma_f32_16x16x32_bf16 v[116:119], v[174:177], v[214:217], v[116:119]
	v_mfma_f32_16x16x32_bf16 v[112:115], v[182:185], v[214:217], v[112:115]
	v_mfma_f32_16x16x32_bf16 v[100:103], v[174:177], v[222:225], v[100:103]
	v_mfma_f32_16x16x32_bf16 v[96:99], v[182:185], v[222:225], v[96:99]
	v_mfma_f32_16x16x32_bf16 v[84:87], v[174:177], v[230:233], v[84:87]
	v_mfma_f32_16x16x32_bf16 v[80:83], v[182:185], v[230:233], v[80:83]
	v_mfma_f32_16x16x32_bf16 v[124:127], v[178:181], v[210:213], v[124:127]
	v_mfma_f32_16x16x32_bf16 v[120:123], v[186:189], v[210:213], v[120:123]
	v_mfma_f32_16x16x32_bf16 v[116:119], v[178:181], v[218:221], v[116:119]
	v_mfma_f32_16x16x32_bf16 v[112:115], v[186:189], v[218:221], v[112:115]
	v_mfma_f32_16x16x32_bf16 v[100:103], v[178:181], v[226:229], v[100:103]
	v_mfma_f32_16x16x32_bf16 v[96:99], v[186:189], v[226:229], v[96:99]
	v_mfma_f32_16x16x32_bf16 v[84:87], v[178:181], v[234:237], v[84:87]
	v_mfma_f32_16x16x32_bf16 v[80:83], v[186:189], v[234:237], v[80:83]
	v_mfma_f32_16x16x32_bf16 v[108:111], v[190:193], v[206:209], v[108:111]
	v_mfma_f32_16x16x32_bf16 v[104:107], v[198:201], v[206:209], v[104:107]
	v_mfma_f32_16x16x32_bf16 v[92:95], v[190:193], v[214:217], v[92:95]
	v_mfma_f32_16x16x32_bf16 v[88:91], v[198:201], v[214:217], v[88:91]
	v_mfma_f32_16x16x32_bf16 v[76:79], v[190:193], v[222:225], v[76:79]
	v_mfma_f32_16x16x32_bf16 v[72:75], v[198:201], v[222:225], v[72:75]
	v_mfma_f32_16x16x32_bf16 v[68:71], v[190:193], v[230:233], v[68:71]
	v_mfma_f32_16x16x32_bf16 v[64:67], v[198:201], v[230:233], v[64:67]
	v_mfma_f32_16x16x32_bf16 v[108:111], v[194:197], v[210:213], v[108:111]
	v_mfma_f32_16x16x32_bf16 v[104:107], v[202:205], v[210:213], v[104:107]
	v_mfma_f32_16x16x32_bf16 v[92:95], v[194:197], v[218:221], v[92:95]
	v_mfma_f32_16x16x32_bf16 v[88:91], v[202:205], v[218:221], v[88:91]
	v_mfma_f32_16x16x32_bf16 v[76:79], v[194:197], v[226:229], v[76:79]
	v_mfma_f32_16x16x32_bf16 v[72:75], v[202:205], v[226:229], v[72:75]
	v_mfma_f32_16x16x32_bf16 v[68:71], v[194:197], v[234:237], v[68:71]
	v_mfma_f32_16x16x32_bf16 v[64:67], v[202:205], v[234:237], v[64:67]
	s_barrier
	s_add_i32 s51, s63, s28
	v_lshl_add_u64 v[130:131], s[44:45], 0, v[136:137]
	s_mov_b32 m0, s51
	ds_read_b128 v[206:209], v172 offset:16384
	ds_read_b128 v[210:213], v172 offset:17408
	ds_read_b128 v[214:217], v172 offset:18432
	ds_read_b128 v[218:221], v172 offset:19456
	ds_read_b128 v[222:225], v172 offset:20480
	ds_read_b128 v[226:229], v172 offset:21504
	ds_read_b128 v[230:233], v172 offset:22528
	ds_read_b128 v[234:237], v172 offset:23552
	global_load_lds_dwordx4 v[130:131], off
	s_add_i32 m0, s51, 0x2000
	s_add_u32 s70, s44, 0x20000
	v_lshl_add_u64 v[166:167], s[44:45], 0, v[132:133]
	s_addc_u32 s71, s45, 0
	s_add_i32 s51, s64, s28
	global_load_lds_dwordx4 v[166:167], off
	v_lshl_add_u64 v[238:239], s[70:71], 0, v[136:137]
	s_mov_b32 m0, s51
	v_lshl_add_u64 v[240:241], s[46:47], 0, v[134:135]
	global_load_lds_dwordx4 v[238:239], off
	v_lshl_add_u64 v[238:239], s[70:71], 0, v[132:133]
	s_add_i32 m0, s51, 0x2000
	s_nop 0
	global_load_lds_dwordx4 v[238:239], off
	v_lshl_add_u64 v[238:239], s[46:47], 0, v[138:139]
	s_mov_b32 m0, s54
	s_nop 0
	global_load_lds_dwordx4 v[238:239], off
	s_mov_b32 m0, s55
	s_nop 0
	global_load_lds_dwordx4 v[240:241], off
	s_waitcnt vmcnt(8)
	s_waitcnt lgkmcnt(0)
	s_barrier
	v_mfma_f32_16x16x32_bf16 v[60:63], v[174:177], v[206:209], v[60:63]
	v_mfma_f32_16x16x32_bf16 v[56:59], v[182:185], v[206:209], v[56:59]
	v_mfma_f32_16x16x32_bf16 v[52:55], v[174:177], v[214:217], v[52:55]
	v_mfma_f32_16x16x32_bf16 v[48:51], v[182:185], v[214:217], v[48:51]
	v_mfma_f32_16x16x32_bf16 v[36:39], v[174:177], v[222:225], v[36:39]
	v_mfma_f32_16x16x32_bf16 v[32:35], v[182:185], v[222:225], v[32:35]
	v_mfma_f32_16x16x32_bf16 v[20:23], v[174:177], v[230:233], v[20:23]
	v_mfma_f32_16x16x32_bf16 v[16:19], v[182:185], v[230:233], v[16:19]
	v_mfma_f32_16x16x32_bf16 v[60:63], v[178:181], v[210:213], v[60:63]
	v_mfma_f32_16x16x32_bf16 v[56:59], v[186:189], v[210:213], v[56:59]
	v_mfma_f32_16x16x32_bf16 v[52:55], v[178:181], v[218:221], v[52:55]
	v_mfma_f32_16x16x32_bf16 v[48:51], v[186:189], v[218:221], v[48:51]
	v_mfma_f32_16x16x32_bf16 v[36:39], v[178:181], v[226:229], v[36:39]
	v_mfma_f32_16x16x32_bf16 v[32:35], v[186:189], v[226:229], v[32:35]
	v_mfma_f32_16x16x32_bf16 v[20:23], v[178:181], v[234:237], v[20:23]
	v_mfma_f32_16x16x32_bf16 v[16:19], v[186:189], v[234:237], v[16:19]
	v_mfma_f32_16x16x32_bf16 v[44:47], v[190:193], v[206:209], v[44:47]
	v_mfma_f32_16x16x32_bf16 v[40:43], v[198:201], v[206:209], v[40:43]
	v_mfma_f32_16x16x32_bf16 v[28:31], v[190:193], v[214:217], v[28:31]
	v_mfma_f32_16x16x32_bf16 v[24:27], v[198:201], v[214:217], v[24:27]
	v_mfma_f32_16x16x32_bf16 v[12:15], v[190:193], v[222:225], v[12:15]
	v_mfma_f32_16x16x32_bf16 v[8:11], v[198:201], v[222:225], v[8:11]
	v_mfma_f32_16x16x32_bf16 v[4:7], v[190:193], v[230:233], v[4:7]
	v_mfma_f32_16x16x32_bf16 v[0:3], v[198:201], v[230:233], v[0:3]
	v_mfma_f32_16x16x32_bf16 v[44:47], v[194:197], v[210:213], v[44:47]
	v_mfma_f32_16x16x32_bf16 v[40:43], v[202:205], v[210:213], v[40:43]
	v_mfma_f32_16x16x32_bf16 v[28:31], v[194:197], v[218:221], v[28:31]
	v_mfma_f32_16x16x32_bf16 v[24:27], v[202:205], v[218:221], v[24:27]
	v_mfma_f32_16x16x32_bf16 v[12:15], v[194:197], v[226:229], v[12:15]
	v_mfma_f32_16x16x32_bf16 v[8:11], v[202:205], v[226:229], v[8:11]
	v_mfma_f32_16x16x32_bf16 v[4:7], v[194:197], v[234:237], v[4:7]
	v_mfma_f32_16x16x32_bf16 v[0:3], v[202:205], v[234:237], v[0:3]
	s_barrier
	s_add_i32 s51, 0, 0x18000
	s_add_i32 s70, 0, 0x1c000
	v_add_u32_e32 v186, s51, v153
	v_add_u32_e32 v202, s70, v153
	ds_read_b128 v[174:177], v186
	ds_read_b128 v[178:181], v186 offset:1024
	ds_read_b128 v[182:185], v186 offset:2048
	ds_read_b128 v[186:189], v186 offset:3072
	ds_read_b128 v[190:193], v202
	ds_read_b128 v[194:197], v202 offset:1024
	ds_read_b128 v[198:201], v202 offset:2048
	ds_read_b128 v[202:205], v202 offset:3072
	s_add_u32 s46, s46, 0x20000
	s_addc_u32 s47, s47, 0
	s_mov_b32 m0, s56
	v_lshl_add_u64 v[242:243], s[46:47], 0, v[138:139]
	ds_read_b128 v[206:209], v172 offset:32768
	ds_read_b128 v[210:213], v172 offset:33792
	ds_read_b128 v[214:217], v172 offset:34816
	ds_read_b128 v[218:221], v172 offset:35840
	ds_read_b128 v[222:225], v172 offset:36864
	ds_read_b128 v[226:229], v172 offset:37888
	ds_read_b128 v[230:233], v172 offset:38912
	ds_read_b128 v[234:237], v172 offset:39936
	global_load_lds_dwordx4 v[242:243], off
	v_lshl_add_u64 v[242:243], s[46:47], 0, v[134:135]
	s_mov_b32 m0, s57
	s_nop 0
	global_load_lds_dwordx4 v[242:243], off
	s_waitcnt vmcnt(8)
	s_waitcnt lgkmcnt(0)
	s_barrier
	v_mfma_f32_16x16x32_bf16 v[124:127], v[174:177], v[206:209], v[124:127]
	v_mfma_f32_16x16x32_bf16 v[120:123], v[182:185], v[206:209], v[120:123]
	v_mfma_f32_16x16x32_bf16 v[116:119], v[174:177], v[214:217], v[116:119]
	v_mfma_f32_16x16x32_bf16 v[112:115], v[182:185], v[214:217], v[112:115]
	v_mfma_f32_16x16x32_bf16 v[100:103], v[174:177], v[222:225], v[100:103]
	v_mfma_f32_16x16x32_bf16 v[96:99], v[182:185], v[222:225], v[96:99]
	v_mfma_f32_16x16x32_bf16 v[84:87], v[174:177], v[230:233], v[84:87]
	v_mfma_f32_16x16x32_bf16 v[80:83], v[182:185], v[230:233], v[80:83]
	v_mfma_f32_16x16x32_bf16 v[124:127], v[178:181], v[210:213], v[124:127]
	v_mfma_f32_16x16x32_bf16 v[120:123], v[186:189], v[210:213], v[120:123]
	v_mfma_f32_16x16x32_bf16 v[116:119], v[178:181], v[218:221], v[116:119]
	v_mfma_f32_16x16x32_bf16 v[112:115], v[186:189], v[218:221], v[112:115]
	v_mfma_f32_16x16x32_bf16 v[100:103], v[178:181], v[226:229], v[100:103]
	v_mfma_f32_16x16x32_bf16 v[96:99], v[186:189], v[226:229], v[96:99]
	v_mfma_f32_16x16x32_bf16 v[84:87], v[178:181], v[234:237], v[84:87]
	v_mfma_f32_16x16x32_bf16 v[80:83], v[186:189], v[234:237], v[80:83]
	v_mfma_f32_16x16x32_bf16 v[108:111], v[190:193], v[206:209], v[108:111]
	v_mfma_f32_16x16x32_bf16 v[104:107], v[198:201], v[206:209], v[104:107]
	v_mfma_f32_16x16x32_bf16 v[92:95], v[190:193], v[214:217], v[92:95]
	v_mfma_f32_16x16x32_bf16 v[88:91], v[198:201], v[214:217], v[88:91]
	v_mfma_f32_16x16x32_bf16 v[76:79], v[190:193], v[222:225], v[76:79]
	v_mfma_f32_16x16x32_bf16 v[72:75], v[198:201], v[222:225], v[72:75]
	v_mfma_f32_16x16x32_bf16 v[68:71], v[190:193], v[230:233], v[68:71]
	v_mfma_f32_16x16x32_bf16 v[64:67], v[198:201], v[230:233], v[64:67]
	v_mfma_f32_16x16x32_bf16 v[108:111], v[194:197], v[210:213], v[108:111]
	v_mfma_f32_16x16x32_bf16 v[104:107], v[202:205], v[210:213], v[104:107]
	v_mfma_f32_16x16x32_bf16 v[92:95], v[194:197], v[218:221], v[92:95]
	v_mfma_f32_16x16x32_bf16 v[88:91], v[202:205], v[218:221], v[88:91]
	v_mfma_f32_16x16x32_bf16 v[76:79], v[194:197], v[226:229], v[76:79]
	v_mfma_f32_16x16x32_bf16 v[72:75], v[202:205], v[226:229], v[72:75]
	v_mfma_f32_16x16x32_bf16 v[68:71], v[194:197], v[234:237], v[68:71]
	v_mfma_f32_16x16x32_bf16 v[64:67], v[202:205], v[234:237], v[64:67]
	s_barrier
	s_add_i32 s46, s51, s28
	v_lshl_add_u64 v[130:131], v[130:131], 0, s[8:9]
	s_mov_b32 m0, s46
	ds_read_b128 v[206:209], v172 offset:49152
	ds_read_b128 v[210:213], v172 offset:50176
	ds_read_b128 v[214:217], v172 offset:51200
	ds_read_b128 v[218:221], v172 offset:52224
	ds_read_b128 v[222:225], v172 offset:53248
	ds_read_b128 v[226:229], v172 offset:54272
	ds_read_b128 v[230:233], v172 offset:55296
	ds_read_b128 v[234:237], v172 offset:56320
	global_load_lds_dwordx4 v[130:131], off
	s_add_i32 m0, s46, 0x2000
	s_add_u32 s44, s44, 0x20080
	v_lshl_add_u64 v[130:131], v[166:167], 0, s[8:9]
	s_addc_u32 s45, s45, 0
	s_add_i32 s46, s70, s28
	global_load_lds_dwordx4 v[130:131], off
	v_lshl_add_u64 v[130:131], s[44:45], 0, v[136:137]
	s_mov_b32 m0, s46
	s_nop 0
	global_load_lds_dwordx4 v[130:131], off
	v_lshl_add_u64 v[130:131], s[44:45], 0, v[132:133]
	s_add_i32 m0, s46, 0x2000
	s_nop 0
	global_load_lds_dwordx4 v[130:131], off
	v_lshl_add_u64 v[130:131], v[238:239], 0, s[8:9]
	s_mov_b32 m0, s60
	s_nop 0
	global_load_lds_dwordx4 v[130:131], off
	v_lshl_add_u64 v[130:131], v[240:241], 0, s[8:9]
	s_mov_b32 m0, s61
	s_nop 0
	global_load_lds_dwordx4 v[130:131], off
	s_waitcnt vmcnt(8)
	s_waitcnt lgkmcnt(0)
	s_barrier
	v_mfma_f32_16x16x32_bf16 v[60:63], v[174:177], v[206:209], v[60:63]
	v_mfma_f32_16x16x32_bf16 v[56:59], v[182:185], v[206:209], v[56:59]
	v_mfma_f32_16x16x32_bf16 v[52:55], v[174:177], v[214:217], v[52:55]
	v_mfma_f32_16x16x32_bf16 v[48:51], v[182:185], v[214:217], v[48:51]
	v_mfma_f32_16x16x32_bf16 v[36:39], v[174:177], v[222:225], v[36:39]
	v_mfma_f32_16x16x32_bf16 v[32:35], v[182:185], v[222:225], v[32:35]
	v_mfma_f32_16x16x32_bf16 v[20:23], v[174:177], v[230:233], v[20:23]
	v_mfma_f32_16x16x32_bf16 v[16:19], v[182:185], v[230:233], v[16:19]
	v_mfma_f32_16x16x32_bf16 v[60:63], v[178:181], v[210:213], v[60:63]
	v_mfma_f32_16x16x32_bf16 v[56:59], v[186:189], v[210:213], v[56:59]
	v_mfma_f32_16x16x32_bf16 v[52:55], v[178:181], v[218:221], v[52:55]
	v_mfma_f32_16x16x32_bf16 v[48:51], v[186:189], v[218:221], v[48:51]
	v_mfma_f32_16x16x32_bf16 v[36:39], v[178:181], v[226:229], v[36:39]
	v_mfma_f32_16x16x32_bf16 v[32:35], v[186:189], v[226:229], v[32:35]
	v_mfma_f32_16x16x32_bf16 v[20:23], v[178:181], v[234:237], v[20:23]
	v_mfma_f32_16x16x32_bf16 v[16:19], v[186:189], v[234:237], v[16:19]
	v_mfma_f32_16x16x32_bf16 v[44:47], v[190:193], v[206:209], v[44:47]
	v_mfma_f32_16x16x32_bf16 v[40:43], v[198:201], v[206:209], v[40:43]
	v_mfma_f32_16x16x32_bf16 v[28:31], v[190:193], v[214:217], v[28:31]
	v_mfma_f32_16x16x32_bf16 v[24:27], v[198:201], v[214:217], v[24:27]
	v_mfma_f32_16x16x32_bf16 v[12:15], v[190:193], v[222:225], v[12:15]
	v_mfma_f32_16x16x32_bf16 v[8:11], v[198:201], v[222:225], v[8:11]
	v_mfma_f32_16x16x32_bf16 v[4:7], v[190:193], v[230:233], v[4:7]
	v_mfma_f32_16x16x32_bf16 v[0:3], v[198:201], v[230:233], v[0:3]
	v_mfma_f32_16x16x32_bf16 v[44:47], v[194:197], v[210:213], v[44:47]
	v_mfma_f32_16x16x32_bf16 v[40:43], v[202:205], v[210:213], v[40:43]
	v_mfma_f32_16x16x32_bf16 v[28:31], v[194:197], v[218:221], v[28:31]
	v_mfma_f32_16x16x32_bf16 v[24:27], v[202:205], v[218:221], v[24:27]
	v_mfma_f32_16x16x32_bf16 v[12:15], v[194:197], v[226:229], v[12:15]
	v_mfma_f32_16x16x32_bf16 v[8:11], v[202:205], v[226:229], v[8:11]
	v_mfma_f32_16x16x32_bf16 v[4:7], v[194:197], v[234:237], v[4:7]
	v_mfma_f32_16x16x32_bf16 v[0:3], v[202:205], v[234:237], v[0:3]
	s_add_i32 s50, s50, 2
	s_add_u32 s42, s42, 0x100
	s_addc_u32 s43, s43, 0
	s_add_u32 s48, s48, 0x100
	s_addc_u32 s49, s49, 0
	s_cmp_gt_u32 s50, 5
	s_cbranch_scc0 .Lrot_758
	s_barrier
	s_and_b64 vcc, exec, s[14:15]
	s_cbranch_vccz .LBB0_761
	s_barrier

.LBB0_777:
	s_ashr_i32 s15, s14, 31
	s_lshl_b64 s[30:31], s[14:15], 18
	s_add_u32 s30, s29, s30
	s_addc_u32 s31, s33, s31
	s_and_b64 s[34:35], s[0:1], exec
	s_cselect_b32 s15, s31, s41
	s_cselect_b32 s46, s30, s40
	s_ashr_i32 s9, s8, 31
	s_lshl_b64 s[34:35], s[8:9], 18
	v_readlane_b32 s44, v252, 20
	v_readlane_b32 s45, v252, 21
	s_add_u32 s34, s44, s34
	s_addc_u32 s35, s45, s35
	s_and_b64 s[44:45], s[0:1], exec
	s_cselect_b32 s9, s35, s43
	s_cselect_b32 s47, s34, s42
	s_add_u32 s40, s40, 0x20080
	s_addc_u32 s41, s41, 0
	s_add_u32 s50, s42, 0x100
	v_mov_b32_e32 v0, 0
	s_addc_u32 s51, s43, 0
	s_mov_b32 s61, -2
	v_mov_b32_e32 v1, v0
	v_mov_b32_e32 v2, v0
	v_mov_b32_e32 v3, v0
	v_mov_b32_e32 v20, v0
	v_mov_b32_e32 v21, v0
	v_mov_b32_e32 v22, v0
	v_mov_b32_e32 v23, v0
	v_mov_b32_e32 v4, v0
	v_mov_b32_e32 v5, v0
	v_mov_b32_e32 v6, v0
	v_mov_b32_e32 v7, v0
	v_mov_b32_e32 v28, v0
	v_mov_b32_e32 v29, v0
	v_mov_b32_e32 v30, v0
	v_mov_b32_e32 v31, v0
	v_mov_b32_e32 v8, v0
	v_mov_b32_e32 v9, v0
	v_mov_b32_e32 v10, v0
	v_mov_b32_e32 v11, v0
	v_mov_b32_e32 v36, v0
	v_mov_b32_e32 v37, v0
	v_mov_b32_e32 v38, v0
	v_mov_b32_e32 v39, v0
	v_mov_b32_e32 v12, v0
	v_mov_b32_e32 v13, v0
	v_mov_b32_e32 v14, v0
	v_mov_b32_e32 v15, v0
	v_mov_b32_e32 v44, v0
	v_mov_b32_e32 v45, v0
	v_mov_b32_e32 v46, v0
	v_mov_b32_e32 v47, v0
	v_mov_b32_e32 v60, v0
	v_mov_b32_e32 v61, v0
	v_mov_b32_e32 v62, v0
	v_mov_b32_e32 v63, v0
	v_mov_b32_e32 v84, v0
	v_mov_b32_e32 v85, v0
	v_mov_b32_e32 v86, v0
	v_mov_b32_e32 v87, v0
	v_mov_b32_e32 v68, v0
	v_mov_b32_e32 v69, v0
	v_mov_b32_e32 v70, v0
	v_mov_b32_e32 v71, v0
	v_mov_b32_e32 v92, v0
	v_mov_b32_e32 v93, v0
	v_mov_b32_e32 v94, v0
	v_mov_b32_e32 v95, v0
	v_mov_b32_e32 v72, v0
	v_mov_b32_e32 v73, v0
	v_mov_b32_e32 v74, v0
	v_mov_b32_e32 v75, v0
	v_mov_b32_e32 v100, v0
	v_mov_b32_e32 v101, v0
	v_mov_b32_e32 v102, v0
	v_mov_b32_e32 v103, v0
	v_mov_b32_e32 v76, v0
	v_mov_b32_e32 v77, v0
	v_mov_b32_e32 v78, v0
	v_mov_b32_e32 v79, v0
	v_mov_b32_e32 v108, v0
	v_mov_b32_e32 v109, v0
	v_mov_b32_e32 v110, v0
	v_mov_b32_e32 v111, v0
	v_mov_b32_e32 v16, v0
	v_mov_b32_e32 v17, v0
	v_mov_b32_e32 v18, v0
	v_mov_b32_e32 v19, v0
	v_mov_b32_e32 v48, v0
	v_mov_b32_e32 v49, v0
	v_mov_b32_e32 v50, v0
	v_mov_b32_e32 v51, v0
	v_mov_b32_e32 v24, v0
	v_mov_b32_e32 v25, v0
	v_mov_b32_e32 v26, v0
	v_mov_b32_e32 v27, v0
	v_mov_b32_e32 v52, v0
	v_mov_b32_e32 v53, v0
	v_mov_b32_e32 v54, v0
	v_mov_b32_e32 v55, v0
	v_mov_b32_e32 v32, v0
	v_mov_b32_e32 v33, v0
	v_mov_b32_e32 v34, v0
	v_mov_b32_e32 v35, v0
	v_mov_b32_e32 v56, v0
	v_mov_b32_e32 v57, v0
	v_mov_b32_e32 v58, v0
	v_mov_b32_e32 v59, v0
	v_mov_b32_e32 v40, v0
	v_mov_b32_e32 v41, v0
	v_mov_b32_e32 v42, v0
	v_mov_b32_e32 v43, v0
	v_mov_b32_e32 v64, v0
	v_mov_b32_e32 v65, v0
	v_mov_b32_e32 v66, v0
	v_mov_b32_e32 v67, v0
	v_mov_b32_e32 v80, v0
	v_mov_b32_e32 v81, v0
	v_mov_b32_e32 v82, v0
	v_mov_b32_e32 v83, v0
	v_mov_b32_e32 v112, v0
	v_mov_b32_e32 v113, v0
	v_mov_b32_e32 v114, v0
	v_mov_b32_e32 v115, v0
	v_mov_b32_e32 v88, v0
	v_mov_b32_e32 v89, v0
	v_mov_b32_e32 v90, v0
	v_mov_b32_e32 v91, v0
	v_mov_b32_e32 v116, v0
	v_mov_b32_e32 v117, v0
	v_mov_b32_e32 v118, v0
	v_mov_b32_e32 v119, v0
	v_mov_b32_e32 v96, v0
	v_mov_b32_e32 v97, v0
	v_mov_b32_e32 v98, v0
	v_mov_b32_e32 v99, v0
	v_mov_b32_e32 v120, v0
	v_mov_b32_e32 v121, v0
	v_mov_b32_e32 v122, v0
	v_mov_b32_e32 v123, v0
	v_mov_b32_e32 v104, v0
	v_mov_b32_e32 v105, v0
	v_mov_b32_e32 v106, v0
	v_mov_b32_e32 v107, v0
	v_mov_b32_e32 v124, v0
	v_mov_b32_e32 v125, v0
	v_mov_b32_e32 v126, v0
	v_mov_b32_e32 v127, v0
	s_branch .LBB0_778

.LBB0_778:
	ds_read_b128 v[148:151], v144
	ds_read_b128 v[152:155], v144 offset:1024
	ds_read_b128 v[158:161], v144 offset:2048
	ds_read_b128 v[162:165], v144 offset:3072
	ds_read_b128 v[166:169], v145
	ds_read_b128 v[170:173], v145 offset:1024
	ds_read_b128 v[174:177], v145 offset:2048
	ds_read_b128 v[178:181], v145 offset:3072
	s_add_u32 s42, s40, 0xfffe0080
	s_addc_u32 s43, s41, -1
	s_cmp_eq_u32 s61, 4
	s_cselect_b32 s45, s15, s43
	s_cselect_b32 s44, s46, s42
	s_cselect_b32 s43, s9, s51
	s_cselect_b32 s42, s47, s50
	v_lshl_add_u64 v[214:215], s[40:41], 0, v[134:135]
	s_add_i32 m0, s54, 0xc000
	ds_read_b128 v[182:185], v146
	ds_read_b128 v[186:189], v146 offset:1024
	ds_read_b128 v[190:193], v146 offset:2048
	ds_read_b128 v[194:197], v146 offset:3072
	ds_read_b128 v[198:201], v146 offset:4096
	ds_read_b128 v[202:205], v146 offset:5120
	ds_read_b128 v[206:209], v146 offset:6144
	ds_read_b128 v[210:213], v146 offset:7168
	global_load_lds_dwordx4 v[214:215], off
	v_lshl_add_u64 v[214:215], s[40:41], 0, v[136:137]
	s_add_i32 m0, s54, 0xe000
	s_nop 0
	global_load_lds_dwordx4 v[214:215], off
	s_waitcnt vmcnt(8)
	s_waitcnt lgkmcnt(0)
	s_barrier
	v_mfma_f32_16x16x32_bf16 v[124:127], v[148:151], v[182:185], v[124:127]
	v_mfma_f32_16x16x32_bf16 v[104:107], v[158:161], v[182:185], v[104:107]
	v_mfma_f32_16x16x32_bf16 v[120:123], v[148:151], v[190:193], v[120:123]
	v_mfma_f32_16x16x32_bf16 v[96:99], v[158:161], v[190:193], v[96:99]
	v_mfma_f32_16x16x32_bf16 v[116:119], v[148:151], v[198:201], v[116:119]
	v_mfma_f32_16x16x32_bf16 v[88:91], v[158:161], v[198:201], v[88:91]
	v_mfma_f32_16x16x32_bf16 v[112:115], v[148:151], v[206:209], v[112:115]
	v_mfma_f32_16x16x32_bf16 v[80:83], v[158:161], v[206:209], v[80:83]
	v_mfma_f32_16x16x32_bf16 v[124:127], v[152:155], v[186:189], v[124:127]
	v_mfma_f32_16x16x32_bf16 v[104:107], v[162:165], v[186:189], v[104:107]
	v_mfma_f32_16x16x32_bf16 v[120:123], v[152:155], v[194:197], v[120:123]
	v_mfma_f32_16x16x32_bf16 v[96:99], v[162:165], v[194:197], v[96:99]
	v_mfma_f32_16x16x32_bf16 v[116:119], v[152:155], v[202:205], v[116:119]
	v_mfma_f32_16x16x32_bf16 v[88:91], v[162:165], v[202:205], v[88:91]
	v_mfma_f32_16x16x32_bf16 v[112:115], v[152:155], v[210:213], v[112:115]
	v_mfma_f32_16x16x32_bf16 v[80:83], v[162:165], v[210:213], v[80:83]
	v_mfma_f32_16x16x32_bf16 v[64:67], v[166:169], v[182:185], v[64:67]
	v_mfma_f32_16x16x32_bf16 v[40:43], v[174:177], v[182:185], v[40:43]
	v_mfma_f32_16x16x32_bf16 v[56:59], v[166:169], v[190:193], v[56:59]
	v_mfma_f32_16x16x32_bf16 v[32:35], v[174:177], v[190:193], v[32:35]
	v_mfma_f32_16x16x32_bf16 v[52:55], v[166:169], v[198:201], v[52:55]
	v_mfma_f32_16x16x32_bf16 v[24:27], v[174:177], v[198:201], v[24:27]
	v_mfma_f32_16x16x32_bf16 v[48:51], v[166:169], v[206:209], v[48:51]
	v_mfma_f32_16x16x32_bf16 v[16:19], v[174:177], v[206:209], v[16:19]
	v_mfma_f32_16x16x32_bf16 v[64:67], v[170:173], v[186:189], v[64:67]
	v_mfma_f32_16x16x32_bf16 v[40:43], v[178:181], v[186:189], v[40:43]
	v_mfma_f32_16x16x32_bf16 v[56:59], v[170:173], v[194:197], v[56:59]
	v_mfma_f32_16x16x32_bf16 v[32:35], v[178:181], v[194:197], v[32:35]
	v_mfma_f32_16x16x32_bf16 v[52:55], v[170:173], v[202:205], v[52:55]
	v_mfma_f32_16x16x32_bf16 v[24:27], v[178:181], v[202:205], v[24:27]
	v_mfma_f32_16x16x32_bf16 v[48:51], v[170:173], v[210:213], v[48:51]
	v_mfma_f32_16x16x32_bf16 v[16:19], v[178:181], v[210:213], v[16:19]
	s_barrier
	s_add_i32 s62, s48, s28
	v_lshl_add_u64 v[214:215], s[42:43], 0, v[130:131]
	s_mov_b32 m0, s62
	ds_read_b128 v[182:185], v146 offset:16384
	ds_read_b128 v[186:189], v146 offset:17408
	ds_read_b128 v[190:193], v146 offset:18432
	ds_read_b128 v[194:197], v146 offset:19456
	ds_read_b128 v[198:201], v146 offset:20480
	ds_read_b128 v[202:205], v146 offset:21504
	ds_read_b128 v[206:209], v146 offset:22528
	ds_read_b128 v[210:213], v146 offset:23552
	global_load_lds_dwordx4 v[214:215], off
	s_add_i32 m0, s62, 0x2000
	s_add_u32 s62, s42, 0x20000
	v_lshl_add_u64 v[216:217], s[42:43], 0, v[128:129]
	s_addc_u32 s63, s43, 0
	s_add_i32 s64, s49, s28
	global_load_lds_dwordx4 v[216:217], off
	v_lshl_add_u64 v[218:219], s[62:63], 0, v[130:131]
	s_mov_b32 m0, s64
	v_lshl_add_u64 v[220:221], s[44:45], 0, v[128:129]
	global_load_lds_dwordx4 v[218:219], off
	v_lshl_add_u64 v[218:219], s[62:63], 0, v[128:129]
	s_add_i32 m0, s64, 0x2000
	s_nop 0
	global_load_lds_dwordx4 v[218:219], off
	v_lshl_add_u64 v[218:219], s[44:45], 0, v[130:131]
	s_mov_b32 m0, s54
	s_nop 0
	global_load_lds_dwordx4 v[218:219], off
	s_mov_b32 m0, s55
	s_nop 0
	global_load_lds_dwordx4 v[220:221], off
	s_waitcnt vmcnt(8)
	s_waitcnt lgkmcnt(0)
	s_barrier
	v_mfma_f32_16x16x32_bf16 v[108:111], v[148:151], v[182:185], v[108:111]
	v_mfma_f32_16x16x32_bf16 v[76:79], v[158:161], v[182:185], v[76:79]
	v_mfma_f32_16x16x32_bf16 v[100:103], v[148:151], v[190:193], v[100:103]
	v_mfma_f32_16x16x32_bf16 v[72:75], v[158:161], v[190:193], v[72:75]
	v_mfma_f32_16x16x32_bf16 v[92:95], v[148:151], v[198:201], v[92:95]
	v_mfma_f32_16x16x32_bf16 v[68:71], v[158:161], v[198:201], v[68:71]
	v_mfma_f32_16x16x32_bf16 v[84:87], v[148:151], v[206:209], v[84:87]
	v_mfma_f32_16x16x32_bf16 v[60:63], v[158:161], v[206:209], v[60:63]
	v_mfma_f32_16x16x32_bf16 v[108:111], v[152:155], v[186:189], v[108:111]
	v_mfma_f32_16x16x32_bf16 v[76:79], v[162:165], v[186:189], v[76:79]
	v_mfma_f32_16x16x32_bf16 v[100:103], v[152:155], v[194:197], v[100:103]
	v_mfma_f32_16x16x32_bf16 v[72:75], v[162:165], v[194:197], v[72:75]
	v_mfma_f32_16x16x32_bf16 v[92:95], v[152:155], v[202:205], v[92:95]
	v_mfma_f32_16x16x32_bf16 v[68:71], v[162:165], v[202:205], v[68:71]
	v_mfma_f32_16x16x32_bf16 v[84:87], v[152:155], v[210:213], v[84:87]
	v_mfma_f32_16x16x32_bf16 v[60:63], v[162:165], v[210:213], v[60:63]
	v_mfma_f32_16x16x32_bf16 v[44:47], v[166:169], v[182:185], v[44:47]
	v_mfma_f32_16x16x32_bf16 v[12:15], v[174:177], v[182:185], v[12:15]
	v_mfma_f32_16x16x32_bf16 v[36:39], v[166:169], v[190:193], v[36:39]
	v_mfma_f32_16x16x32_bf16 v[8:11], v[174:177], v[190:193], v[8:11]
	v_mfma_f32_16x16x32_bf16 v[28:31], v[166:169], v[198:201], v[28:31]
	v_mfma_f32_16x16x32_bf16 v[4:7], v[174:177], v[198:201], v[4:7]
	v_mfma_f32_16x16x32_bf16 v[20:23], v[166:169], v[206:209], v[20:23]
	v_mfma_f32_16x16x32_bf16 v[0:3], v[174:177], v[206:209], v[0:3]
	v_mfma_f32_16x16x32_bf16 v[44:47], v[170:173], v[186:189], v[44:47]
	v_mfma_f32_16x16x32_bf16 v[12:15], v[178:181], v[186:189], v[12:15]
	v_mfma_f32_16x16x32_bf16 v[36:39], v[170:173], v[194:197], v[36:39]
	v_mfma_f32_16x16x32_bf16 v[8:11], v[178:181], v[194:197], v[8:11]
	v_mfma_f32_16x16x32_bf16 v[28:31], v[170:173], v[202:205], v[28:31]
	v_mfma_f32_16x16x32_bf16 v[4:7], v[178:181], v[202:205], v[4:7]
	v_mfma_f32_16x16x32_bf16 v[20:23], v[170:173], v[210:213], v[20:23]
	v_mfma_f32_16x16x32_bf16 v[0:3], v[178:181], v[210:213], v[0:3]
	s_barrier
	s_add_i32 s62, 0, 0x18000
	v_add_u32_e32 v147, s62, v143
	s_add_i32 s63, 0, 0x1c000
	ds_read_b128 v[148:151], v147
	ds_read_b128 v[152:155], v147 offset:1024
	ds_read_b128 v[158:161], v147 offset:2048
	ds_read_b128 v[162:165], v147 offset:3072
	v_add_u32_e32 v147, s63, v143
	ds_read_b128 v[166:169], v147
	ds_read_b128 v[170:173], v147 offset:1024
	ds_read_b128 v[174:177], v147 offset:2048
	ds_read_b128 v[178:181], v147 offset:3072
	s_add_u32 s44, s44, 0x20000
	s_addc_u32 s45, s45, 0
	s_mov_b32 m0, s56
	v_lshl_add_u64 v[222:223], s[44:45], 0, v[130:131]
	ds_read_b128 v[182:185], v146 offset:32768
	ds_read_b128 v[186:189], v146 offset:33792
	ds_read_b128 v[190:193], v146 offset:34816
	ds_read_b128 v[194:197], v146 offset:35840
	ds_read_b128 v[198:201], v146 offset:36864
	ds_read_b128 v[202:205], v146 offset:37888
	ds_read_b128 v[206:209], v146 offset:38912
	ds_read_b128 v[210:213], v146 offset:39936
	global_load_lds_dwordx4 v[222:223], off
	v_lshl_add_u64 v[222:223], s[44:45], 0, v[128:129]
	s_mov_b32 m0, s57
	s_nop 0
	global_load_lds_dwordx4 v[222:223], off
	s_waitcnt vmcnt(8)
	s_waitcnt lgkmcnt(0)
	s_barrier
	v_mfma_f32_16x16x32_bf16 v[124:127], v[148:151], v[182:185], v[124:127]
	v_mfma_f32_16x16x32_bf16 v[104:107], v[158:161], v[182:185], v[104:107]
	v_mfma_f32_16x16x32_bf16 v[120:123], v[148:151], v[190:193], v[120:123]
	v_mfma_f32_16x16x32_bf16 v[96:99], v[158:161], v[190:193], v[96:99]
	v_mfma_f32_16x16x32_bf16 v[116:119], v[148:151], v[198:201], v[116:119]
	v_mfma_f32_16x16x32_bf16 v[88:91], v[158:161], v[198:201], v[88:91]
	v_mfma_f32_16x16x32_bf16 v[112:115], v[148:151], v[206:209], v[112:115]
	v_mfma_f32_16x16x32_bf16 v[80:83], v[158:161], v[206:209], v[80:83]
	v_mfma_f32_16x16x32_bf16 v[124:127], v[152:155], v[186:189], v[124:127]
	v_mfma_f32_16x16x32_bf16 v[104:107], v[162:165], v[186:189], v[104:107]
	v_mfma_f32_16x16x32_bf16 v[120:123], v[152:155], v[194:197], v[120:123]
	v_mfma_f32_16x16x32_bf16 v[96:99], v[162:165], v[194:197], v[96:99]
	v_mfma_f32_16x16x32_bf16 v[116:119], v[152:155], v[202:205], v[116:119]
	v_mfma_f32_16x16x32_bf16 v[88:91], v[162:165], v[202:205], v[88:91]
	v_mfma_f32_16x16x32_bf16 v[112:115], v[152:155], v[210:213], v[112:115]
	v_mfma_f32_16x16x32_bf16 v[80:83], v[162:165], v[210:213], v[80:83]
	v_mfma_f32_16x16x32_bf16 v[64:67], v[166:169], v[182:185], v[64:67]
	v_mfma_f32_16x16x32_bf16 v[40:43], v[174:177], v[182:185], v[40:43]
	v_mfma_f32_16x16x32_bf16 v[56:59], v[166:169], v[190:193], v[56:59]
	v_mfma_f32_16x16x32_bf16 v[32:35], v[174:177], v[190:193], v[32:35]
	v_mfma_f32_16x16x32_bf16 v[52:55], v[166:169], v[198:201], v[52:55]
	v_mfma_f32_16x16x32_bf16 v[24:27], v[174:177], v[198:201], v[24:27]
	v_mfma_f32_16x16x32_bf16 v[48:51], v[166:169], v[206:209], v[48:51]
	v_mfma_f32_16x16x32_bf16 v[16:19], v[174:177], v[206:209], v[16:19]
	v_mfma_f32_16x16x32_bf16 v[64:67], v[170:173], v[186:189], v[64:67]
	v_mfma_f32_16x16x32_bf16 v[40:43], v[178:181], v[186:189], v[40:43]
	v_mfma_f32_16x16x32_bf16 v[56:59], v[170:173], v[194:197], v[56:59]
	v_mfma_f32_16x16x32_bf16 v[32:35], v[178:181], v[194:197], v[32:35]
	v_mfma_f32_16x16x32_bf16 v[52:55], v[170:173], v[202:205], v[52:55]
	v_mfma_f32_16x16x32_bf16 v[24:27], v[178:181], v[202:205], v[24:27]
	v_mfma_f32_16x16x32_bf16 v[48:51], v[170:173], v[210:213], v[48:51]
	v_mfma_f32_16x16x32_bf16 v[16:19], v[178:181], v[210:213], v[16:19]
	s_barrier
	s_add_i32 s44, s62, s28
	v_lshl_add_u64 v[214:215], v[214:215], 0, s[4:5]
	s_mov_b32 m0, s44
	ds_read_b128 v[182:185], v146 offset:49152
	ds_read_b128 v[186:189], v146 offset:50176
	ds_read_b128 v[190:193], v146 offset:51200
	ds_read_b128 v[194:197], v146 offset:52224
	ds_read_b128 v[198:201], v146 offset:53248
	ds_read_b128 v[202:205], v146 offset:54272
	ds_read_b128 v[206:209], v146 offset:55296
	ds_read_b128 v[210:213], v146 offset:56320
	global_load_lds_dwordx4 v[214:215], off
	s_add_i32 m0, s44, 0x2000
	s_add_u32 s42, s42, 0x20080
	v_lshl_add_u64 v[214:215], v[216:217], 0, s[4:5]
	s_addc_u32 s43, s43, 0
	s_add_i32 s44, s63, s28
	global_load_lds_dwordx4 v[214:215], off
	v_lshl_add_u64 v[214:215], s[42:43], 0, v[130:131]
	s_mov_b32 m0, s44
	s_nop 0
	global_load_lds_dwordx4 v[214:215], off
	v_lshl_add_u64 v[214:215], s[42:43], 0, v[128:129]
	s_add_i32 m0, s44, 0x2000
	s_nop 0
	global_load_lds_dwordx4 v[214:215], off
	v_lshl_add_u64 v[214:215], v[218:219], 0, s[4:5]
	s_mov_b32 m0, s60
	s_nop 0
	global_load_lds_dwordx4 v[214:215], off
	v_lshl_add_u64 v[214:215], v[220:221], 0, s[4:5]
	s_mov_b32 m0, s36
	s_nop 0
	global_load_lds_dwordx4 v[214:215], off
	s_waitcnt vmcnt(8)
	s_waitcnt lgkmcnt(0)
	s_barrier
	v_mfma_f32_16x16x32_bf16 v[108:111], v[148:151], v[182:185], v[108:111]
	v_mfma_f32_16x16x32_bf16 v[76:79], v[158:161], v[182:185], v[76:79]
	v_mfma_f32_16x16x32_bf16 v[100:103], v[148:151], v[190:193], v[100:103]
	v_mfma_f32_16x16x32_bf16 v[72:75], v[158:161], v[190:193], v[72:75]
	v_mfma_f32_16x16x32_bf16 v[92:95], v[148:151], v[198:201], v[92:95]
	v_mfma_f32_16x16x32_bf16 v[68:71], v[158:161], v[198:201], v[68:71]
	v_mfma_f32_16x16x32_bf16 v[84:87], v[148:151], v[206:209], v[84:87]
	v_mfma_f32_16x16x32_bf16 v[60:63], v[158:161], v[206:209], v[60:63]
	v_mfma_f32_16x16x32_bf16 v[108:111], v[152:155], v[186:189], v[108:111]
	v_mfma_f32_16x16x32_bf16 v[76:79], v[162:165], v[186:189], v[76:79]
	v_mfma_f32_16x16x32_bf16 v[100:103], v[152:155], v[194:197], v[100:103]
	v_mfma_f32_16x16x32_bf16 v[72:75], v[162:165], v[194:197], v[72:75]
	v_mfma_f32_16x16x32_bf16 v[92:95], v[152:155], v[202:205], v[92:95]
	v_mfma_f32_16x16x32_bf16 v[68:71], v[162:165], v[202:205], v[68:71]
	v_mfma_f32_16x16x32_bf16 v[84:87], v[152:155], v[210:213], v[84:87]
	v_mfma_f32_16x16x32_bf16 v[60:63], v[162:165], v[210:213], v[60:63]
	v_mfma_f32_16x16x32_bf16 v[44:47], v[166:169], v[182:185], v[44:47]
	v_mfma_f32_16x16x32_bf16 v[12:15], v[174:177], v[182:185], v[12:15]
	v_mfma_f32_16x16x32_bf16 v[36:39], v[166:169], v[190:193], v[36:39]
	v_mfma_f32_16x16x32_bf16 v[8:11], v[174:177], v[190:193], v[8:11]
	v_mfma_f32_16x16x32_bf16 v[28:31], v[166:169], v[198:201], v[28:31]
	v_mfma_f32_16x16x32_bf16 v[4:7], v[174:177], v[198:201], v[4:7]
	v_mfma_f32_16x16x32_bf16 v[20:23], v[166:169], v[206:209], v[20:23]
	v_mfma_f32_16x16x32_bf16 v[0:3], v[174:177], v[206:209], v[0:3]
	v_mfma_f32_16x16x32_bf16 v[44:47], v[170:173], v[186:189], v[44:47]
	v_mfma_f32_16x16x32_bf16 v[12:15], v[178:181], v[186:189], v[12:15]
	v_mfma_f32_16x16x32_bf16 v[36:39], v[170:173], v[194:197], v[36:39]
	v_mfma_f32_16x16x32_bf16 v[8:11], v[178:181], v[194:197], v[8:11]
	v_mfma_f32_16x16x32_bf16 v[28:31], v[170:173], v[202:205], v[28:31]
	v_mfma_f32_16x16x32_bf16 v[4:7], v[178:181], v[202:205], v[4:7]
	v_mfma_f32_16x16x32_bf16 v[20:23], v[170:173], v[210:213], v[20:23]
	v_mfma_f32_16x16x32_bf16 v[0:3], v[178:181], v[210:213], v[0:3]
	s_add_i32 s61, s61, 2
	s_add_u32 s40, s40, 0x100
	s_addc_u32 s41, s41, 0
	s_add_u32 s50, s50, 0x100
	s_addc_u32 s51, s51, 0
	s_cmp_gt_u32 s61, 5
	s_cbranch_scc0 .Lrot_778
	s_barrier
	s_and_b64 vcc, exec, s[6:7]
	s_cbranch_vccz .LBB0_781
	s_barrier

.LBB0_1140:
	s_add_i32 s35, s48, -2
	s_add_u32 s52, s52, 0x100080
	s_addc_u32 s53, s53, 0
	s_add_u32 s37, s54, 0x100
	v_mov_b32_e32 v0, 0
	s_addc_u32 s39, s55, 0
	s_mov_b32 s45, 0
	v_mov_b32_e32 v1, v0
	v_mov_b32_e32 v2, v0
	v_mov_b32_e32 v3, v0
	v_mov_b32_e32 v4, v0
	v_mov_b32_e32 v5, v0
	v_mov_b32_e32 v6, v0
	v_mov_b32_e32 v7, v0
	v_mov_b32_e32 v16, v0
	v_mov_b32_e32 v17, v0
	v_mov_b32_e32 v18, v0
	v_mov_b32_e32 v19, v0
	v_mov_b32_e32 v20, v0
	v_mov_b32_e32 v21, v0
	v_mov_b32_e32 v22, v0
	v_mov_b32_e32 v23, v0
	v_mov_b32_e32 v32, v0
	v_mov_b32_e32 v33, v0
	v_mov_b32_e32 v34, v0
	v_mov_b32_e32 v35, v0
	v_mov_b32_e32 v36, v0
	v_mov_b32_e32 v37, v0
	v_mov_b32_e32 v38, v0
	v_mov_b32_e32 v39, v0
	v_mov_b32_e32 v48, v0
	v_mov_b32_e32 v49, v0
	v_mov_b32_e32 v50, v0
	v_mov_b32_e32 v51, v0
	v_mov_b32_e32 v52, v0
	v_mov_b32_e32 v53, v0
	v_mov_b32_e32 v54, v0
	v_mov_b32_e32 v55, v0
	v_mov_b32_e32 v8, v0
	v_mov_b32_e32 v9, v0
	v_mov_b32_e32 v10, v0
	v_mov_b32_e32 v11, v0
	v_mov_b32_e32 v12, v0
	v_mov_b32_e32 v13, v0
	v_mov_b32_e32 v14, v0
	v_mov_b32_e32 v15, v0
	v_mov_b32_e32 v24, v0
	v_mov_b32_e32 v25, v0
	v_mov_b32_e32 v26, v0
	v_mov_b32_e32 v27, v0
	v_mov_b32_e32 v28, v0
	v_mov_b32_e32 v29, v0
	v_mov_b32_e32 v30, v0
	v_mov_b32_e32 v31, v0
	v_mov_b32_e32 v40, v0
	v_mov_b32_e32 v41, v0
	v_mov_b32_e32 v42, v0
	v_mov_b32_e32 v43, v0
	v_mov_b32_e32 v44, v0
	v_mov_b32_e32 v45, v0
	v_mov_b32_e32 v46, v0
	v_mov_b32_e32 v47, v0
	v_mov_b32_e32 v56, v0
	v_mov_b32_e32 v57, v0
	v_mov_b32_e32 v58, v0
	v_mov_b32_e32 v59, v0
	v_mov_b32_e32 v60, v0
	v_mov_b32_e32 v61, v0
	v_mov_b32_e32 v62, v0
	v_mov_b32_e32 v63, v0
	v_mov_b32_e32 v64, v0
	v_mov_b32_e32 v65, v0
	v_mov_b32_e32 v66, v0
	v_mov_b32_e32 v67, v0
	v_mov_b32_e32 v68, v0
	v_mov_b32_e32 v69, v0
	v_mov_b32_e32 v70, v0
	v_mov_b32_e32 v71, v0
	v_mov_b32_e32 v80, v0
	v_mov_b32_e32 v81, v0
	v_mov_b32_e32 v82, v0
	v_mov_b32_e32 v83, v0
	v_mov_b32_e32 v84, v0
	v_mov_b32_e32 v85, v0
	v_mov_b32_e32 v86, v0
	v_mov_b32_e32 v87, v0
	v_mov_b32_e32 v96, v0
	v_mov_b32_e32 v97, v0
	v_mov_b32_e32 v98, v0
	v_mov_b32_e32 v99, v0
	v_mov_b32_e32 v100, v0
	v_mov_b32_e32 v101, v0
	v_mov_b32_e32 v102, v0
	v_mov_b32_e32 v103, v0
	v_mov_b32_e32 v112, v0
	v_mov_b32_e32 v113, v0
	v_mov_b32_e32 v114, v0
	v_mov_b32_e32 v115, v0
	v_mov_b32_e32 v116, v0
	v_mov_b32_e32 v117, v0
	v_mov_b32_e32 v118, v0
	v_mov_b32_e32 v119, v0
	v_mov_b32_e32 v72, v0
	v_mov_b32_e32 v73, v0
	v_mov_b32_e32 v74, v0
	v_mov_b32_e32 v75, v0
	v_mov_b32_e32 v76, v0
	v_mov_b32_e32 v77, v0
	v_mov_b32_e32 v78, v0
	v_mov_b32_e32 v79, v0
	v_mov_b32_e32 v88, v0
	v_mov_b32_e32 v89, v0
	v_mov_b32_e32 v90, v0
	v_mov_b32_e32 v91, v0
	v_mov_b32_e32 v92, v0
	v_mov_b32_e32 v93, v0
	v_mov_b32_e32 v94, v0
	v_mov_b32_e32 v95, v0
	v_mov_b32_e32 v104, v0
	v_mov_b32_e32 v105, v0
	v_mov_b32_e32 v106, v0
	v_mov_b32_e32 v107, v0
	v_mov_b32_e32 v108, v0
	v_mov_b32_e32 v109, v0
	v_mov_b32_e32 v110, v0
	v_mov_b32_e32 v111, v0
	v_mov_b32_e32 v120, v0
	v_mov_b32_e32 v121, v0
	v_mov_b32_e32 v122, v0
	v_mov_b32_e32 v123, v0
	v_mov_b32_e32 v124, v0
	v_mov_b32_e32 v125, v0
	v_mov_b32_e32 v126, v0
	v_mov_b32_e32 v127, v0
	s_branch .LBB0_1141

.LBB0_1141:
	ds_read_b128 v[128:131], v177
	ds_read_b128 v[132:135], v177 offset:1024
	ds_read_b128 v[136:139], v177 offset:2048
	ds_read_b128 v[140:143], v177 offset:3072
	ds_read_b128 v[144:147], v178
	ds_read_b128 v[162:165], v178 offset:1024
	ds_read_b128 v[166:169], v178 offset:2048
	ds_read_b128 v[170:173], v178 offset:3072
	s_add_i32 s49, s45, 2
	s_add_u32 s50, s52, 0xfff00080
	s_addc_u32 s51, s53, -1
	s_cmp_eq_u32 s35, s45
	s_cselect_b32 s57, s41, s51
	s_cselect_b32 s56, s40, s50
	s_cselect_b32 s55, s43, s39
	s_cselect_b32 s54, s42, s37
	v_lshl_add_u64 v[214:215], s[52:53], 0, v[156:157]
	s_add_i32 m0, s47, 0xc000
	ds_read_b128 v[180:183], v179
	ds_read_b128 v[184:187], v179 offset:1024
	ds_read_b128 v[188:191], v179 offset:2048
	ds_read_b128 v[192:195], v179 offset:3072
	ds_read_b128 v[196:199], v179 offset:4096
	ds_read_b128 v[202:205], v179 offset:5120
	ds_read_b128 v[206:209], v179 offset:6144
	ds_read_b128 v[210:213], v179 offset:7168
	global_load_lds_dwordx4 v[214:215], off
	v_lshl_add_u64 v[214:215], s[52:53], 0, v[158:159]
	s_add_i32 m0, s47, 0xe000
	s_nop 0
	global_load_lds_dwordx4 v[214:215], off
	s_waitcnt vmcnt(8)
	s_waitcnt lgkmcnt(0)
	s_barrier
	v_mfma_f32_16x16x32_bf16 v[124:127], v[128:131], v[180:183], v[124:127]
	v_mfma_f32_16x16x32_bf16 v[120:123], v[136:139], v[180:183], v[120:123]
	v_mfma_f32_16x16x32_bf16 v[108:111], v[128:131], v[188:191], v[108:111]
	v_mfma_f32_16x16x32_bf16 v[104:107], v[136:139], v[188:191], v[104:107]
	v_mfma_f32_16x16x32_bf16 v[92:95], v[128:131], v[196:199], v[92:95]
	v_mfma_f32_16x16x32_bf16 v[88:91], v[136:139], v[196:199], v[88:91]
	v_mfma_f32_16x16x32_bf16 v[76:79], v[128:131], v[206:209], v[76:79]
	v_mfma_f32_16x16x32_bf16 v[72:75], v[136:139], v[206:209], v[72:75]
	v_mfma_f32_16x16x32_bf16 v[124:127], v[132:135], v[184:187], v[124:127]
	v_mfma_f32_16x16x32_bf16 v[120:123], v[140:143], v[184:187], v[120:123]
	v_mfma_f32_16x16x32_bf16 v[108:111], v[132:135], v[192:195], v[108:111]
	v_mfma_f32_16x16x32_bf16 v[104:107], v[140:143], v[192:195], v[104:107]
	v_mfma_f32_16x16x32_bf16 v[92:95], v[132:135], v[202:205], v[92:95]
	v_mfma_f32_16x16x32_bf16 v[88:91], v[140:143], v[202:205], v[88:91]
	v_mfma_f32_16x16x32_bf16 v[76:79], v[132:135], v[210:213], v[76:79]
	v_mfma_f32_16x16x32_bf16 v[72:75], v[140:143], v[210:213], v[72:75]
	v_mfma_f32_16x16x32_bf16 v[116:119], v[144:147], v[180:183], v[116:119]
	v_mfma_f32_16x16x32_bf16 v[112:115], v[166:169], v[180:183], v[112:115]
	v_mfma_f32_16x16x32_bf16 v[100:103], v[144:147], v[188:191], v[100:103]
	v_mfma_f32_16x16x32_bf16 v[96:99], v[166:169], v[188:191], v[96:99]
	v_mfma_f32_16x16x32_bf16 v[84:87], v[144:147], v[196:199], v[84:87]
	v_mfma_f32_16x16x32_bf16 v[80:83], v[166:169], v[196:199], v[80:83]
	v_mfma_f32_16x16x32_bf16 v[68:71], v[144:147], v[206:209], v[68:71]
	v_mfma_f32_16x16x32_bf16 v[64:67], v[166:169], v[206:209], v[64:67]
	v_mfma_f32_16x16x32_bf16 v[116:119], v[162:165], v[184:187], v[116:119]
	v_mfma_f32_16x16x32_bf16 v[112:115], v[170:173], v[184:187], v[112:115]
	v_mfma_f32_16x16x32_bf16 v[100:103], v[162:165], v[192:195], v[100:103]
	v_mfma_f32_16x16x32_bf16 v[96:99], v[170:173], v[192:195], v[96:99]
	v_mfma_f32_16x16x32_bf16 v[84:87], v[162:165], v[202:205], v[84:87]
	v_mfma_f32_16x16x32_bf16 v[80:83], v[170:173], v[202:205], v[80:83]
	v_mfma_f32_16x16x32_bf16 v[68:71], v[162:165], v[210:213], v[68:71]
	v_mfma_f32_16x16x32_bf16 v[64:67], v[170:173], v[210:213], v[64:67]
	s_barrier
	s_add_i32 s45, s67, s33
	v_lshl_add_u64 v[214:215], s[54:55], 0, v[150:151]
	s_mov_b32 m0, s45
	ds_read_b128 v[180:183], v179 offset:16384
	ds_read_b128 v[184:187], v179 offset:17408
	ds_read_b128 v[188:191], v179 offset:18432
	ds_read_b128 v[192:195], v179 offset:19456
	ds_read_b128 v[196:199], v179 offset:20480
	ds_read_b128 v[202:205], v179 offset:21504
	ds_read_b128 v[206:209], v179 offset:22528
	ds_read_b128 v[210:213], v179 offset:23552
	global_load_lds_dwordx4 v[214:215], off
	s_add_i32 m0, s45, 0x2000
	s_add_u32 s50, s54, 0x100000
	v_lshl_add_u64 v[216:217], s[54:55], 0, v[154:155]
	s_addc_u32 s51, s55, 0
	s_add_i32 s45, s68, s33
	global_load_lds_dwordx4 v[216:217], off
	v_lshl_add_u64 v[218:219], s[50:51], 0, v[150:151]
	s_mov_b32 m0, s45
	v_lshl_add_u64 v[220:221], s[56:57], 0, v[152:153]
	global_load_lds_dwordx4 v[218:219], off
	v_lshl_add_u64 v[218:219], s[50:51], 0, v[154:155]
	s_add_i32 m0, s45, 0x2000
	s_nop 0
	global_load_lds_dwordx4 v[218:219], off
	v_lshl_add_u64 v[218:219], s[56:57], 0, v[148:149]
	s_mov_b32 m0, s47
	s_nop 0
	global_load_lds_dwordx4 v[218:219], off
	s_mov_b32 m0, s60
	s_nop 0
	global_load_lds_dwordx4 v[220:221], off
	s_waitcnt vmcnt(8)
	s_waitcnt lgkmcnt(0)
	s_barrier
	v_mfma_f32_16x16x32_bf16 v[60:63], v[128:131], v[180:183], v[60:63]
	v_mfma_f32_16x16x32_bf16 v[56:59], v[136:139], v[180:183], v[56:59]
	v_mfma_f32_16x16x32_bf16 v[44:47], v[128:131], v[188:191], v[44:47]
	v_mfma_f32_16x16x32_bf16 v[40:43], v[136:139], v[188:191], v[40:43]
	v_mfma_f32_16x16x32_bf16 v[28:31], v[128:131], v[196:199], v[28:31]
	v_mfma_f32_16x16x32_bf16 v[24:27], v[136:139], v[196:199], v[24:27]
	v_mfma_f32_16x16x32_bf16 v[12:15], v[128:131], v[206:209], v[12:15]
	v_mfma_f32_16x16x32_bf16 v[8:11], v[136:139], v[206:209], v[8:11]
	v_mfma_f32_16x16x32_bf16 v[60:63], v[132:135], v[184:187], v[60:63]
	v_mfma_f32_16x16x32_bf16 v[56:59], v[140:143], v[184:187], v[56:59]
	v_mfma_f32_16x16x32_bf16 v[44:47], v[132:135], v[192:195], v[44:47]
	v_mfma_f32_16x16x32_bf16 v[40:43], v[140:143], v[192:195], v[40:43]
	v_mfma_f32_16x16x32_bf16 v[28:31], v[132:135], v[202:205], v[28:31]
	v_mfma_f32_16x16x32_bf16 v[24:27], v[140:143], v[202:205], v[24:27]
	v_mfma_f32_16x16x32_bf16 v[12:15], v[132:135], v[210:213], v[12:15]
	v_mfma_f32_16x16x32_bf16 v[8:11], v[140:143], v[210:213], v[8:11]
	v_mfma_f32_16x16x32_bf16 v[52:55], v[144:147], v[180:183], v[52:55]
	v_mfma_f32_16x16x32_bf16 v[48:51], v[166:169], v[180:183], v[48:51]
	v_mfma_f32_16x16x32_bf16 v[36:39], v[144:147], v[188:191], v[36:39]
	v_mfma_f32_16x16x32_bf16 v[32:35], v[166:169], v[188:191], v[32:35]
	v_mfma_f32_16x16x32_bf16 v[20:23], v[144:147], v[196:199], v[20:23]
	v_mfma_f32_16x16x32_bf16 v[16:19], v[166:169], v[196:199], v[16:19]
	v_mfma_f32_16x16x32_bf16 v[4:7], v[144:147], v[206:209], v[4:7]
	v_mfma_f32_16x16x32_bf16 v[0:3], v[166:169], v[206:209], v[0:3]
	v_mfma_f32_16x16x32_bf16 v[52:55], v[162:165], v[184:187], v[52:55]
	v_mfma_f32_16x16x32_bf16 v[48:51], v[170:173], v[184:187], v[48:51]
	v_mfma_f32_16x16x32_bf16 v[36:39], v[162:165], v[192:195], v[36:39]
	v_mfma_f32_16x16x32_bf16 v[32:35], v[170:173], v[192:195], v[32:35]
	v_mfma_f32_16x16x32_bf16 v[20:23], v[162:165], v[202:205], v[20:23]
	v_mfma_f32_16x16x32_bf16 v[16:19], v[170:173], v[202:205], v[16:19]
	v_mfma_f32_16x16x32_bf16 v[4:7], v[162:165], v[210:213], v[4:7]
	v_mfma_f32_16x16x32_bf16 v[0:3], v[170:173], v[210:213], v[0:3]
	s_barrier
	s_add_i32 s45, 0, 0x18000
	s_add_i32 s72, 0, 0x1c000
	v_add_u32_e32 v140, s45, v175
	v_add_u32_e32 v170, s72, v175
	ds_read_b128 v[128:131], v140
	ds_read_b128 v[132:135], v140 offset:1024
	ds_read_b128 v[136:139], v140 offset:2048
	ds_read_b128 v[140:143], v140 offset:3072
	ds_read_b128 v[144:147], v170
	ds_read_b128 v[162:165], v170 offset:1024
	ds_read_b128 v[166:169], v170 offset:2048
	ds_read_b128 v[170:173], v170 offset:3072
	s_add_u32 s50, s56, 0x100000
	s_addc_u32 s51, s57, 0
	s_mov_b32 m0, s61
	v_lshl_add_u64 v[222:223], s[50:51], 0, v[148:149]
	ds_read_b128 v[180:183], v179 offset:32768
	ds_read_b128 v[184:187], v179 offset:33792
	ds_read_b128 v[188:191], v179 offset:34816
	ds_read_b128 v[192:195], v179 offset:35840
	ds_read_b128 v[196:199], v179 offset:36864
	ds_read_b128 v[202:205], v179 offset:37888
	ds_read_b128 v[206:209], v179 offset:38912
	ds_read_b128 v[210:213], v179 offset:39936
	global_load_lds_dwordx4 v[222:223], off
	v_lshl_add_u64 v[222:223], s[50:51], 0, v[152:153]
	s_mov_b32 m0, s62
	s_nop 0
	global_load_lds_dwordx4 v[222:223], off
	s_waitcnt vmcnt(8)
	s_waitcnt lgkmcnt(0)
	s_barrier
	v_mfma_f32_16x16x32_bf16 v[124:127], v[128:131], v[180:183], v[124:127]
	v_mfma_f32_16x16x32_bf16 v[120:123], v[136:139], v[180:183], v[120:123]
	v_mfma_f32_16x16x32_bf16 v[108:111], v[128:131], v[188:191], v[108:111]
	v_mfma_f32_16x16x32_bf16 v[104:107], v[136:139], v[188:191], v[104:107]
	v_mfma_f32_16x16x32_bf16 v[92:95], v[128:131], v[196:199], v[92:95]
	v_mfma_f32_16x16x32_bf16 v[88:91], v[136:139], v[196:199], v[88:91]
	v_mfma_f32_16x16x32_bf16 v[76:79], v[128:131], v[206:209], v[76:79]
	v_mfma_f32_16x16x32_bf16 v[72:75], v[136:139], v[206:209], v[72:75]
	v_mfma_f32_16x16x32_bf16 v[124:127], v[132:135], v[184:187], v[124:127]
	v_mfma_f32_16x16x32_bf16 v[120:123], v[140:143], v[184:187], v[120:123]
	v_mfma_f32_16x16x32_bf16 v[108:111], v[132:135], v[192:195], v[108:111]
	v_mfma_f32_16x16x32_bf16 v[104:107], v[140:143], v[192:195], v[104:107]
	v_mfma_f32_16x16x32_bf16 v[92:95], v[132:135], v[202:205], v[92:95]
	v_mfma_f32_16x16x32_bf16 v[88:91], v[140:143], v[202:205], v[88:91]
	v_mfma_f32_16x16x32_bf16 v[76:79], v[132:135], v[210:213], v[76:79]
	v_mfma_f32_16x16x32_bf16 v[72:75], v[140:143], v[210:213], v[72:75]
	v_mfma_f32_16x16x32_bf16 v[116:119], v[144:147], v[180:183], v[116:119]
	v_mfma_f32_16x16x32_bf16 v[112:115], v[166:169], v[180:183], v[112:115]
	v_mfma_f32_16x16x32_bf16 v[100:103], v[144:147], v[188:191], v[100:103]
	v_mfma_f32_16x16x32_bf16 v[96:99], v[166:169], v[188:191], v[96:99]
	v_mfma_f32_16x16x32_bf16 v[84:87], v[144:147], v[196:199], v[84:87]
	v_mfma_f32_16x16x32_bf16 v[80:83], v[166:169], v[196:199], v[80:83]
	v_mfma_f32_16x16x32_bf16 v[68:71], v[144:147], v[206:209], v[68:71]
	v_mfma_f32_16x16x32_bf16 v[64:67], v[166:169], v[206:209], v[64:67]
	v_mfma_f32_16x16x32_bf16 v[116:119], v[162:165], v[184:187], v[116:119]
	v_mfma_f32_16x16x32_bf16 v[112:115], v[170:173], v[184:187], v[112:115]
	v_mfma_f32_16x16x32_bf16 v[100:103], v[162:165], v[192:195], v[100:103]
	v_mfma_f32_16x16x32_bf16 v[96:99], v[170:173], v[192:195], v[96:99]
	v_mfma_f32_16x16x32_bf16 v[84:87], v[162:165], v[202:205], v[84:87]
	v_mfma_f32_16x16x32_bf16 v[80:83], v[170:173], v[202:205], v[80:83]
	v_mfma_f32_16x16x32_bf16 v[68:71], v[162:165], v[210:213], v[68:71]
	v_mfma_f32_16x16x32_bf16 v[64:67], v[170:173], v[210:213], v[64:67]
	s_barrier
	s_add_i32 s45, s45, s33
	v_lshl_add_u64 v[214:215], v[214:215], 0, s[10:11]
	s_mov_b32 m0, s45
	ds_read_b128 v[180:183], v179 offset:49152
	ds_read_b128 v[184:187], v179 offset:50176
	ds_read_b128 v[188:191], v179 offset:51200
	ds_read_b128 v[192:195], v179 offset:52224
	ds_read_b128 v[196:199], v179 offset:53248
	ds_read_b128 v[202:205], v179 offset:54272
	ds_read_b128 v[206:209], v179 offset:55296
	ds_read_b128 v[210:213], v179 offset:56320
	global_load_lds_dwordx4 v[214:215], off
	s_add_i32 m0, s45, 0x2000
	s_add_u32 s50, s54, 0x100080
	v_lshl_add_u64 v[214:215], v[216:217], 0, s[10:11]
	s_addc_u32 s51, s55, 0
	s_add_i32 s45, s72, s33
	global_load_lds_dwordx4 v[214:215], off
	v_lshl_add_u64 v[214:215], s[50:51], 0, v[150:151]
	s_mov_b32 m0, s45
	s_nop 0
	global_load_lds_dwordx4 v[214:215], off
	v_lshl_add_u64 v[214:215], s[50:51], 0, v[154:155]
	s_add_i32 m0, s45, 0x2000
	s_nop 0
	global_load_lds_dwordx4 v[214:215], off
	v_lshl_add_u64 v[214:215], v[218:219], 0, s[10:11]
	s_mov_b32 m0, s63
	s_nop 0
	global_load_lds_dwordx4 v[214:215], off
	v_lshl_add_u64 v[214:215], v[220:221], 0, s[10:11]
	s_mov_b32 m0, s64
	s_nop 0
	global_load_lds_dwordx4 v[214:215], off
	s_waitcnt vmcnt(8)
	s_waitcnt lgkmcnt(0)
	s_barrier
	v_mfma_f32_16x16x32_bf16 v[60:63], v[128:131], v[180:183], v[60:63]
	v_mfma_f32_16x16x32_bf16 v[56:59], v[136:139], v[180:183], v[56:59]
	v_mfma_f32_16x16x32_bf16 v[44:47], v[128:131], v[188:191], v[44:47]
	v_mfma_f32_16x16x32_bf16 v[40:43], v[136:139], v[188:191], v[40:43]
	v_mfma_f32_16x16x32_bf16 v[28:31], v[128:131], v[196:199], v[28:31]
	v_mfma_f32_16x16x32_bf16 v[24:27], v[136:139], v[196:199], v[24:27]
	v_mfma_f32_16x16x32_bf16 v[12:15], v[128:131], v[206:209], v[12:15]
	v_mfma_f32_16x16x32_bf16 v[8:11], v[136:139], v[206:209], v[8:11]
	v_mfma_f32_16x16x32_bf16 v[60:63], v[132:135], v[184:187], v[60:63]
	v_mfma_f32_16x16x32_bf16 v[56:59], v[140:143], v[184:187], v[56:59]
	v_mfma_f32_16x16x32_bf16 v[44:47], v[132:135], v[192:195], v[44:47]
	v_mfma_f32_16x16x32_bf16 v[40:43], v[140:143], v[192:195], v[40:43]
	v_mfma_f32_16x16x32_bf16 v[28:31], v[132:135], v[202:205], v[28:31]
	v_mfma_f32_16x16x32_bf16 v[24:27], v[140:143], v[202:205], v[24:27]
	v_mfma_f32_16x16x32_bf16 v[12:15], v[132:135], v[210:213], v[12:15]
	v_mfma_f32_16x16x32_bf16 v[8:11], v[140:143], v[210:213], v[8:11]
	v_mfma_f32_16x16x32_bf16 v[52:55], v[144:147], v[180:183], v[52:55]
	v_mfma_f32_16x16x32_bf16 v[48:51], v[166:169], v[180:183], v[48:51]
	v_mfma_f32_16x16x32_bf16 v[36:39], v[144:147], v[188:191], v[36:39]
	v_mfma_f32_16x16x32_bf16 v[32:35], v[166:169], v[188:191], v[32:35]
	v_mfma_f32_16x16x32_bf16 v[20:23], v[144:147], v[196:199], v[20:23]
	v_mfma_f32_16x16x32_bf16 v[16:19], v[166:169], v[196:199], v[16:19]
	v_mfma_f32_16x16x32_bf16 v[4:7], v[144:147], v[206:209], v[4:7]
	v_mfma_f32_16x16x32_bf16 v[0:3], v[166:169], v[206:209], v[0:3]
	v_mfma_f32_16x16x32_bf16 v[52:55], v[162:165], v[184:187], v[52:55]
	v_mfma_f32_16x16x32_bf16 v[48:51], v[170:173], v[184:187], v[48:51]
	v_mfma_f32_16x16x32_bf16 v[36:39], v[162:165], v[192:195], v[36:39]
	v_mfma_f32_16x16x32_bf16 v[32:35], v[170:173], v[192:195], v[32:35]
	v_mfma_f32_16x16x32_bf16 v[20:23], v[162:165], v[202:205], v[20:23]
	v_mfma_f32_16x16x32_bf16 v[16:19], v[170:173], v[202:205], v[16:19]
	v_mfma_f32_16x16x32_bf16 v[4:7], v[162:165], v[210:213], v[4:7]
	v_mfma_f32_16x16x32_bf16 v[0:3], v[170:173], v[210:213], v[0:3]
	s_add_u32 s52, s52, 0x100
	s_addc_u32 s53, s53, 0
	s_add_u32 s37, s37, 0x100
	s_addc_u32 s39, s39, 0
	s_cmp_ge_i32 s49, s48
	s_mov_b32 s45, s49
	s_cbranch_scc0 .Lrot_1141
	s_barrier
	s_and_b64 vcc, exec, s[14:15]
	s_cbranch_vccz .LBB0_1144

.LBB0_1298:
	s_ashr_i32 s13, s12, 31
	s_lshl_b64 s[14:15], s[12:13], 21
	v_readlane_b32 s16, v253, 6
	v_readlane_b32 s17, v253, 7
	s_add_u32 s14, s16, s14
	s_addc_u32 s15, s17, s15
	s_and_b64 s[16:17], s[0:1], exec
	s_cselect_b32 s13, s15, s35
	s_cselect_b32 s53, s14, s34
	s_ashr_i32 s11, s10, 31
	s_lshl_b64 s[16:17], s[10:11], 21
	s_add_u32 s16, s40, s16
	s_addc_u32 s17, s41, s17
	s_and_b64 s[38:39], s[0:1], exec
	s_cselect_b32 s11, s17, s37
	s_cselect_b32 s54, s16, s36
	s_add_u32 s34, s34, 0x100080
	s_addc_u32 s35, s35, 0
	s_add_u32 s55, s36, 0x100
	v_mov_b32_e32 v0, 0
	s_addc_u32 s56, s37, 0
	s_mov_b32 s57, -2
	v_mov_b32_e32 v1, v0
	v_mov_b32_e32 v2, v0
	v_mov_b32_e32 v3, v0
	v_mov_b32_e32 v4, v0
	v_mov_b32_e32 v5, v0
	v_mov_b32_e32 v6, v0
	v_mov_b32_e32 v7, v0
	v_mov_b32_e32 v16, v0
	v_mov_b32_e32 v17, v0
	v_mov_b32_e32 v18, v0
	v_mov_b32_e32 v19, v0
	v_mov_b32_e32 v20, v0
	v_mov_b32_e32 v21, v0
	v_mov_b32_e32 v22, v0
	v_mov_b32_e32 v23, v0
	v_mov_b32_e32 v32, v0
	v_mov_b32_e32 v33, v0
	v_mov_b32_e32 v34, v0
	v_mov_b32_e32 v35, v0
	v_mov_b32_e32 v36, v0
	v_mov_b32_e32 v37, v0
	v_mov_b32_e32 v38, v0
	v_mov_b32_e32 v39, v0
	v_mov_b32_e32 v48, v0
	v_mov_b32_e32 v49, v0
	v_mov_b32_e32 v50, v0
	v_mov_b32_e32 v51, v0
	v_mov_b32_e32 v52, v0
	v_mov_b32_e32 v53, v0
	v_mov_b32_e32 v54, v0
	v_mov_b32_e32 v55, v0
	v_mov_b32_e32 v8, v0
	v_mov_b32_e32 v9, v0
	v_mov_b32_e32 v10, v0
	v_mov_b32_e32 v11, v0
	v_mov_b32_e32 v12, v0
	v_mov_b32_e32 v13, v0
	v_mov_b32_e32 v14, v0
	v_mov_b32_e32 v15, v0
	v_mov_b32_e32 v24, v0
	v_mov_b32_e32 v25, v0
	v_mov_b32_e32 v26, v0
	v_mov_b32_e32 v27, v0
	v_mov_b32_e32 v28, v0
	v_mov_b32_e32 v29, v0
	v_mov_b32_e32 v30, v0
	v_mov_b32_e32 v31, v0
	v_mov_b32_e32 v40, v0
	v_mov_b32_e32 v41, v0
	v_mov_b32_e32 v42, v0
	v_mov_b32_e32 v43, v0
	v_mov_b32_e32 v44, v0
	v_mov_b32_e32 v45, v0
	v_mov_b32_e32 v46, v0
	v_mov_b32_e32 v47, v0
	v_mov_b32_e32 v56, v0
	v_mov_b32_e32 v57, v0
	v_mov_b32_e32 v58, v0
	v_mov_b32_e32 v59, v0
	v_mov_b32_e32 v60, v0
	v_mov_b32_e32 v61, v0
	v_mov_b32_e32 v62, v0
	v_mov_b32_e32 v63, v0
	v_mov_b32_e32 v64, v0
	v_mov_b32_e32 v65, v0
	v_mov_b32_e32 v66, v0
	v_mov_b32_e32 v67, v0
	v_mov_b32_e32 v68, v0
	v_mov_b32_e32 v69, v0
	v_mov_b32_e32 v70, v0
	v_mov_b32_e32 v71, v0
	v_mov_b32_e32 v80, v0
	v_mov_b32_e32 v81, v0
	v_mov_b32_e32 v82, v0
	v_mov_b32_e32 v83, v0
	v_mov_b32_e32 v84, v0
	v_mov_b32_e32 v85, v0
	v_mov_b32_e32 v86, v0
	v_mov_b32_e32 v87, v0
	v_mov_b32_e32 v96, v0
	v_mov_b32_e32 v97, v0
	v_mov_b32_e32 v98, v0
	v_mov_b32_e32 v99, v0
	v_mov_b32_e32 v100, v0
	v_mov_b32_e32 v101, v0
	v_mov_b32_e32 v102, v0
	v_mov_b32_e32 v103, v0
	v_mov_b32_e32 v112, v0
	v_mov_b32_e32 v113, v0
	v_mov_b32_e32 v114, v0
	v_mov_b32_e32 v115, v0
	v_mov_b32_e32 v116, v0
	v_mov_b32_e32 v117, v0
	v_mov_b32_e32 v118, v0
	v_mov_b32_e32 v119, v0
	v_mov_b32_e32 v72, v0
	v_mov_b32_e32 v73, v0
	v_mov_b32_e32 v74, v0
	v_mov_b32_e32 v75, v0
	v_mov_b32_e32 v76, v0
	v_mov_b32_e32 v77, v0
	v_mov_b32_e32 v78, v0
	v_mov_b32_e32 v79, v0
	v_mov_b32_e32 v88, v0
	v_mov_b32_e32 v89, v0
	v_mov_b32_e32 v90, v0
	v_mov_b32_e32 v91, v0
	v_mov_b32_e32 v92, v0
	v_mov_b32_e32 v93, v0
	v_mov_b32_e32 v94, v0
	v_mov_b32_e32 v95, v0
	v_mov_b32_e32 v104, v0
	v_mov_b32_e32 v105, v0
	v_mov_b32_e32 v106, v0
	v_mov_b32_e32 v107, v0
	v_mov_b32_e32 v108, v0
	v_mov_b32_e32 v109, v0
	v_mov_b32_e32 v110, v0
	v_mov_b32_e32 v111, v0
	v_mov_b32_e32 v120, v0
	v_mov_b32_e32 v121, v0
	v_mov_b32_e32 v122, v0
	v_mov_b32_e32 v123, v0
	v_mov_b32_e32 v124, v0
	v_mov_b32_e32 v125, v0
	v_mov_b32_e32 v126, v0
	v_mov_b32_e32 v127, v0
	s_branch .LBB0_1299

.LBB0_1299:
	ds_read_b128 v[144:147], v153 offset:0
	ds_read_b128 v[156:159], v153 offset:1024
	ds_read_b128 v[160:163], v153 offset:2048
	ds_read_b128 v[164:167], v153 offset:3072
	ds_read_b128 v[168:171], v154 offset:0
	ds_read_b128 v[172:175], v154 offset:1024
	ds_read_b128 v[176:179], v154 offset:2048
	ds_read_b128 v[180:183], v154 offset:3072
	s_add_u32 s36, s34, 0xfff00080
	s_addc_u32 s37, s35, -1
	s_cmp_eq_u32 s57, 60
	s_cselect_b32 s39, s13, s37
	s_cselect_b32 s38, s53, s36
	s_cselect_b32 s37, s11, s56
	s_cselect_b32 s36, s54, s55
	ds_read_b128 v[184:187], v155 offset:0
	ds_read_b128 v[188:191], v155 offset:1024
	ds_read_b128 v[192:195], v155 offset:2048
	ds_read_b128 v[196:199], v155 offset:3072
	ds_read_b128 v[202:205], v155 offset:4096
	ds_read_b128 v[206:209], v155 offset:5120
	ds_read_b128 v[210:213], v155 offset:6144
	ds_read_b128 v[214:217], v155 offset:7168
	s_add_i32 m0, s31, 0xc000
	s_nop 0
	global_load_lds_dwordx4 v136, s[34:35]
	s_add_i32 m0, s31, 0xe000
	s_nop 0
	global_load_lds_dwordx4 v138, s[34:35]
	s_waitcnt vmcnt(8)
	s_waitcnt lgkmcnt(0)
	s_barrier
	v_mfma_f32_16x16x32_bf16 v[124:127], v[144:147], v[184:187], v[124:127]
	v_mfma_f32_16x16x32_bf16 v[120:123], v[160:163], v[184:187], v[120:123]
	v_mfma_f32_16x16x32_bf16 v[108:111], v[144:147], v[192:195], v[108:111]
	v_mfma_f32_16x16x32_bf16 v[104:107], v[160:163], v[192:195], v[104:107]
	v_mfma_f32_16x16x32_bf16 v[92:95], v[144:147], v[202:205], v[92:95]
	v_mfma_f32_16x16x32_bf16 v[88:91], v[160:163], v[202:205], v[88:91]
	v_mfma_f32_16x16x32_bf16 v[76:79], v[144:147], v[210:213], v[76:79]
	v_mfma_f32_16x16x32_bf16 v[72:75], v[160:163], v[210:213], v[72:75]
	v_mfma_f32_16x16x32_bf16 v[124:127], v[156:159], v[188:191], v[124:127]
	v_mfma_f32_16x16x32_bf16 v[120:123], v[164:167], v[188:191], v[120:123]
	v_mfma_f32_16x16x32_bf16 v[108:111], v[156:159], v[196:199], v[108:111]
	v_mfma_f32_16x16x32_bf16 v[104:107], v[164:167], v[196:199], v[104:107]
	v_mfma_f32_16x16x32_bf16 v[92:95], v[156:159], v[206:209], v[92:95]
	v_mfma_f32_16x16x32_bf16 v[88:91], v[164:167], v[206:209], v[88:91]
	v_mfma_f32_16x16x32_bf16 v[76:79], v[156:159], v[214:217], v[76:79]
	v_mfma_f32_16x16x32_bf16 v[72:75], v[164:167], v[214:217], v[72:75]
	v_mfma_f32_16x16x32_bf16 v[116:119], v[168:171], v[184:187], v[116:119]
	v_mfma_f32_16x16x32_bf16 v[112:115], v[176:179], v[184:187], v[112:115]
	v_mfma_f32_16x16x32_bf16 v[100:103], v[168:171], v[192:195], v[100:103]
	v_mfma_f32_16x16x32_bf16 v[96:99], v[176:179], v[192:195], v[96:99]
	v_mfma_f32_16x16x32_bf16 v[84:87], v[168:171], v[202:205], v[84:87]
	v_mfma_f32_16x16x32_bf16 v[80:83], v[176:179], v[202:205], v[80:83]
	v_mfma_f32_16x16x32_bf16 v[68:71], v[168:171], v[210:213], v[68:71]
	v_mfma_f32_16x16x32_bf16 v[64:67], v[176:179], v[210:213], v[64:67]
	v_mfma_f32_16x16x32_bf16 v[116:119], v[172:175], v[188:191], v[116:119]
	v_mfma_f32_16x16x32_bf16 v[112:115], v[180:183], v[188:191], v[112:115]
	v_mfma_f32_16x16x32_bf16 v[100:103], v[172:175], v[196:199], v[100:103]
	v_mfma_f32_16x16x32_bf16 v[96:99], v[180:183], v[196:199], v[96:99]
	v_mfma_f32_16x16x32_bf16 v[84:87], v[172:175], v[206:209], v[84:87]
	v_mfma_f32_16x16x32_bf16 v[80:83], v[180:183], v[206:209], v[80:83]
	v_mfma_f32_16x16x32_bf16 v[68:71], v[172:175], v[214:217], v[68:71]
	v_mfma_f32_16x16x32_bf16 v[64:67], v[180:183], v[214:217], v[64:67]
	s_barrier
	s_add_u32 s58, s36, 0x100000
	s_addc_u32 s59, s37, 0
	ds_read_b128 v[184:187], v155 offset:16384
	ds_read_b128 v[188:191], v155 offset:17408
	ds_read_b128 v[192:195], v155 offset:18432
	ds_read_b128 v[196:199], v155 offset:19456
	ds_read_b128 v[202:205], v155 offset:20480
	ds_read_b128 v[206:209], v155 offset:21504
	ds_read_b128 v[210:213], v155 offset:22528
	ds_read_b128 v[214:217], v155 offset:23552
	s_add_i32 m0, s31, 0x10000
	s_nop 0
	global_load_lds_dwordx4 v130, s[36:37]
	s_add_i32 m0, s31, 0x12000
	s_nop 0
	global_load_lds_dwordx4 v134, s[36:37]
	s_add_i32 m0, s31, 0x14000
	s_nop 0
	global_load_lds_dwordx4 v130, s[58:59]
	s_add_i32 m0, s31, 0x16000
	s_nop 0
	global_load_lds_dwordx4 v134, s[58:59]
	s_add_i32 m0, s31, 0x0
	s_nop 0
	global_load_lds_dwordx4 v128, s[38:39]
	s_add_i32 m0, s31, 0x2000
	s_nop 0
	global_load_lds_dwordx4 v132, s[38:39]
	s_waitcnt vmcnt(8)
	s_waitcnt lgkmcnt(0)
	s_barrier
	v_mfma_f32_16x16x32_bf16 v[60:63], v[144:147], v[184:187], v[60:63]
	v_mfma_f32_16x16x32_bf16 v[56:59], v[160:163], v[184:187], v[56:59]
	v_mfma_f32_16x16x32_bf16 v[44:47], v[144:147], v[192:195], v[44:47]
	v_mfma_f32_16x16x32_bf16 v[40:43], v[160:163], v[192:195], v[40:43]
	v_mfma_f32_16x16x32_bf16 v[28:31], v[144:147], v[202:205], v[28:31]
	v_mfma_f32_16x16x32_bf16 v[24:27], v[160:163], v[202:205], v[24:27]
	v_mfma_f32_16x16x32_bf16 v[12:15], v[144:147], v[210:213], v[12:15]
	v_mfma_f32_16x16x32_bf16 v[8:11], v[160:163], v[210:213], v[8:11]
	v_mfma_f32_16x16x32_bf16 v[60:63], v[156:159], v[188:191], v[60:63]
	v_mfma_f32_16x16x32_bf16 v[56:59], v[164:167], v[188:191], v[56:59]
	v_mfma_f32_16x16x32_bf16 v[44:47], v[156:159], v[196:199], v[44:47]
	v_mfma_f32_16x16x32_bf16 v[40:43], v[164:167], v[196:199], v[40:43]
	v_mfma_f32_16x16x32_bf16 v[28:31], v[156:159], v[206:209], v[28:31]
	v_mfma_f32_16x16x32_bf16 v[24:27], v[164:167], v[206:209], v[24:27]
	v_mfma_f32_16x16x32_bf16 v[12:15], v[156:159], v[214:217], v[12:15]
	v_mfma_f32_16x16x32_bf16 v[8:11], v[164:167], v[214:217], v[8:11]
	v_mfma_f32_16x16x32_bf16 v[52:55], v[168:171], v[184:187], v[52:55]
	v_mfma_f32_16x16x32_bf16 v[48:51], v[176:179], v[184:187], v[48:51]
	v_mfma_f32_16x16x32_bf16 v[36:39], v[168:171], v[192:195], v[36:39]
	v_mfma_f32_16x16x32_bf16 v[32:35], v[176:179], v[192:195], v[32:35]
	v_mfma_f32_16x16x32_bf16 v[20:23], v[168:171], v[202:205], v[20:23]
	v_mfma_f32_16x16x32_bf16 v[16:19], v[176:179], v[202:205], v[16:19]
	v_mfma_f32_16x16x32_bf16 v[4:7], v[168:171], v[210:213], v[4:7]
	v_mfma_f32_16x16x32_bf16 v[0:3], v[176:179], v[210:213], v[0:3]
	v_mfma_f32_16x16x32_bf16 v[52:55], v[172:175], v[188:191], v[52:55]
	v_mfma_f32_16x16x32_bf16 v[48:51], v[180:183], v[188:191], v[48:51]
	v_mfma_f32_16x16x32_bf16 v[36:39], v[172:175], v[196:199], v[36:39]
	v_mfma_f32_16x16x32_bf16 v[32:35], v[180:183], v[196:199], v[32:35]
	v_mfma_f32_16x16x32_bf16 v[20:23], v[172:175], v[206:209], v[20:23]
	v_mfma_f32_16x16x32_bf16 v[16:19], v[180:183], v[206:209], v[16:19]
	v_mfma_f32_16x16x32_bf16 v[4:7], v[172:175], v[214:217], v[4:7]
	v_mfma_f32_16x16x32_bf16 v[0:3], v[180:183], v[214:217], v[0:3]
	s_barrier
	s_add_u32 s98, s38, 0x100000
	s_addc_u32 s99, s39, 0
	ds_read_b128 v[144:147], v153 offset:32768
	ds_read_b128 v[156:159], v153 offset:33792
	ds_read_b128 v[160:163], v153 offset:34816
	ds_read_b128 v[164:167], v153 offset:35840
	ds_read_b128 v[168:171], v154 offset:32768
	ds_read_b128 v[172:175], v154 offset:33792
	ds_read_b128 v[176:179], v154 offset:34816
	ds_read_b128 v[180:183], v154 offset:35840
	ds_read_b128 v[184:187], v155 offset:32768
	ds_read_b128 v[188:191], v155 offset:33792
	ds_read_b128 v[192:195], v155 offset:34816
	ds_read_b128 v[196:199], v155 offset:35840
	ds_read_b128 v[202:205], v155 offset:36864
	ds_read_b128 v[206:209], v155 offset:37888
	ds_read_b128 v[210:213], v155 offset:38912
	ds_read_b128 v[214:217], v155 offset:39936
	s_add_i32 m0, s31, 0x4000
	s_nop 0
	global_load_lds_dwordx4 v128, s[98:99]
	s_add_i32 m0, s31, 0x6000
	s_nop 0
	global_load_lds_dwordx4 v132, s[98:99]
	s_waitcnt vmcnt(8)
	s_waitcnt lgkmcnt(0)
	s_barrier
	v_mfma_f32_16x16x32_bf16 v[124:127], v[144:147], v[184:187], v[124:127]
	v_mfma_f32_16x16x32_bf16 v[120:123], v[160:163], v[184:187], v[120:123]
	v_mfma_f32_16x16x32_bf16 v[108:111], v[144:147], v[192:195], v[108:111]
	v_mfma_f32_16x16x32_bf16 v[104:107], v[160:163], v[192:195], v[104:107]
	v_mfma_f32_16x16x32_bf16 v[92:95], v[144:147], v[202:205], v[92:95]
	v_mfma_f32_16x16x32_bf16 v[88:91], v[160:163], v[202:205], v[88:91]
	v_mfma_f32_16x16x32_bf16 v[76:79], v[144:147], v[210:213], v[76:79]
	v_mfma_f32_16x16x32_bf16 v[72:75], v[160:163], v[210:213], v[72:75]
	v_mfma_f32_16x16x32_bf16 v[124:127], v[156:159], v[188:191], v[124:127]
	v_mfma_f32_16x16x32_bf16 v[120:123], v[164:167], v[188:191], v[120:123]
	v_mfma_f32_16x16x32_bf16 v[108:111], v[156:159], v[196:199], v[108:111]
	v_mfma_f32_16x16x32_bf16 v[104:107], v[164:167], v[196:199], v[104:107]
	v_mfma_f32_16x16x32_bf16 v[92:95], v[156:159], v[206:209], v[92:95]
	v_mfma_f32_16x16x32_bf16 v[88:91], v[164:167], v[206:209], v[88:91]
	v_mfma_f32_16x16x32_bf16 v[76:79], v[156:159], v[214:217], v[76:79]
	v_mfma_f32_16x16x32_bf16 v[72:75], v[164:167], v[214:217], v[72:75]
	v_mfma_f32_16x16x32_bf16 v[116:119], v[168:171], v[184:187], v[116:119]
	v_mfma_f32_16x16x32_bf16 v[112:115], v[176:179], v[184:187], v[112:115]
	v_mfma_f32_16x16x32_bf16 v[100:103], v[168:171], v[192:195], v[100:103]
	v_mfma_f32_16x16x32_bf16 v[96:99], v[176:179], v[192:195], v[96:99]
	v_mfma_f32_16x16x32_bf16 v[84:87], v[168:171], v[202:205], v[84:87]
	v_mfma_f32_16x16x32_bf16 v[80:83], v[176:179], v[202:205], v[80:83]
	v_mfma_f32_16x16x32_bf16 v[68:71], v[168:171], v[210:213], v[68:71]
	v_mfma_f32_16x16x32_bf16 v[64:67], v[176:179], v[210:213], v[64:67]
	v_mfma_f32_16x16x32_bf16 v[116:119], v[172:175], v[188:191], v[116:119]
	v_mfma_f32_16x16x32_bf16 v[112:115], v[180:183], v[188:191], v[112:115]
	v_mfma_f32_16x16x32_bf16 v[100:103], v[172:175], v[196:199], v[100:103]
	v_mfma_f32_16x16x32_bf16 v[96:99], v[180:183], v[196:199], v[96:99]
	v_mfma_f32_16x16x32_bf16 v[84:87], v[172:175], v[206:209], v[84:87]
	v_mfma_f32_16x16x32_bf16 v[80:83], v[180:183], v[206:209], v[80:83]
	v_mfma_f32_16x16x32_bf16 v[68:71], v[172:175], v[214:217], v[68:71]
	v_mfma_f32_16x16x32_bf16 v[64:67], v[180:183], v[214:217], v[64:67]
	s_barrier
	s_add_u32 s100, s36, 0x80
	s_addc_u32 s101, s37, 0
	s_add_u32 s58, s36, 0x100080
	s_addc_u32 s59, s37, 0
	s_add_u32 s98, s38, 0x80
	s_addc_u32 s99, s39, 0
	ds_read_b128 v[184:187], v155 offset:49152
	ds_read_b128 v[188:191], v155 offset:50176
	ds_read_b128 v[192:195], v155 offset:51200
	ds_read_b128 v[196:199], v155 offset:52224
	ds_read_b128 v[202:205], v155 offset:53248
	ds_read_b128 v[206:209], v155 offset:54272
	ds_read_b128 v[210:213], v155 offset:55296
	ds_read_b128 v[214:217], v155 offset:56320
	s_add_i32 m0, s31, 0x18000
	s_nop 0
	global_load_lds_dwordx4 v130, s[100:101]
	s_add_i32 m0, s31, 0x1a000
	s_nop 0
	global_load_lds_dwordx4 v134, s[100:101]
	s_add_i32 m0, s31, 0x1c000
	s_nop 0
	global_load_lds_dwordx4 v130, s[58:59]
	s_add_i32 m0, s31, 0x1e000
	s_nop 0
	global_load_lds_dwordx4 v134, s[58:59]
	s_add_i32 m0, s31, 0x8000
	s_nop 0
	global_load_lds_dwordx4 v128, s[98:99]
	s_add_i32 m0, s31, 0xa000
	s_nop 0
	global_load_lds_dwordx4 v132, s[98:99]
	s_waitcnt vmcnt(8)
	s_waitcnt lgkmcnt(0)
	s_barrier
	v_mfma_f32_16x16x32_bf16 v[60:63], v[144:147], v[184:187], v[60:63]
	v_mfma_f32_16x16x32_bf16 v[56:59], v[160:163], v[184:187], v[56:59]
	v_mfma_f32_16x16x32_bf16 v[44:47], v[144:147], v[192:195], v[44:47]
	v_mfma_f32_16x16x32_bf16 v[40:43], v[160:163], v[192:195], v[40:43]
	v_mfma_f32_16x16x32_bf16 v[28:31], v[144:147], v[202:205], v[28:31]
	v_mfma_f32_16x16x32_bf16 v[24:27], v[160:163], v[202:205], v[24:27]
	v_mfma_f32_16x16x32_bf16 v[12:15], v[144:147], v[210:213], v[12:15]
	v_mfma_f32_16x16x32_bf16 v[8:11], v[160:163], v[210:213], v[8:11]
	v_mfma_f32_16x16x32_bf16 v[60:63], v[156:159], v[188:191], v[60:63]
	v_mfma_f32_16x16x32_bf16 v[56:59], v[164:167], v[188:191], v[56:59]
	v_mfma_f32_16x16x32_bf16 v[44:47], v[156:159], v[196:199], v[44:47]
	v_mfma_f32_16x16x32_bf16 v[40:43], v[164:167], v[196:199], v[40:43]
	v_mfma_f32_16x16x32_bf16 v[28:31], v[156:159], v[206:209], v[28:31]
	v_mfma_f32_16x16x32_bf16 v[24:27], v[164:167], v[206:209], v[24:27]
	v_mfma_f32_16x16x32_bf16 v[12:15], v[156:159], v[214:217], v[12:15]
	v_mfma_f32_16x16x32_bf16 v[8:11], v[164:167], v[214:217], v[8:11]
	v_mfma_f32_16x16x32_bf16 v[52:55], v[168:171], v[184:187], v[52:55]
	v_mfma_f32_16x16x32_bf16 v[48:51], v[176:179], v[184:187], v[48:51]
	v_mfma_f32_16x16x32_bf16 v[36:39], v[168:171], v[192:195], v[36:39]
	v_mfma_f32_16x16x32_bf16 v[32:35], v[176:179], v[192:195], v[32:35]
	v_mfma_f32_16x16x32_bf16 v[20:23], v[168:171], v[202:205], v[20:23]
	v_mfma_f32_16x16x32_bf16 v[16:19], v[176:179], v[202:205], v[16:19]
	v_mfma_f32_16x16x32_bf16 v[4:7], v[168:171], v[210:213], v[4:7]
	v_mfma_f32_16x16x32_bf16 v[0:3], v[176:179], v[210:213], v[0:3]
	v_mfma_f32_16x16x32_bf16 v[52:55], v[172:175], v[188:191], v[52:55]
	v_mfma_f32_16x16x32_bf16 v[48:51], v[180:183], v[188:191], v[48:51]
	v_mfma_f32_16x16x32_bf16 v[36:39], v[172:175], v[196:199], v[36:39]
	v_mfma_f32_16x16x32_bf16 v[32:35], v[180:183], v[196:199], v[32:35]
	v_mfma_f32_16x16x32_bf16 v[20:23], v[172:175], v[206:209], v[20:23]
	v_mfma_f32_16x16x32_bf16 v[16:19], v[180:183], v[206:209], v[16:19]
	v_mfma_f32_16x16x32_bf16 v[4:7], v[172:175], v[214:217], v[4:7]
	v_mfma_f32_16x16x32_bf16 v[0:3], v[180:183], v[214:217], v[0:3]
	s_add_i32 s57, s57, 2
	s_add_u32 s34, s34, 0x100
	s_addc_u32 s35, s35, 0
	s_add_u32 s55, s55, 0x100
	s_addc_u32 s56, s56, 0
	s_cmp_gt_u32 s57, 61
	s_cbranch_scc0 .Lrot_1299
	s_barrier
	s_and_b64 vcc, exec, s[6:7]
	s_cbranch_vccz .LBB0_1302
	s_barrier

.LBB0_1408:
	s_add_i32 s37, s67, -2
	s_add_u32 s68, s44, 0x100
	v_mov_b32_e32 v0, 0
	s_addc_u32 s69, s45, 0
	s_mov_b32 s46, 0
	v_mov_b32_e32 v1, v0
	v_mov_b32_e32 v2, v0
	v_mov_b32_e32 v3, v0
	v_mov_b32_e32 v4, v0
	v_mov_b32_e32 v5, v0
	v_mov_b32_e32 v6, v0
	v_mov_b32_e32 v7, v0
	v_mov_b32_e32 v16, v0
	v_mov_b32_e32 v17, v0
	v_mov_b32_e32 v18, v0
	v_mov_b32_e32 v19, v0
	v_mov_b32_e32 v20, v0
	v_mov_b32_e32 v21, v0
	v_mov_b32_e32 v22, v0
	v_mov_b32_e32 v23, v0
	v_mov_b32_e32 v32, v0
	v_mov_b32_e32 v33, v0
	v_mov_b32_e32 v34, v0
	v_mov_b32_e32 v35, v0
	v_mov_b32_e32 v36, v0
	v_mov_b32_e32 v37, v0
	v_mov_b32_e32 v38, v0
	v_mov_b32_e32 v39, v0
	v_mov_b32_e32 v48, v0
	v_mov_b32_e32 v49, v0
	v_mov_b32_e32 v50, v0
	v_mov_b32_e32 v51, v0
	v_mov_b32_e32 v52, v0
	v_mov_b32_e32 v53, v0
	v_mov_b32_e32 v54, v0
	v_mov_b32_e32 v55, v0
	v_mov_b32_e32 v8, v0
	v_mov_b32_e32 v9, v0
	v_mov_b32_e32 v10, v0
	v_mov_b32_e32 v11, v0
	v_mov_b32_e32 v12, v0
	v_mov_b32_e32 v13, v0
	v_mov_b32_e32 v14, v0
	v_mov_b32_e32 v15, v0
	v_mov_b32_e32 v24, v0
	v_mov_b32_e32 v25, v0
	v_mov_b32_e32 v26, v0
	v_mov_b32_e32 v27, v0
	v_mov_b32_e32 v28, v0
	v_mov_b32_e32 v29, v0
	v_mov_b32_e32 v30, v0
	v_mov_b32_e32 v31, v0
	v_mov_b32_e32 v40, v0
	v_mov_b32_e32 v41, v0
	v_mov_b32_e32 v42, v0
	v_mov_b32_e32 v43, v0
	v_mov_b32_e32 v44, v0
	v_mov_b32_e32 v45, v0
	v_mov_b32_e32 v46, v0
	v_mov_b32_e32 v47, v0
	v_mov_b32_e32 v56, v0
	v_mov_b32_e32 v57, v0
	v_mov_b32_e32 v58, v0
	v_mov_b32_e32 v59, v0
	v_mov_b32_e32 v60, v0
	v_mov_b32_e32 v61, v0
	v_mov_b32_e32 v62, v0
	v_mov_b32_e32 v63, v0
	v_mov_b32_e32 v64, v0
	v_mov_b32_e32 v65, v0
	v_mov_b32_e32 v66, v0
	v_mov_b32_e32 v67, v0
	v_mov_b32_e32 v68, v0
	v_mov_b32_e32 v69, v0
	v_mov_b32_e32 v70, v0
	v_mov_b32_e32 v71, v0
	v_mov_b32_e32 v80, v0
	v_mov_b32_e32 v81, v0
	v_mov_b32_e32 v82, v0
	v_mov_b32_e32 v83, v0
	v_mov_b32_e32 v84, v0
	v_mov_b32_e32 v85, v0
	v_mov_b32_e32 v86, v0
	v_mov_b32_e32 v87, v0
	v_mov_b32_e32 v96, v0
	v_mov_b32_e32 v97, v0
	v_mov_b32_e32 v98, v0
	v_mov_b32_e32 v99, v0
	v_mov_b32_e32 v100, v0
	v_mov_b32_e32 v101, v0
	v_mov_b32_e32 v102, v0
	v_mov_b32_e32 v103, v0
	v_mov_b32_e32 v112, v0
	v_mov_b32_e32 v113, v0
	v_mov_b32_e32 v114, v0
	v_mov_b32_e32 v115, v0
	v_mov_b32_e32 v116, v0
	v_mov_b32_e32 v117, v0
	v_mov_b32_e32 v118, v0
	v_mov_b32_e32 v119, v0
	v_mov_b32_e32 v72, v0
	v_mov_b32_e32 v73, v0
	v_mov_b32_e32 v74, v0
	v_mov_b32_e32 v75, v0
	v_mov_b32_e32 v76, v0
	v_mov_b32_e32 v77, v0
	v_mov_b32_e32 v78, v0
	v_mov_b32_e32 v79, v0
	v_mov_b32_e32 v88, v0
	v_mov_b32_e32 v89, v0
	v_mov_b32_e32 v90, v0
	v_mov_b32_e32 v91, v0
	v_mov_b32_e32 v92, v0
	v_mov_b32_e32 v93, v0
	v_mov_b32_e32 v94, v0
	v_mov_b32_e32 v95, v0
	v_mov_b32_e32 v104, v0
	v_mov_b32_e32 v105, v0
	v_mov_b32_e32 v106, v0
	v_mov_b32_e32 v107, v0
	v_mov_b32_e32 v108, v0
	v_mov_b32_e32 v109, v0
	v_mov_b32_e32 v110, v0
	v_mov_b32_e32 v111, v0
	v_mov_b32_e32 v120, v0
	v_mov_b32_e32 v121, v0
	v_mov_b32_e32 v122, v0
	v_mov_b32_e32 v123, v0
	v_mov_b32_e32 v124, v0
	v_mov_b32_e32 v125, v0
	v_mov_b32_e32 v126, v0
	v_mov_b32_e32 v127, v0
	s_branch .LBB0_1409

.LBB0_1409:
	ds_read_b128 v[128:131], v177 offset:0
	ds_read_b128 v[146:149], v177 offset:1024
	ds_read_b128 v[150:153], v177 offset:2048
	ds_read_b128 v[154:157], v177 offset:3072
	ds_read_b128 v[158:161], v178 offset:0
	ds_read_b128 v[162:165], v178 offset:1024
	ds_read_b128 v[166:169], v178 offset:2048
	ds_read_b128 v[170:173], v178 offset:3072
	s_add_i32 s70, s46, 2
	s_add_u32 s44, s42, 0x100
	s_addc_u32 s45, s43, 0
	s_cmp_eq_u32 s37, s46
	s_cselect_b32 s46, s40, s68
	s_cselect_b32 s49, s39, s45
	s_cselect_b32 s48, s38, s44
	s_cselect_b32 s47, s41, s69
	ds_read_b128 v[180:183], v179 offset:0
	ds_read_b128 v[184:187], v179 offset:1024
	ds_read_b128 v[188:191], v179 offset:2048
	ds_read_b128 v[192:195], v179 offset:3072
	ds_read_b128 v[196:199], v179 offset:4096
	ds_read_b128 v[202:205], v179 offset:5120
	ds_read_b128 v[206:209], v179 offset:6144
	ds_read_b128 v[210:213], v179 offset:7168
	s_add_i32 m0, s50, 0xc000
	s_nop 0
	global_load_lds_dwordx4 v140, s[42:43]
	s_add_i32 m0, s50, 0xe000
	s_nop 0
	global_load_lds_dwordx4 v142, s[42:43]
	s_waitcnt vmcnt(8)
	s_waitcnt lgkmcnt(0)
	s_barrier
	v_mfma_f32_16x16x32_bf16 v[124:127], v[128:131], v[180:183], v[124:127]
	v_mfma_f32_16x16x32_bf16 v[120:123], v[150:153], v[180:183], v[120:123]
	v_mfma_f32_16x16x32_bf16 v[108:111], v[128:131], v[188:191], v[108:111]
	v_mfma_f32_16x16x32_bf16 v[104:107], v[150:153], v[188:191], v[104:107]
	v_mfma_f32_16x16x32_bf16 v[92:95], v[128:131], v[196:199], v[92:95]
	v_mfma_f32_16x16x32_bf16 v[88:91], v[150:153], v[196:199], v[88:91]
	v_mfma_f32_16x16x32_bf16 v[76:79], v[128:131], v[206:209], v[76:79]
	v_mfma_f32_16x16x32_bf16 v[72:75], v[150:153], v[206:209], v[72:75]
	v_mfma_f32_16x16x32_bf16 v[124:127], v[146:149], v[184:187], v[124:127]
	v_mfma_f32_16x16x32_bf16 v[120:123], v[154:157], v[184:187], v[120:123]
	v_mfma_f32_16x16x32_bf16 v[108:111], v[146:149], v[192:195], v[108:111]
	v_mfma_f32_16x16x32_bf16 v[104:107], v[154:157], v[192:195], v[104:107]
	v_mfma_f32_16x16x32_bf16 v[92:95], v[146:149], v[202:205], v[92:95]
	v_mfma_f32_16x16x32_bf16 v[88:91], v[154:157], v[202:205], v[88:91]
	v_mfma_f32_16x16x32_bf16 v[76:79], v[146:149], v[210:213], v[76:79]
	v_mfma_f32_16x16x32_bf16 v[72:75], v[154:157], v[210:213], v[72:75]
	v_mfma_f32_16x16x32_bf16 v[116:119], v[158:161], v[180:183], v[116:119]
	v_mfma_f32_16x16x32_bf16 v[112:115], v[166:169], v[180:183], v[112:115]
	v_mfma_f32_16x16x32_bf16 v[100:103], v[158:161], v[188:191], v[100:103]
	v_mfma_f32_16x16x32_bf16 v[96:99], v[166:169], v[188:191], v[96:99]
	v_mfma_f32_16x16x32_bf16 v[84:87], v[158:161], v[196:199], v[84:87]
	v_mfma_f32_16x16x32_bf16 v[80:83], v[166:169], v[196:199], v[80:83]
	v_mfma_f32_16x16x32_bf16 v[68:71], v[158:161], v[206:209], v[68:71]
	v_mfma_f32_16x16x32_bf16 v[64:67], v[166:169], v[206:209], v[64:67]
	v_mfma_f32_16x16x32_bf16 v[116:119], v[162:165], v[184:187], v[116:119]
	v_mfma_f32_16x16x32_bf16 v[112:115], v[170:173], v[184:187], v[112:115]
	v_mfma_f32_16x16x32_bf16 v[100:103], v[162:165], v[192:195], v[100:103]
	v_mfma_f32_16x16x32_bf16 v[96:99], v[170:173], v[192:195], v[96:99]
	v_mfma_f32_16x16x32_bf16 v[84:87], v[162:165], v[202:205], v[84:87]
	v_mfma_f32_16x16x32_bf16 v[80:83], v[170:173], v[202:205], v[80:83]
	v_mfma_f32_16x16x32_bf16 v[68:71], v[162:165], v[210:213], v[68:71]
	v_mfma_f32_16x16x32_bf16 v[64:67], v[170:173], v[210:213], v[64:67]
	s_barrier
	s_add_u32 s42, s46, 0x2b0000
	s_addc_u32 s43, s47, 0
	ds_read_b128 v[180:183], v179 offset:16384
	ds_read_b128 v[184:187], v179 offset:17408
	ds_read_b128 v[188:191], v179 offset:18432
	ds_read_b128 v[192:195], v179 offset:19456
	ds_read_b128 v[196:199], v179 offset:20480
	ds_read_b128 v[202:205], v179 offset:21504
	ds_read_b128 v[206:209], v179 offset:22528
	ds_read_b128 v[210:213], v179 offset:23552
	s_add_i32 m0, s50, 0x10000
	s_nop 0
	global_load_lds_dwordx4 v134, s[46:47]
	s_add_i32 m0, s50, 0x12000
	s_nop 0
	global_load_lds_dwordx4 v138, s[46:47]
	s_add_i32 m0, s50, 0x14000
	s_nop 0
	global_load_lds_dwordx4 v134, s[42:43]
	s_add_i32 m0, s50, 0x16000
	s_nop 0
	global_load_lds_dwordx4 v138, s[42:43]
	s_add_i32 m0, s50, 0x0
	s_nop 0
	global_load_lds_dwordx4 v132, s[48:49]
	s_add_i32 m0, s50, 0x2000
	s_nop 0
	global_load_lds_dwordx4 v136, s[48:49]
	s_waitcnt vmcnt(8)
	s_waitcnt lgkmcnt(0)
	s_barrier
	v_mfma_f32_16x16x32_bf16 v[60:63], v[128:131], v[180:183], v[60:63]
	v_mfma_f32_16x16x32_bf16 v[56:59], v[150:153], v[180:183], v[56:59]
	v_mfma_f32_16x16x32_bf16 v[44:47], v[128:131], v[188:191], v[44:47]
	v_mfma_f32_16x16x32_bf16 v[40:43], v[150:153], v[188:191], v[40:43]
	v_mfma_f32_16x16x32_bf16 v[28:31], v[128:131], v[196:199], v[28:31]
	v_mfma_f32_16x16x32_bf16 v[24:27], v[150:153], v[196:199], v[24:27]
	v_mfma_f32_16x16x32_bf16 v[12:15], v[128:131], v[206:209], v[12:15]
	v_mfma_f32_16x16x32_bf16 v[8:11], v[150:153], v[206:209], v[8:11]
	v_mfma_f32_16x16x32_bf16 v[60:63], v[146:149], v[184:187], v[60:63]
	v_mfma_f32_16x16x32_bf16 v[56:59], v[154:157], v[184:187], v[56:59]
	v_mfma_f32_16x16x32_bf16 v[44:47], v[146:149], v[192:195], v[44:47]
	v_mfma_f32_16x16x32_bf16 v[40:43], v[154:157], v[192:195], v[40:43]
	v_mfma_f32_16x16x32_bf16 v[28:31], v[146:149], v[202:205], v[28:31]
	v_mfma_f32_16x16x32_bf16 v[24:27], v[154:157], v[202:205], v[24:27]
	v_mfma_f32_16x16x32_bf16 v[12:15], v[146:149], v[210:213], v[12:15]
	v_mfma_f32_16x16x32_bf16 v[8:11], v[154:157], v[210:213], v[8:11]
	v_mfma_f32_16x16x32_bf16 v[52:55], v[158:161], v[180:183], v[52:55]
	v_mfma_f32_16x16x32_bf16 v[48:51], v[166:169], v[180:183], v[48:51]
	v_mfma_f32_16x16x32_bf16 v[36:39], v[158:161], v[188:191], v[36:39]
	v_mfma_f32_16x16x32_bf16 v[32:35], v[166:169], v[188:191], v[32:35]
	v_mfma_f32_16x16x32_bf16 v[20:23], v[158:161], v[196:199], v[20:23]
	v_mfma_f32_16x16x32_bf16 v[16:19], v[166:169], v[196:199], v[16:19]
	v_mfma_f32_16x16x32_bf16 v[4:7], v[158:161], v[206:209], v[4:7]
	v_mfma_f32_16x16x32_bf16 v[0:3], v[166:169], v[206:209], v[0:3]
	v_mfma_f32_16x16x32_bf16 v[52:55], v[162:165], v[184:187], v[52:55]
	v_mfma_f32_16x16x32_bf16 v[48:51], v[170:173], v[184:187], v[48:51]
	v_mfma_f32_16x16x32_bf16 v[36:39], v[162:165], v[192:195], v[36:39]
	v_mfma_f32_16x16x32_bf16 v[32:35], v[170:173], v[192:195], v[32:35]
	v_mfma_f32_16x16x32_bf16 v[20:23], v[162:165], v[202:205], v[20:23]
	v_mfma_f32_16x16x32_bf16 v[16:19], v[170:173], v[202:205], v[16:19]
	v_mfma_f32_16x16x32_bf16 v[4:7], v[162:165], v[210:213], v[4:7]
	v_mfma_f32_16x16x32_bf16 v[0:3], v[170:173], v[210:213], v[0:3]
	s_barrier
	s_add_u32 s98, s48, 0x2b0000
	s_addc_u32 s99, s49, 0
	ds_read_b128 v[128:131], v177 offset:32768
	ds_read_b128 v[146:149], v177 offset:33792
	ds_read_b128 v[150:153], v177 offset:34816
	ds_read_b128 v[154:157], v177 offset:35840
	ds_read_b128 v[158:161], v178 offset:32768
	ds_read_b128 v[162:165], v178 offset:33792
	ds_read_b128 v[166:169], v178 offset:34816
	ds_read_b128 v[170:173], v178 offset:35840
	ds_read_b128 v[180:183], v179 offset:32768
	ds_read_b128 v[184:187], v179 offset:33792
	ds_read_b128 v[188:191], v179 offset:34816
	ds_read_b128 v[192:195], v179 offset:35840
	ds_read_b128 v[196:199], v179 offset:36864
	ds_read_b128 v[202:205], v179 offset:37888
	ds_read_b128 v[206:209], v179 offset:38912
	ds_read_b128 v[210:213], v179 offset:39936
	s_add_i32 m0, s50, 0x4000
	s_nop 0
	global_load_lds_dwordx4 v132, s[98:99]
	s_add_i32 m0, s50, 0x6000
	s_nop 0
	global_load_lds_dwordx4 v136, s[98:99]
	s_waitcnt vmcnt(8)
	s_waitcnt lgkmcnt(0)
	s_barrier
	v_mfma_f32_16x16x32_bf16 v[124:127], v[128:131], v[180:183], v[124:127]
	v_mfma_f32_16x16x32_bf16 v[120:123], v[150:153], v[180:183], v[120:123]
	v_mfma_f32_16x16x32_bf16 v[108:111], v[128:131], v[188:191], v[108:111]
	v_mfma_f32_16x16x32_bf16 v[104:107], v[150:153], v[188:191], v[104:107]
	v_mfma_f32_16x16x32_bf16 v[92:95], v[128:131], v[196:199], v[92:95]
	v_mfma_f32_16x16x32_bf16 v[88:91], v[150:153], v[196:199], v[88:91]
	v_mfma_f32_16x16x32_bf16 v[76:79], v[128:131], v[206:209], v[76:79]
	v_mfma_f32_16x16x32_bf16 v[72:75], v[150:153], v[206:209], v[72:75]
	v_mfma_f32_16x16x32_bf16 v[124:127], v[146:149], v[184:187], v[124:127]
	v_mfma_f32_16x16x32_bf16 v[120:123], v[154:157], v[184:187], v[120:123]
	v_mfma_f32_16x16x32_bf16 v[108:111], v[146:149], v[192:195], v[108:111]
	v_mfma_f32_16x16x32_bf16 v[104:107], v[154:157], v[192:195], v[104:107]
	v_mfma_f32_16x16x32_bf16 v[92:95], v[146:149], v[202:205], v[92:95]
	v_mfma_f32_16x16x32_bf16 v[88:91], v[154:157], v[202:205], v[88:91]
	v_mfma_f32_16x16x32_bf16 v[76:79], v[146:149], v[210:213], v[76:79]
	v_mfma_f32_16x16x32_bf16 v[72:75], v[154:157], v[210:213], v[72:75]
	v_mfma_f32_16x16x32_bf16 v[116:119], v[158:161], v[180:183], v[116:119]
	v_mfma_f32_16x16x32_bf16 v[112:115], v[166:169], v[180:183], v[112:115]
	v_mfma_f32_16x16x32_bf16 v[100:103], v[158:161], v[188:191], v[100:103]
	v_mfma_f32_16x16x32_bf16 v[96:99], v[166:169], v[188:191], v[96:99]
	v_mfma_f32_16x16x32_bf16 v[84:87], v[158:161], v[196:199], v[84:87]
	v_mfma_f32_16x16x32_bf16 v[80:83], v[166:169], v[196:199], v[80:83]
	v_mfma_f32_16x16x32_bf16 v[68:71], v[158:161], v[206:209], v[68:71]
	v_mfma_f32_16x16x32_bf16 v[64:67], v[166:169], v[206:209], v[64:67]
	v_mfma_f32_16x16x32_bf16 v[116:119], v[162:165], v[184:187], v[116:119]
	v_mfma_f32_16x16x32_bf16 v[112:115], v[170:173], v[184:187], v[112:115]
	v_mfma_f32_16x16x32_bf16 v[100:103], v[162:165], v[192:195], v[100:103]
	v_mfma_f32_16x16x32_bf16 v[96:99], v[170:173], v[192:195], v[96:99]
	v_mfma_f32_16x16x32_bf16 v[84:87], v[162:165], v[202:205], v[84:87]
	v_mfma_f32_16x16x32_bf16 v[80:83], v[170:173], v[202:205], v[80:83]
	v_mfma_f32_16x16x32_bf16 v[68:71], v[162:165], v[210:213], v[68:71]
	v_mfma_f32_16x16x32_bf16 v[64:67], v[170:173], v[210:213], v[64:67]
	s_barrier
	s_add_u32 s100, s46, 0x80
	s_addc_u32 s101, s47, 0
	s_add_u32 s42, s46, 0x2b0080
	s_addc_u32 s43, s47, 0
	s_add_u32 s98, s48, 0x80
	s_addc_u32 s99, s49, 0
	ds_read_b128 v[180:183], v179 offset:49152
	ds_read_b128 v[184:187], v179 offset:50176
	ds_read_b128 v[188:191], v179 offset:51200
	ds_read_b128 v[192:195], v179 offset:52224
	ds_read_b128 v[196:199], v179 offset:53248
	ds_read_b128 v[202:205], v179 offset:54272
	ds_read_b128 v[206:209], v179 offset:55296
	ds_read_b128 v[210:213], v179 offset:56320
	s_add_i32 m0, s50, 0x18000
	s_nop 0
	global_load_lds_dwordx4 v134, s[100:101]
	s_add_i32 m0, s50, 0x1a000
	s_nop 0
	global_load_lds_dwordx4 v138, s[100:101]
	s_add_i32 m0, s50, 0x1c000
	s_nop 0
	global_load_lds_dwordx4 v134, s[42:43]
	s_add_i32 m0, s50, 0x1e000
	s_nop 0
	global_load_lds_dwordx4 v138, s[42:43]
	s_add_i32 m0, s50, 0x8000
	s_nop 0
	global_load_lds_dwordx4 v132, s[98:99]
	s_add_i32 m0, s50, 0xa000
	s_nop 0
	global_load_lds_dwordx4 v136, s[98:99]
	s_waitcnt vmcnt(8)
	s_waitcnt lgkmcnt(0)
	s_barrier
	v_mfma_f32_16x16x32_bf16 v[60:63], v[128:131], v[180:183], v[60:63]
	v_mfma_f32_16x16x32_bf16 v[56:59], v[150:153], v[180:183], v[56:59]
	v_mfma_f32_16x16x32_bf16 v[44:47], v[128:131], v[188:191], v[44:47]
	v_mfma_f32_16x16x32_bf16 v[40:43], v[150:153], v[188:191], v[40:43]
	v_mfma_f32_16x16x32_bf16 v[28:31], v[128:131], v[196:199], v[28:31]
	v_mfma_f32_16x16x32_bf16 v[24:27], v[150:153], v[196:199], v[24:27]
	v_mfma_f32_16x16x32_bf16 v[12:15], v[128:131], v[206:209], v[12:15]
	v_mfma_f32_16x16x32_bf16 v[8:11], v[150:153], v[206:209], v[8:11]
	v_mfma_f32_16x16x32_bf16 v[60:63], v[146:149], v[184:187], v[60:63]
	v_mfma_f32_16x16x32_bf16 v[56:59], v[154:157], v[184:187], v[56:59]
	v_mfma_f32_16x16x32_bf16 v[44:47], v[146:149], v[192:195], v[44:47]
	v_mfma_f32_16x16x32_bf16 v[40:43], v[154:157], v[192:195], v[40:43]
	v_mfma_f32_16x16x32_bf16 v[28:31], v[146:149], v[202:205], v[28:31]
	v_mfma_f32_16x16x32_bf16 v[24:27], v[154:157], v[202:205], v[24:27]
	v_mfma_f32_16x16x32_bf16 v[12:15], v[146:149], v[210:213], v[12:15]
	v_mfma_f32_16x16x32_bf16 v[8:11], v[154:157], v[210:213], v[8:11]
	v_mfma_f32_16x16x32_bf16 v[52:55], v[158:161], v[180:183], v[52:55]
	v_mfma_f32_16x16x32_bf16 v[48:51], v[166:169], v[180:183], v[48:51]
	v_mfma_f32_16x16x32_bf16 v[36:39], v[158:161], v[188:191], v[36:39]
	v_mfma_f32_16x16x32_bf16 v[32:35], v[166:169], v[188:191], v[32:35]
	v_mfma_f32_16x16x32_bf16 v[20:23], v[158:161], v[196:199], v[20:23]
	v_mfma_f32_16x16x32_bf16 v[16:19], v[166:169], v[196:199], v[16:19]
	v_mfma_f32_16x16x32_bf16 v[4:7], v[158:161], v[206:209], v[4:7]
	v_mfma_f32_16x16x32_bf16 v[0:3], v[166:169], v[206:209], v[0:3]
	v_mfma_f32_16x16x32_bf16 v[52:55], v[162:165], v[184:187], v[52:55]
	v_mfma_f32_16x16x32_bf16 v[48:51], v[170:173], v[184:187], v[48:51]
	v_mfma_f32_16x16x32_bf16 v[36:39], v[162:165], v[192:195], v[36:39]
	v_mfma_f32_16x16x32_bf16 v[32:35], v[170:173], v[192:195], v[32:35]
	v_mfma_f32_16x16x32_bf16 v[20:23], v[162:165], v[202:205], v[20:23]
	v_mfma_f32_16x16x32_bf16 v[16:19], v[170:173], v[202:205], v[16:19]
	v_mfma_f32_16x16x32_bf16 v[4:7], v[162:165], v[210:213], v[4:7]
	v_mfma_f32_16x16x32_bf16 v[0:3], v[170:173], v[210:213], v[0:3]
	s_add_u32 s68, s68, 0x100
	s_addc_u32 s69, s69, 0
	s_cmp_ge_i32 s70, s67
	s_mov_b64 s[42:43], s[44:45]
	s_mov_b32 s46, s70
	s_cbranch_scc0 .Lrot_1409
	s_barrier
	s_and_b64 vcc, exec, s[14:15]
	s_cbranch_vccz .LBB0_1412
